# K-loops: lgkmcnt(0) wait placed before the pre-burst barrier (re-measure, candidate)
# baseline (speedup 1.0000x reference)
.LBB0_124:
	s_ashr_i32 s79, s78, 31
	s_lshl_b64 s[10:11], s[78:79], 19
	s_add_u32 s80, s54, s10
	v_cmp_lt_i64_e32 vcc, s[72:73], v[178:179]
	s_addc_u32 s81, s55, s11
	s_and_b64 s[10:11], vcc, exec
	s_cselect_b32 s1, s81, s87
	s_cselect_b32 s10, s80, s86
	s_ashr_i32 s77, s76, 31
	s_lshl_b64 s[36:37], s[76:77], 19
	s_add_u32 s72, s66, s36
	s_addc_u32 s73, s59, s37
	s_and_b64 s[36:37], vcc, exec
	s_cselect_b32 s11, s73, s83
	s_cselect_b32 s25, s72, s82
	s_add_u32 s86, s86, 0x40080
	s_addc_u32 s87, s87, 0
	s_add_u32 s33, s82, 0x100
	s_addc_u32 s36, s83, 0
	s_mov_b32 s37, -2
	s_add_u32 s27, s86, 0xfffc0080
	s_addc_u32 s56, s87, -1
	s_add_i32 s57, 0, 0x10000
	v_add_u32_e32 v76, s57, v217
	ds_read_b128 v[64:67], v76
	ds_read_b128 v[68:71], v76 offset:1024
	ds_read_b128 v[72:75], v76 offset:2048
	ds_read_b128 v[76:79], v76 offset:3072
	s_cmp_eq_u32 s37, 12
	s_cselect_b32 vcc_hi, s1, s56
	s_cselect_b32 vcc_lo, s10, s27
	s_cselect_b32 s83, s11, s36
	s_cselect_b32 s82, s25, s33
	v_lshl_add_u64 v[168:169], s[86:87], 0, v[164:165]
	s_add_i32 m0, s75, 0xc000
	ds_read_b128 v[80:83], v220
	ds_read_b128 v[84:87], v220 offset:1024
	ds_read_b128 v[88:91], v220 offset:2048
	ds_read_b128 v[92:95], v220 offset:3072
	ds_read_b128 v[188:191], v220 offset:4096
	ds_read_b128 v[192:195], v220 offset:5120
	ds_read_b128 v[196:199], v220 offset:6144
	ds_read_b128 v[200:203], v220 offset:7168
	global_load_lds_dwordx4 v[168:169], off
	v_lshl_add_u64 v[168:169], s[86:87], 0, v[166:167]
	s_add_i32 m0, s75, 0xe000
	s_nop 0
	global_load_lds_dwordx4 v[168:169], off
	s_waitcnt lgkmcnt(8)
	s_setprio 1
	s_waitcnt lgkmcnt(0)
	s_barrier
	v_mfma_f32_16x16x32_bf16 v[146:149], v[64:67], v[80:83], 0
	v_mfma_f32_16x16x32_bf16 v[116:119], v[72:75], v[80:83], 0
	v_mfma_f32_16x16x32_bf16 v[158:161], v[64:67], v[88:91], 0
	v_mfma_f32_16x16x32_bf16 v[124:127], v[72:75], v[88:91], 0
	v_mfma_f32_16x16x32_bf16 v[154:157], v[64:67], v[188:191], 0
	v_mfma_f32_16x16x32_bf16 v[112:115], v[72:75], v[188:191], 0
	v_mfma_f32_16x16x32_bf16 v[150:153], v[64:67], v[196:199], 0
	v_mfma_f32_16x16x32_bf16 v[120:123], v[72:75], v[196:199], 0
	v_mfma_f32_16x16x32_bf16 v[146:149], v[68:71], v[84:87], v[146:149]
	v_mfma_f32_16x16x32_bf16 v[116:119], v[76:79], v[84:87], v[116:119]
	v_mfma_f32_16x16x32_bf16 v[158:161], v[68:71], v[92:95], v[158:161]
	v_mfma_f32_16x16x32_bf16 v[124:127], v[76:79], v[92:95], v[124:127]
	v_mfma_f32_16x16x32_bf16 v[154:157], v[68:71], v[192:195], v[154:157]
	v_mfma_f32_16x16x32_bf16 v[112:115], v[76:79], v[192:195], v[112:115]
	v_mfma_f32_16x16x32_bf16 v[150:153], v[68:71], v[200:203], v[150:153]
	v_mfma_f32_16x16x32_bf16 v[120:123], v[76:79], v[200:203], v[120:123]
	s_barrier
	s_setprio 0
	s_add_i32 s27, 0, 0x14000
	v_add_u32_e32 v168, s27, v217
	s_add_i32 s56, s57, s74
	ds_read_b128 v[204:207], v168
	ds_read_b128 v[222:225], v168 offset:1024
	ds_read_b128 v[228:231], v168 offset:2048
	ds_read_b128 v[232:235], v168 offset:3072
	v_lshl_add_u64 v[168:169], s[82:83], 0, v[144:145]
	s_mov_b32 m0, s56
	v_lshl_add_u64 v[176:177], s[82:83], 0, v[162:163]
	global_load_lds_dwordx4 v[168:169], off
	s_add_i32 m0, s56, 0x2000
	s_nop 0
	global_load_lds_dwordx4 v[176:177], off
	s_setprio 1
	s_waitcnt lgkmcnt(0)
	s_barrier
	v_mfma_f32_16x16x32_bf16 v[140:143], v[204:207], v[80:83], 0
	v_mfma_f32_16x16x32_bf16 v[80:83], v[228:231], v[80:83], 0
	v_mfma_f32_16x16x32_bf16 v[140:143], v[222:225], v[84:87], v[140:143]
	v_mfma_f32_16x16x32_bf16 v[80:83], v[232:235], v[84:87], v[80:83]
	v_mfma_f32_16x16x32_bf16 v[84:87], v[204:207], v[88:91], 0
	v_mfma_f32_16x16x32_bf16 v[88:91], v[228:231], v[88:91], 0
	v_mfma_f32_16x16x32_bf16 v[100:103], v[228:231], v[188:191], 0
	v_mfma_f32_16x16x32_bf16 v[104:107], v[204:207], v[196:199], 0
	v_mfma_f32_16x16x32_bf16 v[96:99], v[228:231], v[196:199], 0
	v_mfma_f32_16x16x32_bf16 v[84:87], v[222:225], v[92:95], v[84:87]
	v_mfma_f32_16x16x32_bf16 v[88:91], v[232:235], v[92:95], v[88:91]
	v_mfma_f32_16x16x32_bf16 v[92:95], v[204:207], v[188:191], 0
	v_mfma_f32_16x16x32_bf16 v[100:103], v[232:235], v[192:195], v[100:103]
	v_mfma_f32_16x16x32_bf16 v[128:131], v[222:225], v[200:203], v[104:107]
	v_mfma_f32_16x16x32_bf16 v[96:99], v[232:235], v[200:203], v[96:99]
	v_mfma_f32_16x16x32_bf16 v[92:95], v[222:225], v[192:195], v[92:95]
	s_barrier
	s_setprio 0
	s_mov_b32 m0, s75
	v_lshl_add_u64 v[240:241], vcc, 0, v[144:145]
	ds_read_b128 v[104:107], v220 offset:16384
	ds_read_b128 v[108:111], v220 offset:17408
	ds_read_b128 v[132:135], v220 offset:18432
	ds_read_b128 v[136:139], v220 offset:19456
	ds_read_b128 v[188:191], v220 offset:20480
	ds_read_b128 v[192:195], v220 offset:21504
	ds_read_b128 v[196:199], v220 offset:22528
	ds_read_b128 v[200:203], v220 offset:23552
	global_load_lds_dwordx4 v[240:241], off
	v_lshl_add_u64 v[242:243], vcc, 0, v[162:163]
	s_mov_b32 m0, s85
	s_nop 0
	global_load_lds_dwordx4 v[242:243], off
	s_setprio 1
	s_waitcnt lgkmcnt(0)
	s_barrier
	v_mfma_f32_16x16x32_bf16 v[48:51], v[64:67], v[104:107], 0
	v_mfma_f32_16x16x32_bf16 v[20:23], v[72:75], v[104:107], 0
	v_mfma_f32_16x16x32_bf16 v[60:63], v[64:67], v[132:135], 0
	v_mfma_f32_16x16x32_bf16 v[28:31], v[72:75], v[132:135], 0
	v_mfma_f32_16x16x32_bf16 v[56:59], v[64:67], v[188:191], 0
	v_mfma_f32_16x16x32_bf16 v[16:19], v[72:75], v[188:191], 0
	v_mfma_f32_16x16x32_bf16 v[52:55], v[64:67], v[196:199], 0
	v_mfma_f32_16x16x32_bf16 v[24:27], v[72:75], v[196:199], 0
	v_mfma_f32_16x16x32_bf16 v[48:51], v[68:71], v[108:111], v[48:51]
	v_mfma_f32_16x16x32_bf16 v[20:23], v[76:79], v[108:111], v[20:23]
	v_mfma_f32_16x16x32_bf16 v[60:63], v[68:71], v[136:139], v[60:63]
	v_mfma_f32_16x16x32_bf16 v[28:31], v[76:79], v[136:139], v[28:31]
	v_mfma_f32_16x16x32_bf16 v[56:59], v[68:71], v[192:195], v[56:59]
	v_mfma_f32_16x16x32_bf16 v[16:19], v[76:79], v[192:195], v[16:19]
	v_mfma_f32_16x16x32_bf16 v[52:55], v[68:71], v[200:203], v[52:55]
	v_mfma_f32_16x16x32_bf16 v[24:27], v[76:79], v[200:203], v[24:27]
	s_barrier
	s_setprio 0
	s_add_u32 s56, s82, 0x40000
	s_addc_u32 s57, s83, 0
	s_add_i32 s27, s27, s74
	v_lshl_add_u64 v[64:65], s[56:57], 0, v[144:145]
	s_mov_b32 m0, s27
	s_nop 0
	global_load_lds_dwordx4 v[64:65], off
	v_lshl_add_u64 v[64:65], s[56:57], 0, v[162:163]
	s_add_i32 m0, s27, 0x2000
	s_nop 0
	global_load_lds_dwordx4 v[64:65], off
	s_waitcnt vmcnt(6)
	s_setprio 1
	s_barrier
	v_mfma_f32_16x16x32_bf16 v[44:47], v[204:207], v[104:107], 0
	v_mfma_f32_16x16x32_bf16 v[12:15], v[228:231], v[104:107], 0
	v_mfma_f32_16x16x32_bf16 v[40:43], v[204:207], v[132:135], 0
	v_mfma_f32_16x16x32_bf16 v[8:11], v[228:231], v[132:135], 0
	v_mfma_f32_16x16x32_bf16 v[36:39], v[204:207], v[188:191], 0
	v_mfma_f32_16x16x32_bf16 v[4:7], v[228:231], v[188:191], 0
	v_mfma_f32_16x16x32_bf16 v[32:35], v[204:207], v[196:199], 0
	v_mfma_f32_16x16x32_bf16 v[0:3], v[228:231], v[196:199], 0
	v_mfma_f32_16x16x32_bf16 v[44:47], v[222:225], v[108:111], v[44:47]
	v_mfma_f32_16x16x32_bf16 v[12:15], v[232:235], v[108:111], v[12:15]
	v_mfma_f32_16x16x32_bf16 v[40:43], v[222:225], v[136:139], v[40:43]
	v_mfma_f32_16x16x32_bf16 v[8:11], v[232:235], v[136:139], v[8:11]
	v_mfma_f32_16x16x32_bf16 v[36:39], v[222:225], v[192:195], v[36:39]
	v_mfma_f32_16x16x32_bf16 v[4:7], v[232:235], v[192:195], v[4:7]
	v_mfma_f32_16x16x32_bf16 v[32:35], v[222:225], v[200:203], v[32:35]
	v_mfma_f32_16x16x32_bf16 v[0:3], v[232:235], v[200:203], v[0:3]
	s_barrier
	s_setprio 0
	s_add_i32 s27, 0, 0x18000
	v_add_u32_e32 v76, s27, v217
	ds_read_b128 v[64:67], v76
	ds_read_b128 v[68:71], v76 offset:1024
	ds_read_b128 v[72:75], v76 offset:2048
	ds_read_b128 v[76:79], v76 offset:3072
	s_add_u32 s56, vcc_lo, 0x40000
	s_addc_u32 s57, vcc_hi, 0
	s_mov_b32 m0, s98
	v_lshl_add_u64 v[136:137], s[56:57], 0, v[144:145]
	ds_read_b128 v[104:107], v220 offset:32768
	ds_read_b128 v[108:111], v220 offset:33792
	ds_read_b128 v[132:135], v220 offset:34816
	ds_read_b128 v[188:191], v220 offset:35840
	ds_read_b128 v[192:195], v220 offset:36864
	ds_read_b128 v[196:199], v220 offset:37888
	ds_read_b128 v[200:203], v220 offset:38912
	ds_read_b128 v[204:207], v220 offset:39936
	global_load_lds_dwordx4 v[136:137], off
	v_lshl_add_u64 v[136:137], s[56:57], 0, v[162:163]
	s_mov_b32 m0, s29
	s_nop 0
	global_load_lds_dwordx4 v[136:137], off
	s_waitcnt lgkmcnt(8)
	s_setprio 1
	s_waitcnt lgkmcnt(0)
	s_barrier
	v_mfma_f32_16x16x32_bf16 v[136:139], v[64:67], v[104:107], v[146:149]
	v_mfma_f32_16x16x32_bf16 v[146:149], v[68:71], v[108:111], v[136:139]
	v_mfma_f32_16x16x32_bf16 v[136:139], v[64:67], v[132:135], v[158:161]
	v_mfma_f32_16x16x32_bf16 v[158:161], v[68:71], v[188:191], v[136:139]
	v_mfma_f32_16x16x32_bf16 v[136:139], v[64:67], v[192:195], v[154:157]
	v_mfma_f32_16x16x32_bf16 v[116:119], v[72:75], v[104:107], v[116:119]
	v_mfma_f32_16x16x32_bf16 v[124:127], v[72:75], v[132:135], v[124:127]
	v_mfma_f32_16x16x32_bf16 v[154:157], v[68:71], v[196:199], v[136:139]
	v_mfma_f32_16x16x32_bf16 v[112:115], v[72:75], v[192:195], v[112:115]
	v_mfma_f32_16x16x32_bf16 v[136:139], v[64:67], v[200:203], v[150:153]
	v_mfma_f32_16x16x32_bf16 v[120:123], v[72:75], v[200:203], v[120:123]
	v_mfma_f32_16x16x32_bf16 v[116:119], v[76:79], v[108:111], v[116:119]
	v_mfma_f32_16x16x32_bf16 v[124:127], v[76:79], v[188:191], v[124:127]
	v_mfma_f32_16x16x32_bf16 v[112:115], v[76:79], v[196:199], v[112:115]
	v_mfma_f32_16x16x32_bf16 v[150:153], v[68:71], v[204:207], v[136:139]
	v_mfma_f32_16x16x32_bf16 v[120:123], v[76:79], v[204:207], v[120:123]
	s_barrier
	s_setprio 0
	s_add_i32 s58, 0, 0x1c000
	v_add_u32_e32 v136, s58, v217
	s_add_i32 s27, s27, s74
	ds_read_b128 v[222:225], v136
	ds_read_b128 v[228:231], v136 offset:1024
	ds_read_b128 v[232:235], v136 offset:2048
	ds_read_b128 v[236:239], v136 offset:3072
	v_lshl_add_u64 v[136:137], v[168:169], 0, s[18:19]
	s_mov_b32 m0, s27
	s_nop 0
	global_load_lds_dwordx4 v[136:137], off
	v_lshl_add_u64 v[136:137], v[176:177], 0, s[18:19]
	s_add_i32 m0, s27, 0x2000
	s_nop 0
	global_load_lds_dwordx4 v[136:137], off
	s_setprio 1
	s_waitcnt lgkmcnt(0)
	s_barrier
	v_mfma_f32_16x16x32_bf16 v[136:139], v[222:225], v[104:107], v[140:143]
	v_mfma_f32_16x16x32_bf16 v[80:83], v[232:235], v[104:107], v[80:83]
	v_mfma_f32_16x16x32_bf16 v[140:143], v[228:231], v[108:111], v[136:139]
	v_mfma_f32_16x16x32_bf16 v[108:111], v[236:239], v[108:111], v[80:83]
	v_mfma_f32_16x16x32_bf16 v[80:83], v[222:225], v[132:135], v[84:87]
	v_mfma_f32_16x16x32_bf16 v[136:139], v[228:231], v[188:191], v[80:83]
	v_mfma_f32_16x16x32_bf16 v[80:83], v[232:235], v[132:135], v[88:91]
	v_mfma_f32_16x16x32_bf16 v[104:107], v[236:239], v[188:191], v[80:83]
	v_mfma_f32_16x16x32_bf16 v[80:83], v[222:225], v[192:195], v[92:95]
	v_mfma_f32_16x16x32_bf16 v[132:135], v[228:231], v[196:199], v[80:83]
	v_mfma_f32_16x16x32_bf16 v[80:83], v[232:235], v[192:195], v[100:103]
	v_mfma_f32_16x16x32_bf16 v[100:103], v[236:239], v[196:199], v[80:83]
	v_mfma_f32_16x16x32_bf16 v[80:83], v[222:225], v[200:203], v[128:131]
	v_mfma_f32_16x16x32_bf16 v[128:131], v[228:231], v[204:207], v[80:83]
	v_mfma_f32_16x16x32_bf16 v[80:83], v[232:235], v[200:203], v[96:99]
	v_mfma_f32_16x16x32_bf16 v[96:99], v[236:239], v[204:207], v[80:83]
	s_barrier
	s_setprio 0
	s_mov_b32 m0, s31
	v_lshl_add_u64 v[168:169], v[240:241], 0, s[18:19]
	s_nop 2
	ds_read_b128 v[80:83], v220 offset:49152
	ds_read_b128 v[84:87], v220 offset:50176
	ds_read_b128 v[88:91], v220 offset:51200
	ds_read_b128 v[92:95], v220 offset:52224
	ds_read_b128 v[188:191], v220 offset:53248
	ds_read_b128 v[192:195], v220 offset:54272
	ds_read_b128 v[196:199], v220 offset:55296
	ds_read_b128 v[200:203], v220 offset:56320
	global_load_lds_dwordx4 v[168:169], off
	v_lshl_add_u64 v[168:169], v[242:243], 0, s[18:19]
	s_mov_b32 m0, s34
	s_nop 0
	global_load_lds_dwordx4 v[168:169], off
	s_setprio 1
	s_waitcnt lgkmcnt(0)
	s_barrier
	v_mfma_f32_16x16x32_bf16 v[48:51], v[64:67], v[80:83], v[48:51]
	v_mfma_f32_16x16x32_bf16 v[20:23], v[72:75], v[80:83], v[20:23]
	v_mfma_f32_16x16x32_bf16 v[60:63], v[64:67], v[88:91], v[60:63]
	v_mfma_f32_16x16x32_bf16 v[28:31], v[72:75], v[88:91], v[28:31]
	v_mfma_f32_16x16x32_bf16 v[56:59], v[64:67], v[188:191], v[56:59]
	v_mfma_f32_16x16x32_bf16 v[16:19], v[72:75], v[188:191], v[16:19]
	v_mfma_f32_16x16x32_bf16 v[52:55], v[64:67], v[196:199], v[52:55]
	v_mfma_f32_16x16x32_bf16 v[24:27], v[72:75], v[196:199], v[24:27]
	v_mfma_f32_16x16x32_bf16 v[48:51], v[68:71], v[84:87], v[48:51]
	v_mfma_f32_16x16x32_bf16 v[20:23], v[76:79], v[84:87], v[20:23]
	v_mfma_f32_16x16x32_bf16 v[60:63], v[68:71], v[92:95], v[60:63]
	v_mfma_f32_16x16x32_bf16 v[28:31], v[76:79], v[92:95], v[28:31]
	v_mfma_f32_16x16x32_bf16 v[56:59], v[68:71], v[192:195], v[56:59]
	v_mfma_f32_16x16x32_bf16 v[16:19], v[76:79], v[192:195], v[16:19]
	v_mfma_f32_16x16x32_bf16 v[52:55], v[68:71], v[200:203], v[52:55]
	v_mfma_f32_16x16x32_bf16 v[24:27], v[76:79], v[200:203], v[24:27]
	s_barrier
	s_setprio 0
	s_add_u32 s56, s82, 0x40080
	s_addc_u32 s57, s83, 0
	s_add_i32 s27, s58, s74
	v_lshl_add_u64 v[64:65], s[56:57], 0, v[144:145]
	s_mov_b32 m0, s27
	s_nop 0
	global_load_lds_dwordx4 v[64:65], off
	v_lshl_add_u64 v[64:65], s[56:57], 0, v[162:163]
	s_add_i32 m0, s27, 0x2000
	s_nop 0
	global_load_lds_dwordx4 v[64:65], off
	s_waitcnt vmcnt(6)
	s_setprio 1
	s_barrier
	v_mfma_f32_16x16x32_bf16 v[44:47], v[222:225], v[80:83], v[44:47]
	v_mfma_f32_16x16x32_bf16 v[12:15], v[232:235], v[80:83], v[12:15]
	v_mfma_f32_16x16x32_bf16 v[40:43], v[222:225], v[88:91], v[40:43]
	v_mfma_f32_16x16x32_bf16 v[8:11], v[232:235], v[88:91], v[8:11]
	v_mfma_f32_16x16x32_bf16 v[36:39], v[222:225], v[188:191], v[36:39]
	v_mfma_f32_16x16x32_bf16 v[4:7], v[232:235], v[188:191], v[4:7]
	v_mfma_f32_16x16x32_bf16 v[32:35], v[222:225], v[196:199], v[32:35]
	v_mfma_f32_16x16x32_bf16 v[0:3], v[232:235], v[196:199], v[0:3]
	v_mfma_f32_16x16x32_bf16 v[44:47], v[228:231], v[84:87], v[44:47]
	v_mfma_f32_16x16x32_bf16 v[12:15], v[236:239], v[84:87], v[12:15]
	v_mfma_f32_16x16x32_bf16 v[40:43], v[228:231], v[92:95], v[40:43]
	v_mfma_f32_16x16x32_bf16 v[8:11], v[236:239], v[92:95], v[8:11]
	v_mfma_f32_16x16x32_bf16 v[36:39], v[228:231], v[192:195], v[36:39]
	v_mfma_f32_16x16x32_bf16 v[4:7], v[236:239], v[192:195], v[4:7]
	v_mfma_f32_16x16x32_bf16 v[32:35], v[228:231], v[200:203], v[32:35]
	v_mfma_f32_16x16x32_bf16 v[0:3], v[236:239], v[200:203], v[0:3]
	s_barrier
	s_setprio 0
	s_add_i32 s37, s37, 2
	s_add_u32 s86, s86, 0x100
	s_addc_u32 s87, s87, 0
	s_add_u32 s33, s33, 0x100
	s_addc_u32 s36, s36, 0
	s_cmp_gt_u32 s37, 13
.LBB0_125:
	s_add_u32 s27, s86, 0xfffc0080
	s_addc_u32 s56, s87, -1
	s_add_i32 s57, 0, 0x10000
	v_add_u32_e32 v76, s57, v217
	ds_read_b128 v[64:67], v76
	ds_read_b128 v[68:71], v76 offset:1024
	ds_read_b128 v[72:75], v76 offset:2048
	ds_read_b128 v[76:79], v76 offset:3072
	s_cmp_eq_u32 s37, 12
	s_cselect_b32 vcc_hi, s1, s56
	s_cselect_b32 vcc_lo, s10, s27
	s_cselect_b32 s83, s11, s36
	s_cselect_b32 s82, s25, s33
	v_lshl_add_u64 v[168:169], s[86:87], 0, v[164:165]
	s_add_i32 m0, s75, 0xc000
	ds_read_b128 v[80:83], v220
	ds_read_b128 v[84:87], v220 offset:1024
	ds_read_b128 v[88:91], v220 offset:2048
	ds_read_b128 v[92:95], v220 offset:3072
	ds_read_b128 v[188:191], v220 offset:4096
	ds_read_b128 v[192:195], v220 offset:5120
	ds_read_b128 v[196:199], v220 offset:6144
	ds_read_b128 v[200:203], v220 offset:7168
	global_load_lds_dwordx4 v[168:169], off
	v_lshl_add_u64 v[168:169], s[86:87], 0, v[166:167]
	s_add_i32 m0, s75, 0xe000
	s_nop 0
	global_load_lds_dwordx4 v[168:169], off
	s_waitcnt lgkmcnt(8)
	s_setprio 1
	s_waitcnt lgkmcnt(0)
	s_barrier
	v_mfma_f32_16x16x32_bf16 v[146:149], v[64:67], v[80:83], v[146:149]
	v_mfma_f32_16x16x32_bf16 v[116:119], v[72:75], v[80:83], v[116:119]
	v_mfma_f32_16x16x32_bf16 v[158:161], v[64:67], v[88:91], v[158:161]
	v_mfma_f32_16x16x32_bf16 v[124:127], v[72:75], v[88:91], v[124:127]
	v_mfma_f32_16x16x32_bf16 v[154:157], v[64:67], v[188:191], v[154:157]
	v_mfma_f32_16x16x32_bf16 v[112:115], v[72:75], v[188:191], v[112:115]
	v_mfma_f32_16x16x32_bf16 v[150:153], v[64:67], v[196:199], v[150:153]
	v_mfma_f32_16x16x32_bf16 v[120:123], v[72:75], v[196:199], v[120:123]
	v_mfma_f32_16x16x32_bf16 v[146:149], v[68:71], v[84:87], v[146:149]
	v_mfma_f32_16x16x32_bf16 v[116:119], v[76:79], v[84:87], v[116:119]
	v_mfma_f32_16x16x32_bf16 v[158:161], v[68:71], v[92:95], v[158:161]
	v_mfma_f32_16x16x32_bf16 v[124:127], v[76:79], v[92:95], v[124:127]
	v_mfma_f32_16x16x32_bf16 v[154:157], v[68:71], v[192:195], v[154:157]
	v_mfma_f32_16x16x32_bf16 v[112:115], v[76:79], v[192:195], v[112:115]
	v_mfma_f32_16x16x32_bf16 v[150:153], v[68:71], v[200:203], v[150:153]
	v_mfma_f32_16x16x32_bf16 v[120:123], v[76:79], v[200:203], v[120:123]
	s_barrier
	s_setprio 0
	s_add_i32 s27, 0, 0x14000
	v_add_u32_e32 v168, s27, v217
	s_add_i32 s56, s57, s74
	ds_read_b128 v[204:207], v168
	ds_read_b128 v[222:225], v168 offset:1024
	ds_read_b128 v[228:231], v168 offset:2048
	ds_read_b128 v[232:235], v168 offset:3072
	v_lshl_add_u64 v[168:169], s[82:83], 0, v[144:145]
	s_mov_b32 m0, s56
	v_lshl_add_u64 v[176:177], s[82:83], 0, v[162:163]
	global_load_lds_dwordx4 v[168:169], off
	s_add_i32 m0, s56, 0x2000
	s_nop 0
	global_load_lds_dwordx4 v[176:177], off
	s_setprio 1
	s_waitcnt lgkmcnt(0)
	s_barrier
	v_mfma_f32_16x16x32_bf16 v[140:143], v[204:207], v[80:83], v[140:143]
	v_mfma_f32_16x16x32_bf16 v[80:83], v[228:231], v[80:83], v[108:111]
	v_mfma_f32_16x16x32_bf16 v[140:143], v[222:225], v[84:87], v[140:143]
	v_mfma_f32_16x16x32_bf16 v[80:83], v[232:235], v[84:87], v[80:83]
	v_mfma_f32_16x16x32_bf16 v[84:87], v[204:207], v[88:91], v[136:139]
	v_mfma_f32_16x16x32_bf16 v[88:91], v[228:231], v[88:91], v[104:107]
	v_mfma_f32_16x16x32_bf16 v[100:103], v[228:231], v[188:191], v[100:103]
	v_mfma_f32_16x16x32_bf16 v[104:107], v[204:207], v[196:199], v[128:131]
	v_mfma_f32_16x16x32_bf16 v[96:99], v[228:231], v[196:199], v[96:99]
	v_mfma_f32_16x16x32_bf16 v[84:87], v[222:225], v[92:95], v[84:87]
	v_mfma_f32_16x16x32_bf16 v[88:91], v[232:235], v[92:95], v[88:91]
	v_mfma_f32_16x16x32_bf16 v[92:95], v[204:207], v[188:191], v[132:135]
	v_mfma_f32_16x16x32_bf16 v[100:103], v[232:235], v[192:195], v[100:103]
	v_mfma_f32_16x16x32_bf16 v[128:131], v[222:225], v[200:203], v[104:107]
	v_mfma_f32_16x16x32_bf16 v[96:99], v[232:235], v[200:203], v[96:99]
	v_mfma_f32_16x16x32_bf16 v[92:95], v[222:225], v[192:195], v[92:95]
	s_barrier
	s_setprio 0
	s_mov_b32 m0, s75
	v_lshl_add_u64 v[240:241], vcc, 0, v[144:145]
	ds_read_b128 v[104:107], v220 offset:16384
	ds_read_b128 v[108:111], v220 offset:17408
	ds_read_b128 v[132:135], v220 offset:18432
	ds_read_b128 v[136:139], v220 offset:19456
	ds_read_b128 v[188:191], v220 offset:20480
	ds_read_b128 v[192:195], v220 offset:21504
	ds_read_b128 v[196:199], v220 offset:22528
	ds_read_b128 v[200:203], v220 offset:23552
	global_load_lds_dwordx4 v[240:241], off
	v_lshl_add_u64 v[242:243], vcc, 0, v[162:163]
	s_mov_b32 m0, s85
	s_nop 0
	global_load_lds_dwordx4 v[242:243], off
	s_setprio 1
	s_waitcnt lgkmcnt(0)
	s_barrier
	v_mfma_f32_16x16x32_bf16 v[48:51], v[64:67], v[104:107], v[48:51]
	v_mfma_f32_16x16x32_bf16 v[20:23], v[72:75], v[104:107], v[20:23]
	v_mfma_f32_16x16x32_bf16 v[60:63], v[64:67], v[132:135], v[60:63]
	v_mfma_f32_16x16x32_bf16 v[28:31], v[72:75], v[132:135], v[28:31]
	v_mfma_f32_16x16x32_bf16 v[56:59], v[64:67], v[188:191], v[56:59]
	v_mfma_f32_16x16x32_bf16 v[16:19], v[72:75], v[188:191], v[16:19]
	v_mfma_f32_16x16x32_bf16 v[52:55], v[64:67], v[196:199], v[52:55]
	v_mfma_f32_16x16x32_bf16 v[24:27], v[72:75], v[196:199], v[24:27]
	v_mfma_f32_16x16x32_bf16 v[48:51], v[68:71], v[108:111], v[48:51]
	v_mfma_f32_16x16x32_bf16 v[20:23], v[76:79], v[108:111], v[20:23]
	v_mfma_f32_16x16x32_bf16 v[60:63], v[68:71], v[136:139], v[60:63]
	v_mfma_f32_16x16x32_bf16 v[28:31], v[76:79], v[136:139], v[28:31]
	v_mfma_f32_16x16x32_bf16 v[56:59], v[68:71], v[192:195], v[56:59]
	v_mfma_f32_16x16x32_bf16 v[16:19], v[76:79], v[192:195], v[16:19]
	v_mfma_f32_16x16x32_bf16 v[52:55], v[68:71], v[200:203], v[52:55]
	v_mfma_f32_16x16x32_bf16 v[24:27], v[76:79], v[200:203], v[24:27]
	s_barrier
	s_setprio 0
	s_add_u32 s56, s82, 0x40000
	s_addc_u32 s57, s83, 0
	s_add_i32 s27, s27, s74
	v_lshl_add_u64 v[64:65], s[56:57], 0, v[144:145]
	s_mov_b32 m0, s27
	s_nop 0
	global_load_lds_dwordx4 v[64:65], off
	v_lshl_add_u64 v[64:65], s[56:57], 0, v[162:163]
	s_add_i32 m0, s27, 0x2000
	s_nop 0
	global_load_lds_dwordx4 v[64:65], off
	s_waitcnt vmcnt(6)
	s_setprio 1
	s_barrier
	v_mfma_f32_16x16x32_bf16 v[44:47], v[204:207], v[104:107], v[44:47]
	v_mfma_f32_16x16x32_bf16 v[12:15], v[228:231], v[104:107], v[12:15]
	v_mfma_f32_16x16x32_bf16 v[40:43], v[204:207], v[132:135], v[40:43]
	v_mfma_f32_16x16x32_bf16 v[8:11], v[228:231], v[132:135], v[8:11]
	v_mfma_f32_16x16x32_bf16 v[36:39], v[204:207], v[188:191], v[36:39]
	v_mfma_f32_16x16x32_bf16 v[4:7], v[228:231], v[188:191], v[4:7]
	v_mfma_f32_16x16x32_bf16 v[32:35], v[204:207], v[196:199], v[32:35]
	v_mfma_f32_16x16x32_bf16 v[0:3], v[228:231], v[196:199], v[0:3]
	v_mfma_f32_16x16x32_bf16 v[44:47], v[222:225], v[108:111], v[44:47]
	v_mfma_f32_16x16x32_bf16 v[12:15], v[232:235], v[108:111], v[12:15]
	v_mfma_f32_16x16x32_bf16 v[40:43], v[222:225], v[136:139], v[40:43]
	v_mfma_f32_16x16x32_bf16 v[8:11], v[232:235], v[136:139], v[8:11]
	v_mfma_f32_16x16x32_bf16 v[36:39], v[222:225], v[192:195], v[36:39]
	v_mfma_f32_16x16x32_bf16 v[4:7], v[232:235], v[192:195], v[4:7]
	v_mfma_f32_16x16x32_bf16 v[32:35], v[222:225], v[200:203], v[32:35]
	v_mfma_f32_16x16x32_bf16 v[0:3], v[232:235], v[200:203], v[0:3]
	s_barrier
	s_setprio 0
	s_add_i32 s27, 0, 0x18000
	v_add_u32_e32 v76, s27, v217
	ds_read_b128 v[64:67], v76
	ds_read_b128 v[68:71], v76 offset:1024
	ds_read_b128 v[72:75], v76 offset:2048
	ds_read_b128 v[76:79], v76 offset:3072
	s_add_u32 s56, vcc_lo, 0x40000
	s_addc_u32 s57, vcc_hi, 0
	s_mov_b32 m0, s98
	v_lshl_add_u64 v[136:137], s[56:57], 0, v[144:145]
	ds_read_b128 v[104:107], v220 offset:32768
	ds_read_b128 v[108:111], v220 offset:33792
	ds_read_b128 v[132:135], v220 offset:34816
	ds_read_b128 v[188:191], v220 offset:35840
	ds_read_b128 v[192:195], v220 offset:36864
	ds_read_b128 v[196:199], v220 offset:37888
	ds_read_b128 v[200:203], v220 offset:38912
	ds_read_b128 v[204:207], v220 offset:39936
	global_load_lds_dwordx4 v[136:137], off
	v_lshl_add_u64 v[136:137], s[56:57], 0, v[162:163]
	s_mov_b32 m0, s29
	s_nop 0
	global_load_lds_dwordx4 v[136:137], off
	s_waitcnt lgkmcnt(8)
	s_setprio 1
	s_waitcnt lgkmcnt(0)
	s_barrier
	v_mfma_f32_16x16x32_bf16 v[136:139], v[64:67], v[104:107], v[146:149]
	v_mfma_f32_16x16x32_bf16 v[146:149], v[68:71], v[108:111], v[136:139]
	v_mfma_f32_16x16x32_bf16 v[136:139], v[64:67], v[132:135], v[158:161]
	v_mfma_f32_16x16x32_bf16 v[158:161], v[68:71], v[188:191], v[136:139]
	v_mfma_f32_16x16x32_bf16 v[136:139], v[64:67], v[192:195], v[154:157]
	v_mfma_f32_16x16x32_bf16 v[116:119], v[72:75], v[104:107], v[116:119]
	v_mfma_f32_16x16x32_bf16 v[124:127], v[72:75], v[132:135], v[124:127]
	v_mfma_f32_16x16x32_bf16 v[154:157], v[68:71], v[196:199], v[136:139]
	v_mfma_f32_16x16x32_bf16 v[112:115], v[72:75], v[192:195], v[112:115]
	v_mfma_f32_16x16x32_bf16 v[136:139], v[64:67], v[200:203], v[150:153]
	v_mfma_f32_16x16x32_bf16 v[120:123], v[72:75], v[200:203], v[120:123]
	v_mfma_f32_16x16x32_bf16 v[116:119], v[76:79], v[108:111], v[116:119]
	v_mfma_f32_16x16x32_bf16 v[124:127], v[76:79], v[188:191], v[124:127]
	v_mfma_f32_16x16x32_bf16 v[112:115], v[76:79], v[196:199], v[112:115]
	v_mfma_f32_16x16x32_bf16 v[150:153], v[68:71], v[204:207], v[136:139]
	v_mfma_f32_16x16x32_bf16 v[120:123], v[76:79], v[204:207], v[120:123]
	s_barrier
	s_setprio 0
	s_add_i32 s58, 0, 0x1c000
	v_add_u32_e32 v136, s58, v217
	s_add_i32 s27, s27, s74
	ds_read_b128 v[222:225], v136
	ds_read_b128 v[228:231], v136 offset:1024
	ds_read_b128 v[232:235], v136 offset:2048
	ds_read_b128 v[236:239], v136 offset:3072
	v_lshl_add_u64 v[136:137], v[168:169], 0, s[18:19]
	s_mov_b32 m0, s27
	s_nop 0
	global_load_lds_dwordx4 v[136:137], off
	v_lshl_add_u64 v[136:137], v[176:177], 0, s[18:19]
	s_add_i32 m0, s27, 0x2000
	s_nop 0
	global_load_lds_dwordx4 v[136:137], off
	s_setprio 1
	s_waitcnt lgkmcnt(0)
	s_barrier
	v_mfma_f32_16x16x32_bf16 v[136:139], v[222:225], v[104:107], v[140:143]
	v_mfma_f32_16x16x32_bf16 v[80:83], v[232:235], v[104:107], v[80:83]
	v_mfma_f32_16x16x32_bf16 v[140:143], v[228:231], v[108:111], v[136:139]
	v_mfma_f32_16x16x32_bf16 v[108:111], v[236:239], v[108:111], v[80:83]
	v_mfma_f32_16x16x32_bf16 v[80:83], v[222:225], v[132:135], v[84:87]
	v_mfma_f32_16x16x32_bf16 v[136:139], v[228:231], v[188:191], v[80:83]
	v_mfma_f32_16x16x32_bf16 v[80:83], v[232:235], v[132:135], v[88:91]
	v_mfma_f32_16x16x32_bf16 v[104:107], v[236:239], v[188:191], v[80:83]
	v_mfma_f32_16x16x32_bf16 v[80:83], v[222:225], v[192:195], v[92:95]
	v_mfma_f32_16x16x32_bf16 v[132:135], v[228:231], v[196:199], v[80:83]
	v_mfma_f32_16x16x32_bf16 v[80:83], v[232:235], v[192:195], v[100:103]
	v_mfma_f32_16x16x32_bf16 v[100:103], v[236:239], v[196:199], v[80:83]
	v_mfma_f32_16x16x32_bf16 v[80:83], v[222:225], v[200:203], v[128:131]
	v_mfma_f32_16x16x32_bf16 v[128:131], v[228:231], v[204:207], v[80:83]
	v_mfma_f32_16x16x32_bf16 v[80:83], v[232:235], v[200:203], v[96:99]
	v_mfma_f32_16x16x32_bf16 v[96:99], v[236:239], v[204:207], v[80:83]
	s_barrier
	s_setprio 0
	s_mov_b32 m0, s31
	v_lshl_add_u64 v[168:169], v[240:241], 0, s[18:19]
	s_nop 2
	ds_read_b128 v[80:83], v220 offset:49152
	ds_read_b128 v[84:87], v220 offset:50176
	ds_read_b128 v[88:91], v220 offset:51200
	ds_read_b128 v[92:95], v220 offset:52224
	ds_read_b128 v[188:191], v220 offset:53248
	ds_read_b128 v[192:195], v220 offset:54272
	ds_read_b128 v[196:199], v220 offset:55296
	ds_read_b128 v[200:203], v220 offset:56320
	global_load_lds_dwordx4 v[168:169], off
	v_lshl_add_u64 v[168:169], v[242:243], 0, s[18:19]
	s_mov_b32 m0, s34
	s_nop 0
	global_load_lds_dwordx4 v[168:169], off
	s_setprio 1
	s_waitcnt lgkmcnt(0)
	s_barrier
	v_mfma_f32_16x16x32_bf16 v[48:51], v[64:67], v[80:83], v[48:51]
	v_mfma_f32_16x16x32_bf16 v[20:23], v[72:75], v[80:83], v[20:23]
	v_mfma_f32_16x16x32_bf16 v[60:63], v[64:67], v[88:91], v[60:63]
	v_mfma_f32_16x16x32_bf16 v[28:31], v[72:75], v[88:91], v[28:31]
	v_mfma_f32_16x16x32_bf16 v[56:59], v[64:67], v[188:191], v[56:59]
	v_mfma_f32_16x16x32_bf16 v[16:19], v[72:75], v[188:191], v[16:19]
	v_mfma_f32_16x16x32_bf16 v[52:55], v[64:67], v[196:199], v[52:55]
	v_mfma_f32_16x16x32_bf16 v[24:27], v[72:75], v[196:199], v[24:27]
	v_mfma_f32_16x16x32_bf16 v[48:51], v[68:71], v[84:87], v[48:51]
	v_mfma_f32_16x16x32_bf16 v[20:23], v[76:79], v[84:87], v[20:23]
	v_mfma_f32_16x16x32_bf16 v[60:63], v[68:71], v[92:95], v[60:63]
	v_mfma_f32_16x16x32_bf16 v[28:31], v[76:79], v[92:95], v[28:31]
	v_mfma_f32_16x16x32_bf16 v[56:59], v[68:71], v[192:195], v[56:59]
	v_mfma_f32_16x16x32_bf16 v[16:19], v[76:79], v[192:195], v[16:19]
	v_mfma_f32_16x16x32_bf16 v[52:55], v[68:71], v[200:203], v[52:55]
	v_mfma_f32_16x16x32_bf16 v[24:27], v[76:79], v[200:203], v[24:27]
	s_barrier
	s_setprio 0
	s_add_u32 s56, s82, 0x40080
	s_addc_u32 s57, s83, 0
	s_add_i32 s27, s58, s74
	v_lshl_add_u64 v[64:65], s[56:57], 0, v[144:145]
	s_mov_b32 m0, s27
	s_nop 0
	global_load_lds_dwordx4 v[64:65], off
	v_lshl_add_u64 v[64:65], s[56:57], 0, v[162:163]
	s_add_i32 m0, s27, 0x2000
	s_nop 0
	global_load_lds_dwordx4 v[64:65], off
	s_waitcnt vmcnt(6)
	s_setprio 1
	s_barrier
	v_mfma_f32_16x16x32_bf16 v[44:47], v[222:225], v[80:83], v[44:47]
	v_mfma_f32_16x16x32_bf16 v[12:15], v[232:235], v[80:83], v[12:15]
	v_mfma_f32_16x16x32_bf16 v[40:43], v[222:225], v[88:91], v[40:43]
	v_mfma_f32_16x16x32_bf16 v[8:11], v[232:235], v[88:91], v[8:11]
	v_mfma_f32_16x16x32_bf16 v[36:39], v[222:225], v[188:191], v[36:39]
	v_mfma_f32_16x16x32_bf16 v[4:7], v[232:235], v[188:191], v[4:7]
	v_mfma_f32_16x16x32_bf16 v[32:35], v[222:225], v[196:199], v[32:35]
	v_mfma_f32_16x16x32_bf16 v[0:3], v[232:235], v[196:199], v[0:3]
	v_mfma_f32_16x16x32_bf16 v[44:47], v[228:231], v[84:87], v[44:47]
	v_mfma_f32_16x16x32_bf16 v[12:15], v[236:239], v[84:87], v[12:15]
	v_mfma_f32_16x16x32_bf16 v[40:43], v[228:231], v[92:95], v[40:43]
	v_mfma_f32_16x16x32_bf16 v[8:11], v[236:239], v[92:95], v[8:11]
	v_mfma_f32_16x16x32_bf16 v[36:39], v[228:231], v[192:195], v[36:39]
	v_mfma_f32_16x16x32_bf16 v[4:7], v[236:239], v[192:195], v[4:7]
	v_mfma_f32_16x16x32_bf16 v[32:35], v[228:231], v[200:203], v[32:35]
	v_mfma_f32_16x16x32_bf16 v[0:3], v[236:239], v[200:203], v[0:3]
	s_barrier
	s_setprio 0
	s_add_i32 s37, s37, 2
	s_add_u32 s86, s86, 0x100
	s_addc_u32 s87, s87, 0
	s_add_u32 s33, s33, 0x100
	s_addc_u32 s36, s36, 0
	s_cmp_gt_u32 s37, 13
	s_cbranch_scc0 .LBB0_125
	s_lshl_b32 s1, s84, 8
	v_readlane_b32 s10, v254, 61
	s_add_i32 s1, s1, s10
	v_or_b32_e32 v198, s1, v216
	s_add_i32 s10, s1, 0x80
	v_or_b32_e32 v168, s10, v216
	v_lshl_or_b32 v188, s0, 7, v219
	v_lshlrev_b32_e32 v190, 2, v188
	v_lshlrev_b32_e32 v189, 1, v188
	s_ashr_i32 s11, s1, 5
	s_movk_i32 s10, 0xb00
	s_movk_i32 s20, 0x1600
	s_mov_b32 s101, 0xbfb8aa3b
	s_cmp_eq_u32 s84, s100
	s_cbranch_scc1 .Ldepi_w
	v_ashrrev_i32_e32 v199, 31, v198
	v_ashrrev_i32_e32 v169, 31, v168
	v_lshl_add_u64 v[170:171], v[198:199], 3, s[48:49]
	v_lshl_add_u64 v[172:173], v[168:169], 3, s[48:49]
	global_load_dwordx2 v[176:177], v[170:171], off
	global_load_dwordx2 v[202:203], v[170:171], off offset:128
	global_load_dwordx2 v[206:207], v[170:171], off offset:256
	global_load_dwordx2 v[222:223], v[170:171], off offset:384
	global_load_dwordx2 v[200:201], v[172:173], off
	global_load_dwordx2 v[196:197], v[172:173], off offset:128
	global_load_dwordx2 v[194:195], v[172:173], off offset:256
	global_load_dwordx2 v[192:193], v[172:173], off offset:384

.LBB0_195:
	s_add_u32 s42, s78, 0x80
	s_addc_u32 s43, s79, 0
	s_add_u32 s33, s44, 0x100
	s_addc_u32 s37, s45, 0
	s_mov_b32 s27, 0
	s_waitcnt lgkmcnt(0)
	s_add_i32 s56, s27, 2
	s_add_u32 s44, s42, 0x80
	s_addc_u32 s45, s43, 0
	s_add_i32 s57, 0, 0x10000
	v_add_u32_e32 v140, s57, v207
	ds_read_b128 v[128:131], v140
	ds_read_b128 v[132:135], v140 offset:1024
	ds_read_b128 v[136:139], v140 offset:2048
	ds_read_b128 v[140:143], v140 offset:3072
	s_cmp_eq_u32 s82, s27
	s_cselect_b32 s45, s77, s45
	s_cselect_b32 s44, s76, s44
	s_cselect_b32 s79, s1, s37
	s_cselect_b32 s78, s0, s33
	v_lshl_add_u64 v[176:177], s[42:43], 0, v[190:191]
	s_add_i32 m0, s85, 0xc000
	ds_read_b128 v[146:149], v217
	ds_read_b128 v[150:153], v217 offset:1024
	ds_read_b128 v[154:157], v217 offset:2048
	ds_read_b128 v[158:161], v217 offset:3072
	ds_read_b128 v[162:165], v217 offset:4096
	ds_read_b128 v[166:169], v217 offset:5120
	ds_read_b128 v[194:197], v217 offset:6144
	ds_read_b128 v[198:201], v217 offset:7168
	global_load_lds_dwordx4 v[176:177], off
	v_lshl_add_u64 v[176:177], s[42:43], 0, v[192:193]
	s_add_i32 m0, s85, 0xe000
	s_nop 0
	global_load_lds_dwordx4 v[176:177], off
	s_waitcnt lgkmcnt(8)
	s_setprio 1
	s_waitcnt lgkmcnt(0)
	s_barrier
	v_mfma_f32_16x16x32_bf16 v[124:127], v[128:131], v[146:149], 0
	v_mfma_f32_16x16x32_bf16 v[120:123], v[136:139], v[146:149], 0
	v_mfma_f32_16x16x32_bf16 v[108:111], v[128:131], v[154:157], 0
	v_mfma_f32_16x16x32_bf16 v[104:107], v[136:139], v[154:157], 0
	v_mfma_f32_16x16x32_bf16 v[92:95], v[128:131], v[162:165], 0
	v_mfma_f32_16x16x32_bf16 v[88:91], v[136:139], v[162:165], 0
	v_mfma_f32_16x16x32_bf16 v[76:79], v[128:131], v[194:197], 0
	v_mfma_f32_16x16x32_bf16 v[72:75], v[136:139], v[194:197], 0
	v_mfma_f32_16x16x32_bf16 v[124:127], v[132:135], v[150:153], v[124:127]
	v_mfma_f32_16x16x32_bf16 v[120:123], v[140:143], v[150:153], v[120:123]
	v_mfma_f32_16x16x32_bf16 v[108:111], v[132:135], v[158:161], v[108:111]
	v_mfma_f32_16x16x32_bf16 v[104:107], v[140:143], v[158:161], v[104:107]
	v_mfma_f32_16x16x32_bf16 v[92:95], v[132:135], v[166:169], v[92:95]
	v_mfma_f32_16x16x32_bf16 v[88:91], v[140:143], v[166:169], v[88:91]
	v_mfma_f32_16x16x32_bf16 v[76:79], v[132:135], v[198:201], v[76:79]
	v_mfma_f32_16x16x32_bf16 v[72:75], v[140:143], v[198:201], v[72:75]
	s_barrier
	s_setprio 0
	s_add_i32 s27, 0, 0x14000
	v_add_u32_e32 v176, s27, v207
	s_add_i32 s57, s57, s84
	ds_read_b128 v[202:205], v176
	ds_read_b128 v[218:221], v176 offset:1024
	ds_read_b128 v[222:225], v176 offset:2048
	ds_read_b128 v[228:231], v176 offset:3072
	v_lshl_add_u64 v[176:177], s[78:79], 0, v[144:145]
	s_mov_b32 m0, s57
	v_lshl_add_u64 v[232:233], s[78:79], 0, v[188:189]
	global_load_lds_dwordx4 v[176:177], off
	s_add_i32 m0, s57, 0x2000
	s_nop 0
	global_load_lds_dwordx4 v[232:233], off
	s_setprio 1
	s_waitcnt lgkmcnt(0)
	s_barrier
	v_mfma_f32_16x16x32_bf16 v[116:119], v[202:205], v[146:149], 0
	v_mfma_f32_16x16x32_bf16 v[112:115], v[222:225], v[146:149], 0
	v_mfma_f32_16x16x32_bf16 v[100:103], v[202:205], v[154:157], 0
	v_mfma_f32_16x16x32_bf16 v[96:99], v[222:225], v[154:157], 0
	v_mfma_f32_16x16x32_bf16 v[84:87], v[202:205], v[162:165], 0
	v_mfma_f32_16x16x32_bf16 v[80:83], v[222:225], v[162:165], 0
	v_mfma_f32_16x16x32_bf16 v[68:71], v[202:205], v[194:197], 0
	v_mfma_f32_16x16x32_bf16 v[64:67], v[222:225], v[194:197], 0
	v_mfma_f32_16x16x32_bf16 v[116:119], v[218:221], v[150:153], v[116:119]
	v_mfma_f32_16x16x32_bf16 v[112:115], v[228:231], v[150:153], v[112:115]
	v_mfma_f32_16x16x32_bf16 v[100:103], v[218:221], v[158:161], v[100:103]
	v_mfma_f32_16x16x32_bf16 v[96:99], v[228:231], v[158:161], v[96:99]
	v_mfma_f32_16x16x32_bf16 v[84:87], v[218:221], v[166:169], v[84:87]
	v_mfma_f32_16x16x32_bf16 v[80:83], v[228:231], v[166:169], v[80:83]
	v_mfma_f32_16x16x32_bf16 v[68:71], v[218:221], v[198:201], v[68:71]
	v_mfma_f32_16x16x32_bf16 v[64:67], v[228:231], v[198:201], v[64:67]
	s_barrier
	s_setprio 0
	s_mov_b32 m0, s85
	v_lshl_add_u64 v[234:235], s[44:45], 0, v[144:145]
	ds_read_b128 v[146:149], v217 offset:16384
	ds_read_b128 v[150:153], v217 offset:17408
	ds_read_b128 v[154:157], v217 offset:18432
	ds_read_b128 v[158:161], v217 offset:19456
	ds_read_b128 v[162:165], v217 offset:20480
	ds_read_b128 v[166:169], v217 offset:21504
	ds_read_b128 v[194:197], v217 offset:22528
	ds_read_b128 v[198:201], v217 offset:23552
	global_load_lds_dwordx4 v[234:235], off
	v_lshl_add_u64 v[236:237], s[44:45], 0, v[188:189]
	s_mov_b32 m0, s86
	s_nop 0
	global_load_lds_dwordx4 v[236:237], off
	s_setprio 1
	s_waitcnt lgkmcnt(0)
	s_barrier
	v_mfma_f32_16x16x32_bf16 v[60:63], v[128:131], v[146:149], 0
	v_mfma_f32_16x16x32_bf16 v[56:59], v[136:139], v[146:149], 0
	v_mfma_f32_16x16x32_bf16 v[44:47], v[128:131], v[154:157], 0
	v_mfma_f32_16x16x32_bf16 v[40:43], v[136:139], v[154:157], 0
	v_mfma_f32_16x16x32_bf16 v[28:31], v[128:131], v[162:165], 0
	v_mfma_f32_16x16x32_bf16 v[24:27], v[136:139], v[162:165], 0
	v_mfma_f32_16x16x32_bf16 v[12:15], v[128:131], v[194:197], 0
	v_mfma_f32_16x16x32_bf16 v[8:11], v[136:139], v[194:197], 0
	v_mfma_f32_16x16x32_bf16 v[60:63], v[132:135], v[150:153], v[60:63]
	v_mfma_f32_16x16x32_bf16 v[56:59], v[140:143], v[150:153], v[56:59]
	v_mfma_f32_16x16x32_bf16 v[44:47], v[132:135], v[158:161], v[44:47]
	v_mfma_f32_16x16x32_bf16 v[40:43], v[140:143], v[158:161], v[40:43]
	v_mfma_f32_16x16x32_bf16 v[28:31], v[132:135], v[166:169], v[28:31]
	v_mfma_f32_16x16x32_bf16 v[24:27], v[140:143], v[166:169], v[24:27]
	v_mfma_f32_16x16x32_bf16 v[12:15], v[132:135], v[198:201], v[12:15]
	v_mfma_f32_16x16x32_bf16 v[8:11], v[140:143], v[198:201], v[8:11]
	s_barrier
	s_setprio 0
	s_add_u32 s58, s78, s98
	s_addc_u32 s59, s79, 0
	s_add_i32 s27, s27, s84
	v_lshl_add_u64 v[238:239], s[58:59], 0, v[144:145]
	s_mov_b32 m0, s27
	v_lshl_add_u64 v[240:241], s[58:59], 0, v[188:189]
	global_load_lds_dwordx4 v[238:239], off
	s_add_i32 m0, s27, 0x2000
	s_nop 0
	global_load_lds_dwordx4 v[240:241], off
	s_waitcnt vmcnt(6)
	s_setprio 1
	s_barrier
	v_mfma_f32_16x16x32_bf16 v[52:55], v[202:205], v[146:149], 0
	v_mfma_f32_16x16x32_bf16 v[48:51], v[222:225], v[146:149], 0
	v_mfma_f32_16x16x32_bf16 v[36:39], v[202:205], v[154:157], 0
	v_mfma_f32_16x16x32_bf16 v[32:35], v[222:225], v[154:157], 0
	v_mfma_f32_16x16x32_bf16 v[20:23], v[202:205], v[162:165], 0
	v_mfma_f32_16x16x32_bf16 v[16:19], v[222:225], v[162:165], 0
	v_mfma_f32_16x16x32_bf16 v[4:7], v[202:205], v[194:197], 0
	v_mfma_f32_16x16x32_bf16 v[0:3], v[222:225], v[194:197], 0
	v_mfma_f32_16x16x32_bf16 v[52:55], v[218:221], v[150:153], v[52:55]
	v_mfma_f32_16x16x32_bf16 v[48:51], v[228:231], v[150:153], v[48:51]
	v_mfma_f32_16x16x32_bf16 v[36:39], v[218:221], v[158:161], v[36:39]
	v_mfma_f32_16x16x32_bf16 v[32:35], v[228:231], v[158:161], v[32:35]
	v_mfma_f32_16x16x32_bf16 v[20:23], v[218:221], v[166:169], v[20:23]
	v_mfma_f32_16x16x32_bf16 v[16:19], v[228:231], v[166:169], v[16:19]
	v_mfma_f32_16x16x32_bf16 v[4:7], v[218:221], v[198:201], v[4:7]
	v_mfma_f32_16x16x32_bf16 v[0:3], v[228:231], v[198:201], v[0:3]
	s_barrier
	s_setprio 0
	s_add_i32 s27, 0, 0x18000
	v_add_u32_e32 v140, s27, v207
	ds_read_b128 v[128:131], v140
	ds_read_b128 v[132:135], v140 offset:1024
	ds_read_b128 v[136:139], v140 offset:2048
	ds_read_b128 v[140:143], v140 offset:3072
	s_add_u32 s44, s44, s98
	s_addc_u32 s45, s45, 0
	s_mov_b32 m0, s87
	v_lshl_add_u64 v[202:203], s[44:45], 0, v[144:145]
	ds_read_b128 v[146:149], v217 offset:32768
	ds_read_b128 v[150:153], v217 offset:33792
	ds_read_b128 v[154:157], v217 offset:34816
	ds_read_b128 v[158:161], v217 offset:35840
	ds_read_b128 v[162:165], v217 offset:36864
	ds_read_b128 v[166:169], v217 offset:37888
	ds_read_b128 v[194:197], v217 offset:38912
	ds_read_b128 v[198:201], v217 offset:39936
	global_load_lds_dwordx4 v[202:203], off
	v_lshl_add_u64 v[202:203], s[44:45], 0, v[188:189]
	s_mov_b32 m0, s80
	s_nop 0
	global_load_lds_dwordx4 v[202:203], off
	s_waitcnt lgkmcnt(8)
	s_setprio 1
	s_waitcnt lgkmcnt(0)
	s_barrier
	v_mfma_f32_16x16x32_bf16 v[124:127], v[128:131], v[146:149], v[124:127]
	v_mfma_f32_16x16x32_bf16 v[120:123], v[136:139], v[146:149], v[120:123]
	v_mfma_f32_16x16x32_bf16 v[108:111], v[128:131], v[154:157], v[108:111]
	v_mfma_f32_16x16x32_bf16 v[104:107], v[136:139], v[154:157], v[104:107]
	v_mfma_f32_16x16x32_bf16 v[92:95], v[128:131], v[162:165], v[92:95]
	v_mfma_f32_16x16x32_bf16 v[88:91], v[136:139], v[162:165], v[88:91]
	v_mfma_f32_16x16x32_bf16 v[76:79], v[128:131], v[194:197], v[76:79]
	v_mfma_f32_16x16x32_bf16 v[72:75], v[136:139], v[194:197], v[72:75]
	v_mfma_f32_16x16x32_bf16 v[124:127], v[132:135], v[150:153], v[124:127]
	v_mfma_f32_16x16x32_bf16 v[120:123], v[140:143], v[150:153], v[120:123]
	v_mfma_f32_16x16x32_bf16 v[108:111], v[132:135], v[158:161], v[108:111]
	v_mfma_f32_16x16x32_bf16 v[104:107], v[140:143], v[158:161], v[104:107]
	v_mfma_f32_16x16x32_bf16 v[92:95], v[132:135], v[166:169], v[92:95]
	v_mfma_f32_16x16x32_bf16 v[88:91], v[140:143], v[166:169], v[88:91]
	v_mfma_f32_16x16x32_bf16 v[76:79], v[132:135], v[198:201], v[76:79]
	v_mfma_f32_16x16x32_bf16 v[72:75], v[140:143], v[198:201], v[72:75]
	s_barrier
	s_setprio 0
	s_add_i32 s44, 0, 0x1c000
	s_add_i32 s27, s27, s84
	v_add_u32_e32 v228, s44, v207
	v_lshl_add_u64 v[176:177], v[176:177], 0, s[18:19]
	s_mov_b32 m0, s27
	ds_read_b128 v[202:205], v228
	ds_read_b128 v[218:221], v228 offset:1024
	ds_read_b128 v[222:225], v228 offset:2048
	ds_read_b128 v[228:231], v228 offset:3072
	global_load_lds_dwordx4 v[176:177], off
	v_lshl_add_u64 v[176:177], v[232:233], 0, s[18:19]
	s_add_i32 m0, s27, 0x2000
	s_nop 0
	global_load_lds_dwordx4 v[176:177], off
	s_setprio 1
	s_waitcnt lgkmcnt(0)
	s_barrier
	v_mfma_f32_16x16x32_bf16 v[116:119], v[202:205], v[146:149], v[116:119]
	v_mfma_f32_16x16x32_bf16 v[112:115], v[222:225], v[146:149], v[112:115]
	v_mfma_f32_16x16x32_bf16 v[100:103], v[202:205], v[154:157], v[100:103]
	v_mfma_f32_16x16x32_bf16 v[96:99], v[222:225], v[154:157], v[96:99]
	v_mfma_f32_16x16x32_bf16 v[84:87], v[202:205], v[162:165], v[84:87]
	v_mfma_f32_16x16x32_bf16 v[80:83], v[222:225], v[162:165], v[80:83]
	v_mfma_f32_16x16x32_bf16 v[68:71], v[202:205], v[194:197], v[68:71]
	v_mfma_f32_16x16x32_bf16 v[64:67], v[222:225], v[194:197], v[64:67]
	v_mfma_f32_16x16x32_bf16 v[116:119], v[218:221], v[150:153], v[116:119]
	v_mfma_f32_16x16x32_bf16 v[112:115], v[228:231], v[150:153], v[112:115]
	v_mfma_f32_16x16x32_bf16 v[100:103], v[218:221], v[158:161], v[100:103]
	v_mfma_f32_16x16x32_bf16 v[96:99], v[228:231], v[158:161], v[96:99]
	v_mfma_f32_16x16x32_bf16 v[84:87], v[218:221], v[166:169], v[84:87]
	v_mfma_f32_16x16x32_bf16 v[80:83], v[228:231], v[166:169], v[80:83]
	v_mfma_f32_16x16x32_bf16 v[68:71], v[218:221], v[198:201], v[68:71]
	v_mfma_f32_16x16x32_bf16 v[64:67], v[228:231], v[198:201], v[64:67]
	s_barrier
	s_setprio 0
	s_mov_b32 m0, s30
	v_lshl_add_u64 v[176:177], v[234:235], 0, s[18:19]
	ds_read_b128 v[146:149], v217 offset:49152
	ds_read_b128 v[150:153], v217 offset:50176
	ds_read_b128 v[154:157], v217 offset:51200
	ds_read_b128 v[158:161], v217 offset:52224
	ds_read_b128 v[162:165], v217 offset:53248
	ds_read_b128 v[166:169], v217 offset:54272
	ds_read_b128 v[194:197], v217 offset:55296
	ds_read_b128 v[198:201], v217 offset:56320
	global_load_lds_dwordx4 v[176:177], off
	v_lshl_add_u64 v[176:177], v[236:237], 0, s[18:19]
	s_mov_b32 m0, s31
	s_nop 0
	global_load_lds_dwordx4 v[176:177], off
	s_setprio 1
	s_waitcnt lgkmcnt(0)
	s_barrier
	v_mfma_f32_16x16x32_bf16 v[60:63], v[128:131], v[146:149], v[60:63]
	v_mfma_f32_16x16x32_bf16 v[56:59], v[136:139], v[146:149], v[56:59]
	v_mfma_f32_16x16x32_bf16 v[44:47], v[128:131], v[154:157], v[44:47]
	v_mfma_f32_16x16x32_bf16 v[40:43], v[136:139], v[154:157], v[40:43]
	v_mfma_f32_16x16x32_bf16 v[28:31], v[128:131], v[162:165], v[28:31]
	v_mfma_f32_16x16x32_bf16 v[24:27], v[136:139], v[162:165], v[24:27]
	v_mfma_f32_16x16x32_bf16 v[12:15], v[128:131], v[194:197], v[12:15]
	v_mfma_f32_16x16x32_bf16 v[8:11], v[136:139], v[194:197], v[8:11]
	v_mfma_f32_16x16x32_bf16 v[60:63], v[132:135], v[150:153], v[60:63]
	v_mfma_f32_16x16x32_bf16 v[56:59], v[140:143], v[150:153], v[56:59]
	v_mfma_f32_16x16x32_bf16 v[44:47], v[132:135], v[158:161], v[44:47]
	v_mfma_f32_16x16x32_bf16 v[40:43], v[140:143], v[158:161], v[40:43]
	v_mfma_f32_16x16x32_bf16 v[28:31], v[132:135], v[166:169], v[28:31]
	v_mfma_f32_16x16x32_bf16 v[24:27], v[140:143], v[166:169], v[24:27]
	v_mfma_f32_16x16x32_bf16 v[12:15], v[132:135], v[198:201], v[12:15]
	v_mfma_f32_16x16x32_bf16 v[8:11], v[140:143], v[198:201], v[8:11]
	s_barrier
	s_setprio 0
	s_add_i32 s27, s44, s84
	v_lshl_add_u64 v[128:129], v[238:239], 0, s[18:19]
	s_mov_b32 m0, s27
	s_nop 0
	global_load_lds_dwordx4 v[128:129], off
	v_lshl_add_u64 v[128:129], v[240:241], 0, s[18:19]
	s_add_i32 m0, s27, 0x2000
	s_nop 0
	global_load_lds_dwordx4 v[128:129], off
	s_waitcnt vmcnt(6)
	s_setprio 1
	s_barrier
	v_mfma_f32_16x16x32_bf16 v[52:55], v[202:205], v[146:149], v[52:55]
	v_mfma_f32_16x16x32_bf16 v[48:51], v[222:225], v[146:149], v[48:51]
	v_mfma_f32_16x16x32_bf16 v[36:39], v[202:205], v[154:157], v[36:39]
	v_mfma_f32_16x16x32_bf16 v[32:35], v[222:225], v[154:157], v[32:35]
	v_mfma_f32_16x16x32_bf16 v[20:23], v[202:205], v[162:165], v[20:23]
	v_mfma_f32_16x16x32_bf16 v[16:19], v[222:225], v[162:165], v[16:19]
	v_mfma_f32_16x16x32_bf16 v[4:7], v[202:205], v[194:197], v[4:7]
	v_mfma_f32_16x16x32_bf16 v[0:3], v[222:225], v[194:197], v[0:3]
	v_mfma_f32_16x16x32_bf16 v[52:55], v[218:221], v[150:153], v[52:55]
	v_mfma_f32_16x16x32_bf16 v[48:51], v[228:231], v[150:153], v[48:51]
	v_mfma_f32_16x16x32_bf16 v[36:39], v[218:221], v[158:161], v[36:39]
	v_mfma_f32_16x16x32_bf16 v[32:35], v[228:231], v[158:161], v[32:35]
	v_mfma_f32_16x16x32_bf16 v[20:23], v[218:221], v[166:169], v[20:23]
	v_mfma_f32_16x16x32_bf16 v[16:19], v[228:231], v[166:169], v[16:19]
	v_mfma_f32_16x16x32_bf16 v[4:7], v[218:221], v[198:201], v[4:7]
	v_mfma_f32_16x16x32_bf16 v[0:3], v[228:231], v[198:201], v[0:3]
	s_barrier
	s_setprio 0
	s_add_u32 s42, s42, 0x100
	s_addc_u32 s43, s43, 0
	s_add_u32 s33, s33, 0x100
	s_addc_u32 s37, s37, 0
	s_cmp_ge_u32 s56, s34
	s_mov_b32 s27, s56
.LBB0_196:
	s_add_i32 s56, s27, 2
	s_add_u32 s44, s42, 0x80
	s_addc_u32 s45, s43, 0
	s_add_i32 s57, 0, 0x10000
	v_add_u32_e32 v140, s57, v207
	ds_read_b128 v[128:131], v140
	ds_read_b128 v[132:135], v140 offset:1024
	ds_read_b128 v[136:139], v140 offset:2048
	ds_read_b128 v[140:143], v140 offset:3072
	s_cmp_eq_u32 s82, s27
	s_cselect_b32 s45, s77, s45
	s_cselect_b32 s44, s76, s44
	s_cselect_b32 s79, s1, s37
	s_cselect_b32 s78, s0, s33
	v_lshl_add_u64 v[176:177], s[42:43], 0, v[190:191]
	s_add_i32 m0, s85, 0xc000
	ds_read_b128 v[146:149], v217
	ds_read_b128 v[150:153], v217 offset:1024
	ds_read_b128 v[154:157], v217 offset:2048
	ds_read_b128 v[158:161], v217 offset:3072
	ds_read_b128 v[162:165], v217 offset:4096
	ds_read_b128 v[166:169], v217 offset:5120
	ds_read_b128 v[194:197], v217 offset:6144
	ds_read_b128 v[198:201], v217 offset:7168
	global_load_lds_dwordx4 v[176:177], off
	v_lshl_add_u64 v[176:177], s[42:43], 0, v[192:193]
	s_add_i32 m0, s85, 0xe000
	s_nop 0
	global_load_lds_dwordx4 v[176:177], off
	s_waitcnt lgkmcnt(8)
	s_setprio 1
	s_waitcnt lgkmcnt(0)
	s_barrier
	v_mfma_f32_16x16x32_bf16 v[124:127], v[128:131], v[146:149], v[124:127]
	v_mfma_f32_16x16x32_bf16 v[120:123], v[136:139], v[146:149], v[120:123]
	v_mfma_f32_16x16x32_bf16 v[108:111], v[128:131], v[154:157], v[108:111]
	v_mfma_f32_16x16x32_bf16 v[104:107], v[136:139], v[154:157], v[104:107]
	v_mfma_f32_16x16x32_bf16 v[92:95], v[128:131], v[162:165], v[92:95]
	v_mfma_f32_16x16x32_bf16 v[88:91], v[136:139], v[162:165], v[88:91]
	v_mfma_f32_16x16x32_bf16 v[76:79], v[128:131], v[194:197], v[76:79]
	v_mfma_f32_16x16x32_bf16 v[72:75], v[136:139], v[194:197], v[72:75]
	v_mfma_f32_16x16x32_bf16 v[124:127], v[132:135], v[150:153], v[124:127]
	v_mfma_f32_16x16x32_bf16 v[120:123], v[140:143], v[150:153], v[120:123]
	v_mfma_f32_16x16x32_bf16 v[108:111], v[132:135], v[158:161], v[108:111]
	v_mfma_f32_16x16x32_bf16 v[104:107], v[140:143], v[158:161], v[104:107]
	v_mfma_f32_16x16x32_bf16 v[92:95], v[132:135], v[166:169], v[92:95]
	v_mfma_f32_16x16x32_bf16 v[88:91], v[140:143], v[166:169], v[88:91]
	v_mfma_f32_16x16x32_bf16 v[76:79], v[132:135], v[198:201], v[76:79]
	v_mfma_f32_16x16x32_bf16 v[72:75], v[140:143], v[198:201], v[72:75]
	s_barrier
	s_setprio 0
	s_add_i32 s27, 0, 0x14000
	v_add_u32_e32 v176, s27, v207
	s_add_i32 s57, s57, s84
	ds_read_b128 v[202:205], v176
	ds_read_b128 v[218:221], v176 offset:1024
	ds_read_b128 v[222:225], v176 offset:2048
	ds_read_b128 v[228:231], v176 offset:3072
	v_lshl_add_u64 v[176:177], s[78:79], 0, v[144:145]
	s_mov_b32 m0, s57
	v_lshl_add_u64 v[232:233], s[78:79], 0, v[188:189]
	global_load_lds_dwordx4 v[176:177], off
	s_add_i32 m0, s57, 0x2000
	s_nop 0
	global_load_lds_dwordx4 v[232:233], off
	s_setprio 1
	s_waitcnt lgkmcnt(0)
	s_barrier
	v_mfma_f32_16x16x32_bf16 v[116:119], v[202:205], v[146:149], v[116:119]
	v_mfma_f32_16x16x32_bf16 v[112:115], v[222:225], v[146:149], v[112:115]
	v_mfma_f32_16x16x32_bf16 v[100:103], v[202:205], v[154:157], v[100:103]
	v_mfma_f32_16x16x32_bf16 v[96:99], v[222:225], v[154:157], v[96:99]
	v_mfma_f32_16x16x32_bf16 v[84:87], v[202:205], v[162:165], v[84:87]
	v_mfma_f32_16x16x32_bf16 v[80:83], v[222:225], v[162:165], v[80:83]
	v_mfma_f32_16x16x32_bf16 v[68:71], v[202:205], v[194:197], v[68:71]
	v_mfma_f32_16x16x32_bf16 v[64:67], v[222:225], v[194:197], v[64:67]
	v_mfma_f32_16x16x32_bf16 v[116:119], v[218:221], v[150:153], v[116:119]
	v_mfma_f32_16x16x32_bf16 v[112:115], v[228:231], v[150:153], v[112:115]
	v_mfma_f32_16x16x32_bf16 v[100:103], v[218:221], v[158:161], v[100:103]
	v_mfma_f32_16x16x32_bf16 v[96:99], v[228:231], v[158:161], v[96:99]
	v_mfma_f32_16x16x32_bf16 v[84:87], v[218:221], v[166:169], v[84:87]
	v_mfma_f32_16x16x32_bf16 v[80:83], v[228:231], v[166:169], v[80:83]
	v_mfma_f32_16x16x32_bf16 v[68:71], v[218:221], v[198:201], v[68:71]
	v_mfma_f32_16x16x32_bf16 v[64:67], v[228:231], v[198:201], v[64:67]
	s_barrier
	s_setprio 0
	s_mov_b32 m0, s85
	v_lshl_add_u64 v[234:235], s[44:45], 0, v[144:145]
	ds_read_b128 v[146:149], v217 offset:16384
	ds_read_b128 v[150:153], v217 offset:17408
	ds_read_b128 v[154:157], v217 offset:18432
	ds_read_b128 v[158:161], v217 offset:19456
	ds_read_b128 v[162:165], v217 offset:20480
	ds_read_b128 v[166:169], v217 offset:21504
	ds_read_b128 v[194:197], v217 offset:22528
	ds_read_b128 v[198:201], v217 offset:23552
	global_load_lds_dwordx4 v[234:235], off
	v_lshl_add_u64 v[236:237], s[44:45], 0, v[188:189]
	s_mov_b32 m0, s86
	s_nop 0
	global_load_lds_dwordx4 v[236:237], off
	s_setprio 1
	s_waitcnt lgkmcnt(0)
	s_barrier
	v_mfma_f32_16x16x32_bf16 v[60:63], v[128:131], v[146:149], v[60:63]
	v_mfma_f32_16x16x32_bf16 v[56:59], v[136:139], v[146:149], v[56:59]
	v_mfma_f32_16x16x32_bf16 v[44:47], v[128:131], v[154:157], v[44:47]
	v_mfma_f32_16x16x32_bf16 v[40:43], v[136:139], v[154:157], v[40:43]
	v_mfma_f32_16x16x32_bf16 v[28:31], v[128:131], v[162:165], v[28:31]
	v_mfma_f32_16x16x32_bf16 v[24:27], v[136:139], v[162:165], v[24:27]
	v_mfma_f32_16x16x32_bf16 v[12:15], v[128:131], v[194:197], v[12:15]
	v_mfma_f32_16x16x32_bf16 v[8:11], v[136:139], v[194:197], v[8:11]
	v_mfma_f32_16x16x32_bf16 v[60:63], v[132:135], v[150:153], v[60:63]
	v_mfma_f32_16x16x32_bf16 v[56:59], v[140:143], v[150:153], v[56:59]
	v_mfma_f32_16x16x32_bf16 v[44:47], v[132:135], v[158:161], v[44:47]
	v_mfma_f32_16x16x32_bf16 v[40:43], v[140:143], v[158:161], v[40:43]
	v_mfma_f32_16x16x32_bf16 v[28:31], v[132:135], v[166:169], v[28:31]
	v_mfma_f32_16x16x32_bf16 v[24:27], v[140:143], v[166:169], v[24:27]
	v_mfma_f32_16x16x32_bf16 v[12:15], v[132:135], v[198:201], v[12:15]
	v_mfma_f32_16x16x32_bf16 v[8:11], v[140:143], v[198:201], v[8:11]
	s_barrier
	s_setprio 0
	s_add_u32 s58, s78, s98
	s_addc_u32 s59, s79, 0
	s_add_i32 s27, s27, s84
	v_lshl_add_u64 v[238:239], s[58:59], 0, v[144:145]
	s_mov_b32 m0, s27
	v_lshl_add_u64 v[240:241], s[58:59], 0, v[188:189]
	global_load_lds_dwordx4 v[238:239], off
	s_add_i32 m0, s27, 0x2000
	s_nop 0
	global_load_lds_dwordx4 v[240:241], off
	s_waitcnt vmcnt(6)
	s_setprio 1
	s_barrier
	v_mfma_f32_16x16x32_bf16 v[52:55], v[202:205], v[146:149], v[52:55]
	v_mfma_f32_16x16x32_bf16 v[48:51], v[222:225], v[146:149], v[48:51]
	v_mfma_f32_16x16x32_bf16 v[36:39], v[202:205], v[154:157], v[36:39]
	v_mfma_f32_16x16x32_bf16 v[32:35], v[222:225], v[154:157], v[32:35]
	v_mfma_f32_16x16x32_bf16 v[20:23], v[202:205], v[162:165], v[20:23]
	v_mfma_f32_16x16x32_bf16 v[16:19], v[222:225], v[162:165], v[16:19]
	v_mfma_f32_16x16x32_bf16 v[4:7], v[202:205], v[194:197], v[4:7]
	v_mfma_f32_16x16x32_bf16 v[0:3], v[222:225], v[194:197], v[0:3]
	v_mfma_f32_16x16x32_bf16 v[52:55], v[218:221], v[150:153], v[52:55]
	v_mfma_f32_16x16x32_bf16 v[48:51], v[228:231], v[150:153], v[48:51]
	v_mfma_f32_16x16x32_bf16 v[36:39], v[218:221], v[158:161], v[36:39]
	v_mfma_f32_16x16x32_bf16 v[32:35], v[228:231], v[158:161], v[32:35]
	v_mfma_f32_16x16x32_bf16 v[20:23], v[218:221], v[166:169], v[20:23]
	v_mfma_f32_16x16x32_bf16 v[16:19], v[228:231], v[166:169], v[16:19]
	v_mfma_f32_16x16x32_bf16 v[4:7], v[218:221], v[198:201], v[4:7]
	v_mfma_f32_16x16x32_bf16 v[0:3], v[228:231], v[198:201], v[0:3]
	s_barrier
	s_setprio 0
	s_add_i32 s27, 0, 0x18000
	v_add_u32_e32 v140, s27, v207
	ds_read_b128 v[128:131], v140
	ds_read_b128 v[132:135], v140 offset:1024
	ds_read_b128 v[136:139], v140 offset:2048
	ds_read_b128 v[140:143], v140 offset:3072
	s_add_u32 s44, s44, s98
	s_addc_u32 s45, s45, 0
	s_mov_b32 m0, s87
	v_lshl_add_u64 v[202:203], s[44:45], 0, v[144:145]
	ds_read_b128 v[146:149], v217 offset:32768
	ds_read_b128 v[150:153], v217 offset:33792
	ds_read_b128 v[154:157], v217 offset:34816
	ds_read_b128 v[158:161], v217 offset:35840
	ds_read_b128 v[162:165], v217 offset:36864
	ds_read_b128 v[166:169], v217 offset:37888
	ds_read_b128 v[194:197], v217 offset:38912
	ds_read_b128 v[198:201], v217 offset:39936
	global_load_lds_dwordx4 v[202:203], off
	v_lshl_add_u64 v[202:203], s[44:45], 0, v[188:189]
	s_mov_b32 m0, s80
	s_nop 0
	global_load_lds_dwordx4 v[202:203], off
	s_waitcnt lgkmcnt(8)
	s_setprio 1
	s_waitcnt lgkmcnt(0)
	s_barrier
	v_mfma_f32_16x16x32_bf16 v[124:127], v[128:131], v[146:149], v[124:127]
	v_mfma_f32_16x16x32_bf16 v[120:123], v[136:139], v[146:149], v[120:123]
	v_mfma_f32_16x16x32_bf16 v[108:111], v[128:131], v[154:157], v[108:111]
	v_mfma_f32_16x16x32_bf16 v[104:107], v[136:139], v[154:157], v[104:107]
	v_mfma_f32_16x16x32_bf16 v[92:95], v[128:131], v[162:165], v[92:95]
	v_mfma_f32_16x16x32_bf16 v[88:91], v[136:139], v[162:165], v[88:91]
	v_mfma_f32_16x16x32_bf16 v[76:79], v[128:131], v[194:197], v[76:79]
	v_mfma_f32_16x16x32_bf16 v[72:75], v[136:139], v[194:197], v[72:75]
	v_mfma_f32_16x16x32_bf16 v[124:127], v[132:135], v[150:153], v[124:127]
	v_mfma_f32_16x16x32_bf16 v[120:123], v[140:143], v[150:153], v[120:123]
	v_mfma_f32_16x16x32_bf16 v[108:111], v[132:135], v[158:161], v[108:111]
	v_mfma_f32_16x16x32_bf16 v[104:107], v[140:143], v[158:161], v[104:107]
	v_mfma_f32_16x16x32_bf16 v[92:95], v[132:135], v[166:169], v[92:95]
	v_mfma_f32_16x16x32_bf16 v[88:91], v[140:143], v[166:169], v[88:91]
	v_mfma_f32_16x16x32_bf16 v[76:79], v[132:135], v[198:201], v[76:79]
	v_mfma_f32_16x16x32_bf16 v[72:75], v[140:143], v[198:201], v[72:75]
	s_barrier
	s_setprio 0
	s_add_i32 s44, 0, 0x1c000
	s_add_i32 s27, s27, s84
	v_add_u32_e32 v228, s44, v207
	v_lshl_add_u64 v[176:177], v[176:177], 0, s[18:19]
	s_mov_b32 m0, s27
	ds_read_b128 v[202:205], v228
	ds_read_b128 v[218:221], v228 offset:1024
	ds_read_b128 v[222:225], v228 offset:2048
	ds_read_b128 v[228:231], v228 offset:3072
	global_load_lds_dwordx4 v[176:177], off
	v_lshl_add_u64 v[176:177], v[232:233], 0, s[18:19]
	s_add_i32 m0, s27, 0x2000
	s_nop 0
	global_load_lds_dwordx4 v[176:177], off
	s_setprio 1
	s_waitcnt lgkmcnt(0)
	s_barrier
	v_mfma_f32_16x16x32_bf16 v[116:119], v[202:205], v[146:149], v[116:119]
	v_mfma_f32_16x16x32_bf16 v[112:115], v[222:225], v[146:149], v[112:115]
	v_mfma_f32_16x16x32_bf16 v[100:103], v[202:205], v[154:157], v[100:103]
	v_mfma_f32_16x16x32_bf16 v[96:99], v[222:225], v[154:157], v[96:99]
	v_mfma_f32_16x16x32_bf16 v[84:87], v[202:205], v[162:165], v[84:87]
	v_mfma_f32_16x16x32_bf16 v[80:83], v[222:225], v[162:165], v[80:83]
	v_mfma_f32_16x16x32_bf16 v[68:71], v[202:205], v[194:197], v[68:71]
	v_mfma_f32_16x16x32_bf16 v[64:67], v[222:225], v[194:197], v[64:67]
	v_mfma_f32_16x16x32_bf16 v[116:119], v[218:221], v[150:153], v[116:119]
	v_mfma_f32_16x16x32_bf16 v[112:115], v[228:231], v[150:153], v[112:115]
	v_mfma_f32_16x16x32_bf16 v[100:103], v[218:221], v[158:161], v[100:103]
	v_mfma_f32_16x16x32_bf16 v[96:99], v[228:231], v[158:161], v[96:99]
	v_mfma_f32_16x16x32_bf16 v[84:87], v[218:221], v[166:169], v[84:87]
	v_mfma_f32_16x16x32_bf16 v[80:83], v[228:231], v[166:169], v[80:83]
	v_mfma_f32_16x16x32_bf16 v[68:71], v[218:221], v[198:201], v[68:71]
	v_mfma_f32_16x16x32_bf16 v[64:67], v[228:231], v[198:201], v[64:67]
	s_barrier
	s_setprio 0
	s_mov_b32 m0, s30
	v_lshl_add_u64 v[176:177], v[234:235], 0, s[18:19]
	ds_read_b128 v[146:149], v217 offset:49152
	ds_read_b128 v[150:153], v217 offset:50176
	ds_read_b128 v[154:157], v217 offset:51200
	ds_read_b128 v[158:161], v217 offset:52224
	ds_read_b128 v[162:165], v217 offset:53248
	ds_read_b128 v[166:169], v217 offset:54272
	ds_read_b128 v[194:197], v217 offset:55296
	ds_read_b128 v[198:201], v217 offset:56320
	global_load_lds_dwordx4 v[176:177], off
	v_lshl_add_u64 v[176:177], v[236:237], 0, s[18:19]
	s_mov_b32 m0, s31
	s_nop 0
	global_load_lds_dwordx4 v[176:177], off
	s_setprio 1
	s_waitcnt lgkmcnt(0)
	s_barrier
	v_mfma_f32_16x16x32_bf16 v[60:63], v[128:131], v[146:149], v[60:63]
	v_mfma_f32_16x16x32_bf16 v[56:59], v[136:139], v[146:149], v[56:59]
	v_mfma_f32_16x16x32_bf16 v[44:47], v[128:131], v[154:157], v[44:47]
	v_mfma_f32_16x16x32_bf16 v[40:43], v[136:139], v[154:157], v[40:43]
	v_mfma_f32_16x16x32_bf16 v[28:31], v[128:131], v[162:165], v[28:31]
	v_mfma_f32_16x16x32_bf16 v[24:27], v[136:139], v[162:165], v[24:27]
	v_mfma_f32_16x16x32_bf16 v[12:15], v[128:131], v[194:197], v[12:15]
	v_mfma_f32_16x16x32_bf16 v[8:11], v[136:139], v[194:197], v[8:11]
	v_mfma_f32_16x16x32_bf16 v[60:63], v[132:135], v[150:153], v[60:63]
	v_mfma_f32_16x16x32_bf16 v[56:59], v[140:143], v[150:153], v[56:59]
	v_mfma_f32_16x16x32_bf16 v[44:47], v[132:135], v[158:161], v[44:47]
	v_mfma_f32_16x16x32_bf16 v[40:43], v[140:143], v[158:161], v[40:43]
	v_mfma_f32_16x16x32_bf16 v[28:31], v[132:135], v[166:169], v[28:31]
	v_mfma_f32_16x16x32_bf16 v[24:27], v[140:143], v[166:169], v[24:27]
	v_mfma_f32_16x16x32_bf16 v[12:15], v[132:135], v[198:201], v[12:15]
	v_mfma_f32_16x16x32_bf16 v[8:11], v[140:143], v[198:201], v[8:11]
	s_barrier
	s_setprio 0
	s_add_i32 s27, s44, s84
	v_lshl_add_u64 v[128:129], v[238:239], 0, s[18:19]
	s_mov_b32 m0, s27
	s_nop 0
	global_load_lds_dwordx4 v[128:129], off
	v_lshl_add_u64 v[128:129], v[240:241], 0, s[18:19]
	s_add_i32 m0, s27, 0x2000
	s_nop 0
	global_load_lds_dwordx4 v[128:129], off
	s_waitcnt vmcnt(6)
	s_setprio 1
	s_barrier
	v_mfma_f32_16x16x32_bf16 v[52:55], v[202:205], v[146:149], v[52:55]
	v_mfma_f32_16x16x32_bf16 v[48:51], v[222:225], v[146:149], v[48:51]
	v_mfma_f32_16x16x32_bf16 v[36:39], v[202:205], v[154:157], v[36:39]
	v_mfma_f32_16x16x32_bf16 v[32:35], v[222:225], v[154:157], v[32:35]
	v_mfma_f32_16x16x32_bf16 v[20:23], v[202:205], v[162:165], v[20:23]
	v_mfma_f32_16x16x32_bf16 v[16:19], v[222:225], v[162:165], v[16:19]
	v_mfma_f32_16x16x32_bf16 v[4:7], v[202:205], v[194:197], v[4:7]
	v_mfma_f32_16x16x32_bf16 v[0:3], v[222:225], v[194:197], v[0:3]
	v_mfma_f32_16x16x32_bf16 v[52:55], v[218:221], v[150:153], v[52:55]
	v_mfma_f32_16x16x32_bf16 v[48:51], v[228:231], v[150:153], v[48:51]
	v_mfma_f32_16x16x32_bf16 v[36:39], v[218:221], v[158:161], v[36:39]
	v_mfma_f32_16x16x32_bf16 v[32:35], v[228:231], v[158:161], v[32:35]
	v_mfma_f32_16x16x32_bf16 v[20:23], v[218:221], v[166:169], v[20:23]
	v_mfma_f32_16x16x32_bf16 v[16:19], v[228:231], v[166:169], v[16:19]
	v_mfma_f32_16x16x32_bf16 v[4:7], v[218:221], v[198:201], v[4:7]
	v_mfma_f32_16x16x32_bf16 v[0:3], v[228:231], v[198:201], v[0:3]
	s_barrier
	s_setprio 0
	s_add_u32 s42, s42, 0x100
	s_addc_u32 s43, s43, 0
	s_add_u32 s33, s33, 0x100
	s_addc_u32 s37, s37, 0
	s_cmp_ge_u32 s56, s34
	s_mov_b32 s27, s56
	s_cbranch_scc0 .LBB0_196
	v_lshl_add_u32 v194, s11, 8, v206
	v_ashrrev_i32_e32 v195, 31, v194
	v_lshl_or_b32 v196, s10, 8, v216
	v_lshlrev_b64 v[128:129], 11, v[194:195]
	v_ashrrev_i32_e32 v197, 31, v196
	s_and_b64 vcc, exec, s[92:93]
	v_or_b32_e32 v198, 16, v194
	v_lshl_add_u64 v[200:201], s[54:55], 0, v[128:129]
	s_cbranch_vccz .LBB0_215
	v_lshlrev_b64 v[128:129], 12, v[194:195]
	v_lshl_add_u64 v[128:129], s[50:51], 0, v[128:129]
	v_lshlrev_b64 v[130:131], 2, v[196:197]
	v_lshl_add_u64 v[128:129], v[128:129], 0, v[130:131]
	global_load_dwordx4 v[146:149], v[128:129], off offset:16
	global_load_dwordx4 v[150:153], v[128:129], off
	global_load_dwordx4 v[154:157], v[128:129], off offset:528
	global_load_dwordx4 v[158:161], v[128:129], off offset:512
	v_ashrrev_i32_e32 v199, 31, v198
	v_lshlrev_b64 v[128:129], 12, v[198:199]
	v_lshl_add_u64 v[128:129], s[50:51], 0, v[128:129]
	v_lshl_add_u64 v[132:133], v[128:129], 0, v[130:131]
	global_load_dwordx4 v[136:139], v[132:133], off offset:16
	global_load_dwordx4 v[140:143], v[132:133], off
	global_load_dwordx4 v[128:131], v[132:133], off offset:528
	s_nop 0
	global_load_dwordx4 v[132:135], v[132:133], off offset:512
	v_lshl_add_u64 v[166:167], v[196:197], 1, v[200:201]
	s_waitcnt vmcnt(0)
	v_pk_add_f32 v[164:165], v[120:121], v[146:147]
	v_pk_add_f32 v[152:153], v[126:127], v[152:153]
	v_pk_add_f32 v[150:151], v[124:125], v[150:151]
	v_pk_add_f32 v[162:163], v[122:123], v[148:149]
	v_cvt_pk_bf16_f32 v146, v150, v151
	v_cvt_pk_bf16_f32 v147, v152, v153
	v_cvt_pk_bf16_f32 v148, v164, v165
	v_pk_add_f32 v[156:157], v[114:115], v[156:157]
	v_cvt_pk_bf16_f32 v149, v162, v163
	global_store_dwordx4 v[166:167], v[146:149], off
	v_pk_add_f32 v[154:155], v[112:113], v[154:155]
	s_nop 0
	v_mul_f32_e32 v146, v151, v151
	v_mul_f32_e32 v147, v153, v153
	v_fmac_f32_e32 v146, v150, v150
	v_fmac_f32_e32 v147, v152, v152
	v_add_f32_e32 v146, v146, v147
	v_mul_f32_e32 v147, v165, v165
	v_mul_f32_e32 v148, v163, v163
	v_fmac_f32_e32 v147, v164, v164
	v_fmac_f32_e32 v148, v162, v162
	v_add_f32_e32 v147, v147, v148
	v_add_f32_e32 v162, v146, v147
	v_pk_add_f32 v[150:151], v[118:119], v[160:161]
	v_pk_add_f32 v[152:153], v[116:117], v[158:159]
	s_nop 0
	v_cvt_pk_bf16_f32 v146, v152, v153
	v_cvt_pk_bf16_f32 v147, v150, v151
	v_cvt_pk_bf16_f32 v148, v154, v155
	v_cvt_pk_bf16_f32 v149, v156, v157
	global_store_dwordx4 v[166:167], v[146:149], off offset:256
	s_nop 1
	v_mul_f32_e32 v146, v153, v153
	v_mul_f32_e32 v147, v151, v151
	v_fmac_f32_e32 v146, v152, v152
	v_fmac_f32_e32 v147, v150, v150
	v_add_f32_e32 v146, v146, v147
	v_mul_f32_e32 v147, v155, v155
	v_mul_f32_e32 v148, v157, v157
	v_fmac_f32_e32 v147, v154, v154
	v_fmac_f32_e32 v148, v156, v156
	v_add_f32_e32 v147, v147, v148
	v_and_b32_e32 v148, 64, v214
	v_add_f32_e32 v146, v146, v147
	v_xor_b32_e32 v147, 16, v214
	v_add_u32_e32 v148, 64, v148
	v_cmp_lt_i32_e32 vcc, v147, v148
	v_add_f32_e32 v146, v162, v146
	s_nop 0
	v_cndmask_b32_e32 v147, v214, v147, vcc
	v_lshlrev_b32_e32 v218, 2, v147
	ds_bpermute_b32 v147, v218, v146
	s_waitcnt lgkmcnt(0)
	v_add_f32_e32 v146, v146, v147
	v_xor_b32_e32 v147, 32, v214
	v_cmp_lt_i32_e32 vcc, v147, v148
	s_nop 1
	v_cndmask_b32_e32 v147, v214, v147, vcc
	v_lshlrev_b32_e32 v219, 2, v147
	ds_bpermute_b32 v147, v219, v146
	s_and_saveexec_b64 s[42:43], s[38:39]
	s_cbranch_execz .LBB0_200
	s_waitcnt lgkmcnt(0)
	v_add_f32_e32 v146, v146, v147
	v_fma_f32 v146, v146, s91, 0.5
	v_trunc_f32_e32 v146, v146
	v_mul_f32_e32 v147, 0x2f800000, v146
	v_floor_f32_e32 v147, v147
	v_fmac_f32_e32 v146, 0xcf800000, v147
	v_cvt_u32_f32_e32 v146, v146
	v_cvt_u32_f32_e32 v147, v147
	v_lshl_add_u64 v[148:149], v[194:195], 3, s[52:53]
	global_atomic_add_x2 v[148:149], v[146:147], off

.LBB0_325:
	s_ashr_i32 s93, s92, 31
	s_lshl_b64 s[30:31], s[92:93], 19
	s_add_u32 s94, s54, s30
	v_cmp_lt_i64_e32 vcc, s[50:51], v[186:187]
	s_addc_u32 s95, s55, s31
	s_and_b64 s[30:31], vcc, exec
	s_cselect_b32 s1, s95, s53
	s_cselect_b32 s11, s94, s52
	s_ashr_i32 s9, s8, 31
	s_lshl_b64 s[30:31], s[8:9], 19
	s_add_u32 s28, s80, s30
	s_addc_u32 s29, s78, s31
	s_and_b64 s[30:31], vcc, exec
	s_cselect_b32 s25, s29, s73
	s_cselect_b32 s30, s28, s72
	s_add_u32 s52, s52, 0x40080
	s_addc_u32 s53, s53, 0
	s_add_u32 s31, s72, 0x100
	s_addc_u32 s33, s73, 0
	s_mov_b32 s34, -2
	s_add_u32 s27, s52, 0xfffc0080
	s_addc_u32 s35, s53, -1
	s_add_i32 s36, 0, 0x10000
	v_add_u32_e32 v140, s36, v216
	ds_read_b128 v[128:131], v140
	ds_read_b128 v[132:135], v140 offset:1024
	ds_read_b128 v[136:139], v140 offset:2048
	ds_read_b128 v[140:143], v140 offset:3072
	s_cmp_eq_u32 s34, 12
	s_cselect_b32 s75, s1, s35
	s_cselect_b32 s74, s11, s27
	s_cselect_b32 s73, s25, s33
	s_cselect_b32 s72, s30, s31
	v_lshl_add_u64 v[168:169], s[52:53], 0, v[152:153]
	s_add_i32 m0, s83, 0xc000
	ds_read_b128 v[156:159], v217
	ds_read_b128 v[160:163], v217 offset:1024
	ds_read_b128 v[164:167], v217 offset:2048
	ds_read_b128 v[188:191], v217 offset:3072
	ds_read_b128 v[192:195], v217 offset:4096
	ds_read_b128 v[196:199], v217 offset:5120
	ds_read_b128 v[200:203], v217 offset:6144
	ds_read_b128 v[204:207], v217 offset:7168
	global_load_lds_dwordx4 v[168:169], off
	v_lshl_add_u64 v[168:169], s[52:53], 0, v[154:155]
	s_add_i32 m0, s83, 0xe000
	s_nop 0
	global_load_lds_dwordx4 v[168:169], off
	s_waitcnt lgkmcnt(8)
	s_setprio 1
	s_waitcnt lgkmcnt(0)
	s_barrier
	v_mfma_f32_16x16x32_bf16 v[124:127], v[128:131], v[156:159], 0
	v_mfma_f32_16x16x32_bf16 v[120:123], v[136:139], v[156:159], 0
	v_mfma_f32_16x16x32_bf16 v[108:111], v[128:131], v[164:167], 0
	v_mfma_f32_16x16x32_bf16 v[104:107], v[136:139], v[164:167], 0
	v_mfma_f32_16x16x32_bf16 v[92:95], v[128:131], v[192:195], 0
	v_mfma_f32_16x16x32_bf16 v[88:91], v[136:139], v[192:195], 0
	v_mfma_f32_16x16x32_bf16 v[76:79], v[128:131], v[200:203], 0
	v_mfma_f32_16x16x32_bf16 v[72:75], v[136:139], v[200:203], 0
	v_mfma_f32_16x16x32_bf16 v[124:127], v[132:135], v[160:163], v[124:127]
	v_mfma_f32_16x16x32_bf16 v[120:123], v[140:143], v[160:163], v[120:123]
	v_mfma_f32_16x16x32_bf16 v[108:111], v[132:135], v[188:191], v[108:111]
	v_mfma_f32_16x16x32_bf16 v[104:107], v[140:143], v[188:191], v[104:107]
	v_mfma_f32_16x16x32_bf16 v[92:95], v[132:135], v[196:199], v[92:95]
	v_mfma_f32_16x16x32_bf16 v[88:91], v[140:143], v[196:199], v[88:91]
	v_mfma_f32_16x16x32_bf16 v[76:79], v[132:135], v[204:207], v[76:79]
	v_mfma_f32_16x16x32_bf16 v[72:75], v[140:143], v[204:207], v[72:75]
	s_barrier
	s_setprio 0
	s_add_i32 s27, 0, 0x14000
	s_add_i32 s35, s36, s81
	v_add_u32_e32 v144, s27, v216
	v_lshl_add_u64 v[168:169], s[72:73], 0, v[148:149]
	s_mov_b32 m0, s35
	ds_read_b128 v[220:223], v144
	ds_read_b128 v[228:231], v144 offset:1024
	ds_read_b128 v[232:235], v144 offset:2048
	ds_read_b128 v[236:239], v144 offset:3072
	global_load_lds_dwordx4 v[168:169], off
	v_lshl_add_u64 v[176:177], s[72:73], 0, v[146:147]
	s_add_i32 m0, s35, 0x2000
	s_nop 0
	global_load_lds_dwordx4 v[176:177], off
	s_setprio 1
	s_waitcnt lgkmcnt(0)
	s_barrier
	v_mfma_f32_16x16x32_bf16 v[116:119], v[220:223], v[156:159], 0
	v_mfma_f32_16x16x32_bf16 v[112:115], v[232:235], v[156:159], 0
	v_mfma_f32_16x16x32_bf16 v[100:103], v[220:223], v[164:167], 0
	v_mfma_f32_16x16x32_bf16 v[96:99], v[232:235], v[164:167], 0
	v_mfma_f32_16x16x32_bf16 v[84:87], v[220:223], v[192:195], 0
	v_mfma_f32_16x16x32_bf16 v[80:83], v[232:235], v[192:195], 0
	v_mfma_f32_16x16x32_bf16 v[68:71], v[220:223], v[200:203], 0
	v_mfma_f32_16x16x32_bf16 v[64:67], v[232:235], v[200:203], 0
	v_mfma_f32_16x16x32_bf16 v[116:119], v[228:231], v[160:163], v[116:119]
	v_mfma_f32_16x16x32_bf16 v[112:115], v[236:239], v[160:163], v[112:115]
	v_mfma_f32_16x16x32_bf16 v[100:103], v[228:231], v[188:191], v[100:103]
	v_mfma_f32_16x16x32_bf16 v[96:99], v[236:239], v[188:191], v[96:99]
	v_mfma_f32_16x16x32_bf16 v[84:87], v[228:231], v[196:199], v[84:87]
	v_mfma_f32_16x16x32_bf16 v[80:83], v[236:239], v[196:199], v[80:83]
	v_mfma_f32_16x16x32_bf16 v[68:71], v[228:231], v[204:207], v[68:71]
	v_mfma_f32_16x16x32_bf16 v[64:67], v[236:239], v[204:207], v[64:67]
	s_barrier
	s_setprio 0
	s_mov_b32 m0, s83
	v_lshl_add_u64 v[224:225], s[74:75], 0, v[148:149]
	ds_read_b128 v[156:159], v217 offset:16384
	ds_read_b128 v[160:163], v217 offset:17408
	ds_read_b128 v[164:167], v217 offset:18432
	ds_read_b128 v[188:191], v217 offset:19456
	ds_read_b128 v[192:195], v217 offset:20480
	ds_read_b128 v[196:199], v217 offset:21504
	ds_read_b128 v[200:203], v217 offset:22528
	ds_read_b128 v[204:207], v217 offset:23552
	global_load_lds_dwordx4 v[224:225], off
	v_lshl_add_u64 v[240:241], s[74:75], 0, v[146:147]
	s_mov_b32 m0, s84
	s_nop 0
	global_load_lds_dwordx4 v[240:241], off
	s_setprio 1
	s_waitcnt lgkmcnt(0)
	s_barrier
	v_mfma_f32_16x16x32_bf16 v[60:63], v[128:131], v[156:159], 0
	v_mfma_f32_16x16x32_bf16 v[56:59], v[136:139], v[156:159], 0
	v_mfma_f32_16x16x32_bf16 v[44:47], v[128:131], v[164:167], 0
	v_mfma_f32_16x16x32_bf16 v[40:43], v[136:139], v[164:167], 0
	v_mfma_f32_16x16x32_bf16 v[28:31], v[128:131], v[192:195], 0
	v_mfma_f32_16x16x32_bf16 v[24:27], v[136:139], v[192:195], 0
	v_mfma_f32_16x16x32_bf16 v[12:15], v[128:131], v[200:203], 0
	v_mfma_f32_16x16x32_bf16 v[8:11], v[136:139], v[200:203], 0
	v_mfma_f32_16x16x32_bf16 v[60:63], v[132:135], v[160:163], v[60:63]
	v_mfma_f32_16x16x32_bf16 v[56:59], v[140:143], v[160:163], v[56:59]
	v_mfma_f32_16x16x32_bf16 v[44:47], v[132:135], v[188:191], v[44:47]
	v_mfma_f32_16x16x32_bf16 v[40:43], v[140:143], v[188:191], v[40:43]
	v_mfma_f32_16x16x32_bf16 v[28:31], v[132:135], v[196:199], v[28:31]
	v_mfma_f32_16x16x32_bf16 v[24:27], v[140:143], v[196:199], v[24:27]
	v_mfma_f32_16x16x32_bf16 v[12:15], v[132:135], v[204:207], v[12:15]
	v_mfma_f32_16x16x32_bf16 v[8:11], v[140:143], v[204:207], v[8:11]
	s_barrier
	s_setprio 0
	s_add_u32 s36, s72, 0x40000
	s_addc_u32 s37, s73, 0
	s_add_i32 s27, s27, s81
	v_lshl_add_u64 v[128:129], s[36:37], 0, v[148:149]
	s_mov_b32 m0, s27
	s_nop 0
	global_load_lds_dwordx4 v[128:129], off
	v_lshl_add_u64 v[128:129], s[36:37], 0, v[146:147]
	s_add_i32 m0, s27, 0x2000
	s_nop 0
	global_load_lds_dwordx4 v[128:129], off
	s_waitcnt vmcnt(6)
	s_setprio 1
	s_barrier
	v_mfma_f32_16x16x32_bf16 v[52:55], v[220:223], v[156:159], 0
	v_mfma_f32_16x16x32_bf16 v[48:51], v[232:235], v[156:159], 0
	v_mfma_f32_16x16x32_bf16 v[36:39], v[220:223], v[164:167], 0
	v_mfma_f32_16x16x32_bf16 v[32:35], v[232:235], v[164:167], 0
	v_mfma_f32_16x16x32_bf16 v[20:23], v[220:223], v[192:195], 0
	v_mfma_f32_16x16x32_bf16 v[16:19], v[232:235], v[192:195], 0
	v_mfma_f32_16x16x32_bf16 v[4:7], v[220:223], v[200:203], 0
	v_mfma_f32_16x16x32_bf16 v[0:3], v[232:235], v[200:203], 0
	v_mfma_f32_16x16x32_bf16 v[52:55], v[228:231], v[160:163], v[52:55]
	v_mfma_f32_16x16x32_bf16 v[48:51], v[236:239], v[160:163], v[48:51]
	v_mfma_f32_16x16x32_bf16 v[36:39], v[228:231], v[188:191], v[36:39]
	v_mfma_f32_16x16x32_bf16 v[32:35], v[236:239], v[188:191], v[32:35]
	v_mfma_f32_16x16x32_bf16 v[20:23], v[228:231], v[196:199], v[20:23]
	v_mfma_f32_16x16x32_bf16 v[16:19], v[236:239], v[196:199], v[16:19]
	v_mfma_f32_16x16x32_bf16 v[4:7], v[228:231], v[204:207], v[4:7]
	v_mfma_f32_16x16x32_bf16 v[0:3], v[236:239], v[204:207], v[0:3]
	s_barrier
	s_setprio 0
	s_add_i32 s27, 0, 0x18000
	v_add_u32_e32 v140, s27, v216
	ds_read_b128 v[128:131], v140
	ds_read_b128 v[132:135], v140 offset:1024
	ds_read_b128 v[136:139], v140 offset:2048
	ds_read_b128 v[140:143], v140 offset:3072
	s_add_u32 s36, s74, 0x40000
	s_addc_u32 s37, s75, 0
	s_mov_b32 m0, s85
	v_lshl_add_u64 v[220:221], s[36:37], 0, v[148:149]
	ds_read_b128 v[156:159], v217 offset:32768
	ds_read_b128 v[160:163], v217 offset:33792
	ds_read_b128 v[164:167], v217 offset:34816
	ds_read_b128 v[188:191], v217 offset:35840
	ds_read_b128 v[192:195], v217 offset:36864
	ds_read_b128 v[196:199], v217 offset:37888
	ds_read_b128 v[200:203], v217 offset:38912
	ds_read_b128 v[204:207], v217 offset:39936
	global_load_lds_dwordx4 v[220:221], off
	v_lshl_add_u64 v[220:221], s[36:37], 0, v[146:147]
	s_mov_b32 m0, s86
	s_nop 0
	global_load_lds_dwordx4 v[220:221], off
	s_waitcnt lgkmcnt(8)
	s_setprio 1
	s_waitcnt lgkmcnt(0)
	s_barrier
	v_mfma_f32_16x16x32_bf16 v[124:127], v[128:131], v[156:159], v[124:127]
	v_mfma_f32_16x16x32_bf16 v[120:123], v[136:139], v[156:159], v[120:123]
	v_mfma_f32_16x16x32_bf16 v[108:111], v[128:131], v[164:167], v[108:111]
	v_mfma_f32_16x16x32_bf16 v[104:107], v[136:139], v[164:167], v[104:107]
	v_mfma_f32_16x16x32_bf16 v[92:95], v[128:131], v[192:195], v[92:95]
	v_mfma_f32_16x16x32_bf16 v[88:91], v[136:139], v[192:195], v[88:91]
	v_mfma_f32_16x16x32_bf16 v[76:79], v[128:131], v[200:203], v[76:79]
	v_mfma_f32_16x16x32_bf16 v[72:75], v[136:139], v[200:203], v[72:75]
	v_mfma_f32_16x16x32_bf16 v[124:127], v[132:135], v[160:163], v[124:127]
	v_mfma_f32_16x16x32_bf16 v[120:123], v[140:143], v[160:163], v[120:123]
	v_mfma_f32_16x16x32_bf16 v[108:111], v[132:135], v[188:191], v[108:111]
	v_mfma_f32_16x16x32_bf16 v[104:107], v[140:143], v[188:191], v[104:107]
	v_mfma_f32_16x16x32_bf16 v[92:95], v[132:135], v[196:199], v[92:95]
	v_mfma_f32_16x16x32_bf16 v[88:91], v[140:143], v[196:199], v[88:91]
	v_mfma_f32_16x16x32_bf16 v[76:79], v[132:135], v[204:207], v[76:79]
	v_mfma_f32_16x16x32_bf16 v[72:75], v[140:143], v[204:207], v[72:75]
	s_barrier
	s_setprio 0
	s_add_i32 s35, 0, 0x1c000
	s_add_i32 s27, s27, s81
	v_add_u32_e32 v144, s35, v216
	v_lshl_add_u64 v[168:169], v[168:169], 0, s[18:19]
	s_mov_b32 m0, s27
	ds_read_b128 v[220:223], v144
	ds_read_b128 v[228:231], v144 offset:1024
	ds_read_b128 v[232:235], v144 offset:2048
	ds_read_b128 v[236:239], v144 offset:3072
	global_load_lds_dwordx4 v[168:169], off
	v_lshl_add_u64 v[168:169], v[176:177], 0, s[18:19]
	s_add_i32 m0, s27, 0x2000
	s_nop 0
	global_load_lds_dwordx4 v[168:169], off
	s_setprio 1
	s_waitcnt lgkmcnt(0)
	s_barrier
	v_mfma_f32_16x16x32_bf16 v[116:119], v[220:223], v[156:159], v[116:119]
	v_mfma_f32_16x16x32_bf16 v[112:115], v[232:235], v[156:159], v[112:115]
	v_mfma_f32_16x16x32_bf16 v[100:103], v[220:223], v[164:167], v[100:103]
	v_mfma_f32_16x16x32_bf16 v[96:99], v[232:235], v[164:167], v[96:99]
	v_mfma_f32_16x16x32_bf16 v[84:87], v[220:223], v[192:195], v[84:87]
	v_mfma_f32_16x16x32_bf16 v[80:83], v[232:235], v[192:195], v[80:83]
	v_mfma_f32_16x16x32_bf16 v[68:71], v[220:223], v[200:203], v[68:71]
	v_mfma_f32_16x16x32_bf16 v[64:67], v[232:235], v[200:203], v[64:67]
	v_mfma_f32_16x16x32_bf16 v[116:119], v[228:231], v[160:163], v[116:119]
	v_mfma_f32_16x16x32_bf16 v[112:115], v[236:239], v[160:163], v[112:115]
	v_mfma_f32_16x16x32_bf16 v[100:103], v[228:231], v[188:191], v[100:103]
	v_mfma_f32_16x16x32_bf16 v[96:99], v[236:239], v[188:191], v[96:99]
	v_mfma_f32_16x16x32_bf16 v[84:87], v[228:231], v[196:199], v[84:87]
	v_mfma_f32_16x16x32_bf16 v[80:83], v[236:239], v[196:199], v[80:83]
	v_mfma_f32_16x16x32_bf16 v[68:71], v[228:231], v[204:207], v[68:71]
	v_mfma_f32_16x16x32_bf16 v[64:67], v[236:239], v[204:207], v[64:67]
	s_barrier
	s_setprio 0
	s_mov_b32 m0, s87
	v_lshl_add_u64 v[168:169], v[224:225], 0, s[18:19]
	ds_read_b128 v[156:159], v217 offset:49152
	ds_read_b128 v[160:163], v217 offset:50176
	ds_read_b128 v[164:167], v217 offset:51200
	ds_read_b128 v[188:191], v217 offset:52224
	ds_read_b128 v[192:195], v217 offset:53248
	ds_read_b128 v[196:199], v217 offset:54272
	ds_read_b128 v[200:203], v217 offset:55296
	ds_read_b128 v[204:207], v217 offset:56320
	global_load_lds_dwordx4 v[168:169], off
	v_lshl_add_u64 v[168:169], v[240:241], 0, s[18:19]
	s_mov_b32 m0, s79
	s_nop 0
	global_load_lds_dwordx4 v[168:169], off
	s_setprio 1
	s_waitcnt lgkmcnt(0)
	s_barrier
	v_mfma_f32_16x16x32_bf16 v[60:63], v[128:131], v[156:159], v[60:63]
	v_mfma_f32_16x16x32_bf16 v[56:59], v[136:139], v[156:159], v[56:59]
	v_mfma_f32_16x16x32_bf16 v[44:47], v[128:131], v[164:167], v[44:47]
	v_mfma_f32_16x16x32_bf16 v[40:43], v[136:139], v[164:167], v[40:43]
	v_mfma_f32_16x16x32_bf16 v[28:31], v[128:131], v[192:195], v[28:31]
	v_mfma_f32_16x16x32_bf16 v[24:27], v[136:139], v[192:195], v[24:27]
	v_mfma_f32_16x16x32_bf16 v[12:15], v[128:131], v[200:203], v[12:15]
	v_mfma_f32_16x16x32_bf16 v[8:11], v[136:139], v[200:203], v[8:11]
	v_mfma_f32_16x16x32_bf16 v[60:63], v[132:135], v[160:163], v[60:63]
	v_mfma_f32_16x16x32_bf16 v[56:59], v[140:143], v[160:163], v[56:59]
	v_mfma_f32_16x16x32_bf16 v[44:47], v[132:135], v[188:191], v[44:47]
	v_mfma_f32_16x16x32_bf16 v[40:43], v[140:143], v[188:191], v[40:43]
	v_mfma_f32_16x16x32_bf16 v[28:31], v[132:135], v[196:199], v[28:31]
	v_mfma_f32_16x16x32_bf16 v[24:27], v[140:143], v[196:199], v[24:27]
	v_mfma_f32_16x16x32_bf16 v[12:15], v[132:135], v[204:207], v[12:15]
	v_mfma_f32_16x16x32_bf16 v[8:11], v[140:143], v[204:207], v[8:11]
	s_barrier
	s_setprio 0
	s_add_u32 s36, s72, 0x40080
	s_addc_u32 s37, s73, 0
	s_add_i32 s27, s35, s81
	v_lshl_add_u64 v[128:129], s[36:37], 0, v[148:149]
	s_mov_b32 m0, s27
	s_nop 0
	global_load_lds_dwordx4 v[128:129], off
	v_lshl_add_u64 v[128:129], s[36:37], 0, v[146:147]
	s_add_i32 m0, s27, 0x2000
	s_nop 0
	global_load_lds_dwordx4 v[128:129], off
	s_waitcnt vmcnt(6)
	s_setprio 1
	s_barrier
	v_mfma_f32_16x16x32_bf16 v[52:55], v[220:223], v[156:159], v[52:55]
	v_mfma_f32_16x16x32_bf16 v[48:51], v[232:235], v[156:159], v[48:51]
	v_mfma_f32_16x16x32_bf16 v[36:39], v[220:223], v[164:167], v[36:39]
	v_mfma_f32_16x16x32_bf16 v[32:35], v[232:235], v[164:167], v[32:35]
	v_mfma_f32_16x16x32_bf16 v[20:23], v[220:223], v[192:195], v[20:23]
	v_mfma_f32_16x16x32_bf16 v[16:19], v[232:235], v[192:195], v[16:19]
	v_mfma_f32_16x16x32_bf16 v[4:7], v[220:223], v[200:203], v[4:7]
	v_mfma_f32_16x16x32_bf16 v[0:3], v[232:235], v[200:203], v[0:3]
	v_mfma_f32_16x16x32_bf16 v[52:55], v[228:231], v[160:163], v[52:55]
	v_mfma_f32_16x16x32_bf16 v[48:51], v[236:239], v[160:163], v[48:51]
	v_mfma_f32_16x16x32_bf16 v[36:39], v[228:231], v[188:191], v[36:39]
	v_mfma_f32_16x16x32_bf16 v[32:35], v[236:239], v[188:191], v[32:35]
	v_mfma_f32_16x16x32_bf16 v[20:23], v[228:231], v[196:199], v[20:23]
	v_mfma_f32_16x16x32_bf16 v[16:19], v[236:239], v[196:199], v[16:19]
	v_mfma_f32_16x16x32_bf16 v[4:7], v[228:231], v[204:207], v[4:7]
	v_mfma_f32_16x16x32_bf16 v[0:3], v[236:239], v[204:207], v[0:3]
	s_barrier
	s_setprio 0
	s_add_i32 s34, s34, 2
	s_add_u32 s52, s52, 0x100
	s_addc_u32 s53, s53, 0
	s_add_u32 s31, s31, 0x100
	s_addc_u32 s33, s33, 0
	s_cmp_gt_u32 s34, 13
.LBB0_326:
	s_add_u32 s27, s52, 0xfffc0080
	s_addc_u32 s35, s53, -1
	s_add_i32 s36, 0, 0x10000
	v_add_u32_e32 v140, s36, v216
	ds_read_b128 v[128:131], v140
	ds_read_b128 v[132:135], v140 offset:1024
	ds_read_b128 v[136:139], v140 offset:2048
	ds_read_b128 v[140:143], v140 offset:3072
	s_cmp_eq_u32 s34, 12
	s_cselect_b32 s75, s1, s35
	s_cselect_b32 s74, s11, s27
	s_cselect_b32 s73, s25, s33
	s_cselect_b32 s72, s30, s31
	v_lshl_add_u64 v[168:169], s[52:53], 0, v[152:153]
	s_add_i32 m0, s83, 0xc000
	ds_read_b128 v[156:159], v217
	ds_read_b128 v[160:163], v217 offset:1024
	ds_read_b128 v[164:167], v217 offset:2048
	ds_read_b128 v[188:191], v217 offset:3072
	ds_read_b128 v[192:195], v217 offset:4096
	ds_read_b128 v[196:199], v217 offset:5120
	ds_read_b128 v[200:203], v217 offset:6144
	ds_read_b128 v[204:207], v217 offset:7168
	global_load_lds_dwordx4 v[168:169], off
	v_lshl_add_u64 v[168:169], s[52:53], 0, v[154:155]
	s_add_i32 m0, s83, 0xe000
	s_nop 0
	global_load_lds_dwordx4 v[168:169], off
	s_waitcnt lgkmcnt(8)
	s_setprio 1
	s_waitcnt lgkmcnt(0)
	s_barrier
	v_mfma_f32_16x16x32_bf16 v[124:127], v[128:131], v[156:159], v[124:127]
	v_mfma_f32_16x16x32_bf16 v[120:123], v[136:139], v[156:159], v[120:123]
	v_mfma_f32_16x16x32_bf16 v[108:111], v[128:131], v[164:167], v[108:111]
	v_mfma_f32_16x16x32_bf16 v[104:107], v[136:139], v[164:167], v[104:107]
	v_mfma_f32_16x16x32_bf16 v[92:95], v[128:131], v[192:195], v[92:95]
	v_mfma_f32_16x16x32_bf16 v[88:91], v[136:139], v[192:195], v[88:91]
	v_mfma_f32_16x16x32_bf16 v[76:79], v[128:131], v[200:203], v[76:79]
	v_mfma_f32_16x16x32_bf16 v[72:75], v[136:139], v[200:203], v[72:75]
	v_mfma_f32_16x16x32_bf16 v[124:127], v[132:135], v[160:163], v[124:127]
	v_mfma_f32_16x16x32_bf16 v[120:123], v[140:143], v[160:163], v[120:123]
	v_mfma_f32_16x16x32_bf16 v[108:111], v[132:135], v[188:191], v[108:111]
	v_mfma_f32_16x16x32_bf16 v[104:107], v[140:143], v[188:191], v[104:107]
	v_mfma_f32_16x16x32_bf16 v[92:95], v[132:135], v[196:199], v[92:95]
	v_mfma_f32_16x16x32_bf16 v[88:91], v[140:143], v[196:199], v[88:91]
	v_mfma_f32_16x16x32_bf16 v[76:79], v[132:135], v[204:207], v[76:79]
	v_mfma_f32_16x16x32_bf16 v[72:75], v[140:143], v[204:207], v[72:75]
	s_barrier
	s_setprio 0
	s_add_i32 s27, 0, 0x14000
	s_add_i32 s35, s36, s81
	v_add_u32_e32 v144, s27, v216
	v_lshl_add_u64 v[168:169], s[72:73], 0, v[148:149]
	s_mov_b32 m0, s35
	ds_read_b128 v[220:223], v144
	ds_read_b128 v[228:231], v144 offset:1024
	ds_read_b128 v[232:235], v144 offset:2048
	ds_read_b128 v[236:239], v144 offset:3072
	global_load_lds_dwordx4 v[168:169], off
	v_lshl_add_u64 v[176:177], s[72:73], 0, v[146:147]
	s_add_i32 m0, s35, 0x2000
	s_nop 0
	global_load_lds_dwordx4 v[176:177], off
	s_setprio 1
	s_waitcnt lgkmcnt(0)
	s_barrier
	v_mfma_f32_16x16x32_bf16 v[116:119], v[220:223], v[156:159], v[116:119]
	v_mfma_f32_16x16x32_bf16 v[112:115], v[232:235], v[156:159], v[112:115]
	v_mfma_f32_16x16x32_bf16 v[100:103], v[220:223], v[164:167], v[100:103]
	v_mfma_f32_16x16x32_bf16 v[96:99], v[232:235], v[164:167], v[96:99]
	v_mfma_f32_16x16x32_bf16 v[84:87], v[220:223], v[192:195], v[84:87]
	v_mfma_f32_16x16x32_bf16 v[80:83], v[232:235], v[192:195], v[80:83]
	v_mfma_f32_16x16x32_bf16 v[68:71], v[220:223], v[200:203], v[68:71]
	v_mfma_f32_16x16x32_bf16 v[64:67], v[232:235], v[200:203], v[64:67]
	v_mfma_f32_16x16x32_bf16 v[116:119], v[228:231], v[160:163], v[116:119]
	v_mfma_f32_16x16x32_bf16 v[112:115], v[236:239], v[160:163], v[112:115]
	v_mfma_f32_16x16x32_bf16 v[100:103], v[228:231], v[188:191], v[100:103]
	v_mfma_f32_16x16x32_bf16 v[96:99], v[236:239], v[188:191], v[96:99]
	v_mfma_f32_16x16x32_bf16 v[84:87], v[228:231], v[196:199], v[84:87]
	v_mfma_f32_16x16x32_bf16 v[80:83], v[236:239], v[196:199], v[80:83]
	v_mfma_f32_16x16x32_bf16 v[68:71], v[228:231], v[204:207], v[68:71]
	v_mfma_f32_16x16x32_bf16 v[64:67], v[236:239], v[204:207], v[64:67]
	s_barrier
	s_setprio 0
	s_mov_b32 m0, s83
	v_lshl_add_u64 v[224:225], s[74:75], 0, v[148:149]
	ds_read_b128 v[156:159], v217 offset:16384
	ds_read_b128 v[160:163], v217 offset:17408
	ds_read_b128 v[164:167], v217 offset:18432
	ds_read_b128 v[188:191], v217 offset:19456
	ds_read_b128 v[192:195], v217 offset:20480
	ds_read_b128 v[196:199], v217 offset:21504
	ds_read_b128 v[200:203], v217 offset:22528
	ds_read_b128 v[204:207], v217 offset:23552
	global_load_lds_dwordx4 v[224:225], off
	v_lshl_add_u64 v[240:241], s[74:75], 0, v[146:147]
	s_mov_b32 m0, s84
	s_nop 0
	global_load_lds_dwordx4 v[240:241], off
	s_setprio 1
	s_waitcnt lgkmcnt(0)
	s_barrier
	v_mfma_f32_16x16x32_bf16 v[60:63], v[128:131], v[156:159], v[60:63]
	v_mfma_f32_16x16x32_bf16 v[56:59], v[136:139], v[156:159], v[56:59]
	v_mfma_f32_16x16x32_bf16 v[44:47], v[128:131], v[164:167], v[44:47]
	v_mfma_f32_16x16x32_bf16 v[40:43], v[136:139], v[164:167], v[40:43]
	v_mfma_f32_16x16x32_bf16 v[28:31], v[128:131], v[192:195], v[28:31]
	v_mfma_f32_16x16x32_bf16 v[24:27], v[136:139], v[192:195], v[24:27]
	v_mfma_f32_16x16x32_bf16 v[12:15], v[128:131], v[200:203], v[12:15]
	v_mfma_f32_16x16x32_bf16 v[8:11], v[136:139], v[200:203], v[8:11]
	v_mfma_f32_16x16x32_bf16 v[60:63], v[132:135], v[160:163], v[60:63]
	v_mfma_f32_16x16x32_bf16 v[56:59], v[140:143], v[160:163], v[56:59]
	v_mfma_f32_16x16x32_bf16 v[44:47], v[132:135], v[188:191], v[44:47]
	v_mfma_f32_16x16x32_bf16 v[40:43], v[140:143], v[188:191], v[40:43]
	v_mfma_f32_16x16x32_bf16 v[28:31], v[132:135], v[196:199], v[28:31]
	v_mfma_f32_16x16x32_bf16 v[24:27], v[140:143], v[196:199], v[24:27]
	v_mfma_f32_16x16x32_bf16 v[12:15], v[132:135], v[204:207], v[12:15]
	v_mfma_f32_16x16x32_bf16 v[8:11], v[140:143], v[204:207], v[8:11]
	s_barrier
	s_setprio 0
	s_add_u32 s36, s72, 0x40000
	s_addc_u32 s37, s73, 0
	s_add_i32 s27, s27, s81
	v_lshl_add_u64 v[128:129], s[36:37], 0, v[148:149]
	s_mov_b32 m0, s27
	s_nop 0
	global_load_lds_dwordx4 v[128:129], off
	v_lshl_add_u64 v[128:129], s[36:37], 0, v[146:147]
	s_add_i32 m0, s27, 0x2000
	s_nop 0
	global_load_lds_dwordx4 v[128:129], off
	s_waitcnt vmcnt(6)
	s_setprio 1
	s_barrier
	v_mfma_f32_16x16x32_bf16 v[52:55], v[220:223], v[156:159], v[52:55]
	v_mfma_f32_16x16x32_bf16 v[48:51], v[232:235], v[156:159], v[48:51]
	v_mfma_f32_16x16x32_bf16 v[36:39], v[220:223], v[164:167], v[36:39]
	v_mfma_f32_16x16x32_bf16 v[32:35], v[232:235], v[164:167], v[32:35]
	v_mfma_f32_16x16x32_bf16 v[20:23], v[220:223], v[192:195], v[20:23]
	v_mfma_f32_16x16x32_bf16 v[16:19], v[232:235], v[192:195], v[16:19]
	v_mfma_f32_16x16x32_bf16 v[4:7], v[220:223], v[200:203], v[4:7]
	v_mfma_f32_16x16x32_bf16 v[0:3], v[232:235], v[200:203], v[0:3]
	v_mfma_f32_16x16x32_bf16 v[52:55], v[228:231], v[160:163], v[52:55]
	v_mfma_f32_16x16x32_bf16 v[48:51], v[236:239], v[160:163], v[48:51]
	v_mfma_f32_16x16x32_bf16 v[36:39], v[228:231], v[188:191], v[36:39]
	v_mfma_f32_16x16x32_bf16 v[32:35], v[236:239], v[188:191], v[32:35]
	v_mfma_f32_16x16x32_bf16 v[20:23], v[228:231], v[196:199], v[20:23]
	v_mfma_f32_16x16x32_bf16 v[16:19], v[236:239], v[196:199], v[16:19]
	v_mfma_f32_16x16x32_bf16 v[4:7], v[228:231], v[204:207], v[4:7]
	v_mfma_f32_16x16x32_bf16 v[0:3], v[236:239], v[204:207], v[0:3]
	s_barrier
	s_setprio 0
	s_add_i32 s27, 0, 0x18000
	v_add_u32_e32 v140, s27, v216
	ds_read_b128 v[128:131], v140
	ds_read_b128 v[132:135], v140 offset:1024
	ds_read_b128 v[136:139], v140 offset:2048
	ds_read_b128 v[140:143], v140 offset:3072
	s_add_u32 s36, s74, 0x40000
	s_addc_u32 s37, s75, 0
	s_mov_b32 m0, s85
	v_lshl_add_u64 v[220:221], s[36:37], 0, v[148:149]
	ds_read_b128 v[156:159], v217 offset:32768
	ds_read_b128 v[160:163], v217 offset:33792
	ds_read_b128 v[164:167], v217 offset:34816
	ds_read_b128 v[188:191], v217 offset:35840
	ds_read_b128 v[192:195], v217 offset:36864
	ds_read_b128 v[196:199], v217 offset:37888
	ds_read_b128 v[200:203], v217 offset:38912
	ds_read_b128 v[204:207], v217 offset:39936
	global_load_lds_dwordx4 v[220:221], off
	v_lshl_add_u64 v[220:221], s[36:37], 0, v[146:147]
	s_mov_b32 m0, s86
	s_nop 0
	global_load_lds_dwordx4 v[220:221], off
	s_waitcnt lgkmcnt(8)
	s_setprio 1
	s_waitcnt lgkmcnt(0)
	s_barrier
	v_mfma_f32_16x16x32_bf16 v[124:127], v[128:131], v[156:159], v[124:127]
	v_mfma_f32_16x16x32_bf16 v[120:123], v[136:139], v[156:159], v[120:123]
	v_mfma_f32_16x16x32_bf16 v[108:111], v[128:131], v[164:167], v[108:111]
	v_mfma_f32_16x16x32_bf16 v[104:107], v[136:139], v[164:167], v[104:107]
	v_mfma_f32_16x16x32_bf16 v[92:95], v[128:131], v[192:195], v[92:95]
	v_mfma_f32_16x16x32_bf16 v[88:91], v[136:139], v[192:195], v[88:91]
	v_mfma_f32_16x16x32_bf16 v[76:79], v[128:131], v[200:203], v[76:79]
	v_mfma_f32_16x16x32_bf16 v[72:75], v[136:139], v[200:203], v[72:75]
	v_mfma_f32_16x16x32_bf16 v[124:127], v[132:135], v[160:163], v[124:127]
	v_mfma_f32_16x16x32_bf16 v[120:123], v[140:143], v[160:163], v[120:123]
	v_mfma_f32_16x16x32_bf16 v[108:111], v[132:135], v[188:191], v[108:111]
	v_mfma_f32_16x16x32_bf16 v[104:107], v[140:143], v[188:191], v[104:107]
	v_mfma_f32_16x16x32_bf16 v[92:95], v[132:135], v[196:199], v[92:95]
	v_mfma_f32_16x16x32_bf16 v[88:91], v[140:143], v[196:199], v[88:91]
	v_mfma_f32_16x16x32_bf16 v[76:79], v[132:135], v[204:207], v[76:79]
	v_mfma_f32_16x16x32_bf16 v[72:75], v[140:143], v[204:207], v[72:75]
	s_barrier
	s_setprio 0
	s_add_i32 s35, 0, 0x1c000
	s_add_i32 s27, s27, s81
	v_add_u32_e32 v144, s35, v216
	v_lshl_add_u64 v[168:169], v[168:169], 0, s[18:19]
	s_mov_b32 m0, s27
	ds_read_b128 v[220:223], v144
	ds_read_b128 v[228:231], v144 offset:1024
	ds_read_b128 v[232:235], v144 offset:2048
	ds_read_b128 v[236:239], v144 offset:3072
	global_load_lds_dwordx4 v[168:169], off
	v_lshl_add_u64 v[168:169], v[176:177], 0, s[18:19]
	s_add_i32 m0, s27, 0x2000
	s_nop 0
	global_load_lds_dwordx4 v[168:169], off
	s_setprio 1
	s_waitcnt lgkmcnt(0)
	s_barrier
	v_mfma_f32_16x16x32_bf16 v[116:119], v[220:223], v[156:159], v[116:119]
	v_mfma_f32_16x16x32_bf16 v[112:115], v[232:235], v[156:159], v[112:115]
	v_mfma_f32_16x16x32_bf16 v[100:103], v[220:223], v[164:167], v[100:103]
	v_mfma_f32_16x16x32_bf16 v[96:99], v[232:235], v[164:167], v[96:99]
	v_mfma_f32_16x16x32_bf16 v[84:87], v[220:223], v[192:195], v[84:87]
	v_mfma_f32_16x16x32_bf16 v[80:83], v[232:235], v[192:195], v[80:83]
	v_mfma_f32_16x16x32_bf16 v[68:71], v[220:223], v[200:203], v[68:71]
	v_mfma_f32_16x16x32_bf16 v[64:67], v[232:235], v[200:203], v[64:67]
	v_mfma_f32_16x16x32_bf16 v[116:119], v[228:231], v[160:163], v[116:119]
	v_mfma_f32_16x16x32_bf16 v[112:115], v[236:239], v[160:163], v[112:115]
	v_mfma_f32_16x16x32_bf16 v[100:103], v[228:231], v[188:191], v[100:103]
	v_mfma_f32_16x16x32_bf16 v[96:99], v[236:239], v[188:191], v[96:99]
	v_mfma_f32_16x16x32_bf16 v[84:87], v[228:231], v[196:199], v[84:87]
	v_mfma_f32_16x16x32_bf16 v[80:83], v[236:239], v[196:199], v[80:83]
	v_mfma_f32_16x16x32_bf16 v[68:71], v[228:231], v[204:207], v[68:71]
	v_mfma_f32_16x16x32_bf16 v[64:67], v[236:239], v[204:207], v[64:67]
	s_barrier
	s_setprio 0
	s_mov_b32 m0, s87
	v_lshl_add_u64 v[168:169], v[224:225], 0, s[18:19]
	ds_read_b128 v[156:159], v217 offset:49152
	ds_read_b128 v[160:163], v217 offset:50176
	ds_read_b128 v[164:167], v217 offset:51200
	ds_read_b128 v[188:191], v217 offset:52224
	ds_read_b128 v[192:195], v217 offset:53248
	ds_read_b128 v[196:199], v217 offset:54272
	ds_read_b128 v[200:203], v217 offset:55296
	ds_read_b128 v[204:207], v217 offset:56320
	global_load_lds_dwordx4 v[168:169], off
	v_lshl_add_u64 v[168:169], v[240:241], 0, s[18:19]
	s_mov_b32 m0, s79
	s_nop 0
	global_load_lds_dwordx4 v[168:169], off
	s_setprio 1
	s_waitcnt lgkmcnt(0)
	s_barrier
	v_mfma_f32_16x16x32_bf16 v[60:63], v[128:131], v[156:159], v[60:63]
	v_mfma_f32_16x16x32_bf16 v[56:59], v[136:139], v[156:159], v[56:59]
	v_mfma_f32_16x16x32_bf16 v[44:47], v[128:131], v[164:167], v[44:47]
	v_mfma_f32_16x16x32_bf16 v[40:43], v[136:139], v[164:167], v[40:43]
	v_mfma_f32_16x16x32_bf16 v[28:31], v[128:131], v[192:195], v[28:31]
	v_mfma_f32_16x16x32_bf16 v[24:27], v[136:139], v[192:195], v[24:27]
	v_mfma_f32_16x16x32_bf16 v[12:15], v[128:131], v[200:203], v[12:15]
	v_mfma_f32_16x16x32_bf16 v[8:11], v[136:139], v[200:203], v[8:11]
	v_mfma_f32_16x16x32_bf16 v[60:63], v[132:135], v[160:163], v[60:63]
	v_mfma_f32_16x16x32_bf16 v[56:59], v[140:143], v[160:163], v[56:59]
	v_mfma_f32_16x16x32_bf16 v[44:47], v[132:135], v[188:191], v[44:47]
	v_mfma_f32_16x16x32_bf16 v[40:43], v[140:143], v[188:191], v[40:43]
	v_mfma_f32_16x16x32_bf16 v[28:31], v[132:135], v[196:199], v[28:31]
	v_mfma_f32_16x16x32_bf16 v[24:27], v[140:143], v[196:199], v[24:27]
	v_mfma_f32_16x16x32_bf16 v[12:15], v[132:135], v[204:207], v[12:15]
	v_mfma_f32_16x16x32_bf16 v[8:11], v[140:143], v[204:207], v[8:11]
	s_barrier
	s_setprio 0
	s_add_u32 s36, s72, 0x40080
	s_addc_u32 s37, s73, 0
	s_add_i32 s27, s35, s81
	v_lshl_add_u64 v[128:129], s[36:37], 0, v[148:149]
	s_mov_b32 m0, s27
	s_nop 0
	global_load_lds_dwordx4 v[128:129], off
	v_lshl_add_u64 v[128:129], s[36:37], 0, v[146:147]
	s_add_i32 m0, s27, 0x2000
	s_nop 0
	global_load_lds_dwordx4 v[128:129], off
	s_waitcnt vmcnt(6)
	s_setprio 1
	s_barrier
	v_mfma_f32_16x16x32_bf16 v[52:55], v[220:223], v[156:159], v[52:55]
	v_mfma_f32_16x16x32_bf16 v[48:51], v[232:235], v[156:159], v[48:51]
	v_mfma_f32_16x16x32_bf16 v[36:39], v[220:223], v[164:167], v[36:39]
	v_mfma_f32_16x16x32_bf16 v[32:35], v[232:235], v[164:167], v[32:35]
	v_mfma_f32_16x16x32_bf16 v[20:23], v[220:223], v[192:195], v[20:23]
	v_mfma_f32_16x16x32_bf16 v[16:19], v[232:235], v[192:195], v[16:19]
	v_mfma_f32_16x16x32_bf16 v[4:7], v[220:223], v[200:203], v[4:7]
	v_mfma_f32_16x16x32_bf16 v[0:3], v[232:235], v[200:203], v[0:3]
	v_mfma_f32_16x16x32_bf16 v[52:55], v[228:231], v[160:163], v[52:55]
	v_mfma_f32_16x16x32_bf16 v[48:51], v[236:239], v[160:163], v[48:51]
	v_mfma_f32_16x16x32_bf16 v[36:39], v[228:231], v[188:191], v[36:39]
	v_mfma_f32_16x16x32_bf16 v[32:35], v[236:239], v[188:191], v[32:35]
	v_mfma_f32_16x16x32_bf16 v[20:23], v[228:231], v[196:199], v[20:23]
	v_mfma_f32_16x16x32_bf16 v[16:19], v[236:239], v[196:199], v[16:19]
	v_mfma_f32_16x16x32_bf16 v[4:7], v[228:231], v[204:207], v[4:7]
	v_mfma_f32_16x16x32_bf16 v[0:3], v[236:239], v[204:207], v[0:3]
	s_barrier
	s_setprio 0
	s_add_i32 s34, s34, 2
	s_add_u32 s52, s52, 0x100
	s_addc_u32 s53, s53, 0
	s_add_u32 s31, s31, 0x100
	s_addc_u32 s33, s33, 0
	s_cmp_gt_u32 s34, 13
	s_cbranch_scc0 .LBB0_326
	v_lshl_add_u32 v128, s0, 8, v151
	v_readlane_b32 s0, v252, 36
	v_ashrrev_i32_e32 v129, 31, v128
	v_readlane_b32 s1, v252, 37
	v_or_b32_e32 v132, 16, v128
	v_or_b32_e32 v136, 32, v128
	v_lshl_add_u64 v[130:131], v[128:129], 3, s[0:1]
	v_ashrrev_i32_e32 v133, 31, v132
	v_ashrrev_i32_e32 v137, 31, v136
	v_or_b32_e32 v140, 48, v128
	v_lshl_add_u64 v[134:135], v[132:133], 3, s[0:1]
	v_lshl_add_u64 v[138:139], v[136:137], 3, s[0:1]
	v_ashrrev_i32_e32 v141, 31, v140
	global_load_dwordx2 v[202:203], v[130:131], off
	global_load_dwordx2 v[200:201], v[134:135], off
	global_load_dwordx2 v[192:193], v[138:139], off
	global_load_dwordx2 v[166:167], v[130:131], off offset:1024
	v_add_u32_e32 v164, 0x90, v128
	v_add_u32_e32 v158, 0xa0, v128
	v_add_u32_e32 v156, 0xb0, v128
	v_lshl_add_u64 v[142:143], v[140:141], 3, s[0:1]
	v_ashrrev_i32_e32 v165, 31, v164
	v_ashrrev_i32_e32 v159, 31, v158
	v_ashrrev_i32_e32 v157, 31, v156
	v_lshl_add_u64 v[130:131], v[164:165], 3, s[0:1]
	v_lshl_add_u64 v[134:135], v[158:159], 3, s[0:1]
	v_lshl_add_u64 v[138:139], v[156:157], 3, s[0:1]
	global_load_dwordx2 v[196:197], v[142:143], off
	global_load_dwordx2 v[188:189], v[130:131], off
	global_load_dwordx2 v[162:163], v[134:135], off
	global_load_dwordx2 v[160:161], v[138:139], off
	v_add_u32_e32 v168, 0x80, v128
	s_mov_b64 s[0:1], -1
	s_cmp_gt_u32 s10, 1
	v_lshlrev_b32_e32 v144, 1, v150
	v_ashrrev_i32_e32 v169, 31, v168
	v_lshlrev_b64 v[204:205], 10, v[128:129]
	v_lshlrev_b64 v[198:199], 10, v[132:133]
	v_lshlrev_b64 v[194:195], 10, v[136:137]
	v_lshlrev_b64 v[190:191], 10, v[140:141]
	s_waitcnt vmcnt(0)
	v_ffbh_u32_e32 v222, v203
	v_ffbh_u32_e32 v221, v201
	v_ffbh_u32_e32 v220, v193
	v_ffbh_u32_e32 v219, v197
	s_cbranch_scc0 .LBB0_329
	s_cmp_lt_u32 s10, 4
	s_cselect_b64 vcc, -1, 0
	v_readlane_b32 s56, v254, 23
	s_and_b64 s[0:1], vcc, exec
	v_readlane_b32 s70, v254, 37
	v_readlane_b32 s36, v252, 15
	v_readlane_b32 s71, v254, 38
	v_readlane_b32 s37, v252, 16
	s_cselect_b32 s0, s70, s36
	s_mov_b32 s11, 0x4400000
	v_readlane_b32 s30, v254, 62
	s_cselect_b32 s1, s71, s37
	s_cselect_b32 s11, s11, 0x4800000
	v_readlane_b32 s31, v254, 63
	s_add_u32 s0, s0, s30
	s_addc_u32 s1, s1, s31
	global_load_dwordx4 v[136:139], v218, s[0:1] offset:16
	global_load_dwordx4 v[140:143], v218, s[0:1]
	global_load_dwordx4 v[128:131], v218, s[0:1] offset:144
	global_load_dwordx4 v[132:135], v218, s[0:1] offset:128
	v_and_b32_e32 v177, 64, v214
	v_xor_b32_e32 v176, 16, v214
	v_add_u32_e32 v177, 64, v177
	v_cndmask_b32_e32 v223, 1.0, v215, vcc
	v_cmp_lt_i32_e32 vcc, v176, v177
	v_readlane_b32 s9, v254, 52
	s_add_u32 s11, s9, s11
	v_cndmask_b32_e32 v176, v214, v176, vcc
	v_lshlrev_b32_e32 v225, 2, v176
	v_xor_b32_e32 v176, 32, v214
	v_cmp_lt_i32_e32 vcc, v176, v177
	v_readlane_b32 s9, v254, 61
	s_addc_u32 s25, s9, 0
	v_cndmask_b32_e32 v176, v214, v176, vcc
	v_lshlrev_b32_e32 v224, 2, v176
	v_min_u32_e32 v176, 32, v222
	v_lshlrev_b64 v[228:229], v176, v[202:203]
	v_min_u32_e32 v177, 1, v228
	v_or_b32_e32 v177, v229, v177
	v_cvt_f32_u32_e32 v177, v177
	v_sub_u32_e32 v176, 32, v176
	s_lshl_b32 s0, s10, 9
	s_and_b32 s0, s0, 0x200
	v_ldexp_f32 v176, v177, v176
	v_mul_f32_e32 v176, 0x35800000, v176
	v_fmamk_f32 v176, v176, 0x3a800000, v210
	s_add_u32 s0, s11, s0
	v_rsq_f32_e32 v176, v176
	s_addc_u32 s1, s25, 0
	v_lshl_add_u64 v[206:207], s[0:1], 0, v[144:145]
	v_readlane_b32 s48, v252, 27
	v_mov_b32_e32 v228, v176
	v_pk_mul_f32 v[230:231], v[124:125], v[228:229] op_sel_hi:[1,0]
	v_pk_mul_f32 v[232:233], v[126:127], v[228:229] op_sel_hi:[1,0]
	v_pk_mul_f32 v[236:237], v[230:231], v[230:231]
	v_pk_mul_f32 v[234:235], v[232:233], v[232:233]
	v_pk_mul_f32 v[250:251], v[114:115], v[228:229] op_sel_hi:[1,0]
	v_pk_mov_b32 v[238:239], v[236:237], v[234:235] op_sel:[1,0]
	v_mov_b32_e32 v237, v235
	v_pk_add_f32 v[234:235], v[238:239], v[236:237]
	v_pk_mul_f32 v[236:237], v[120:121], v[228:229] op_sel_hi:[1,0]
	v_pk_mul_f32 v[238:239], v[122:123], v[228:229] op_sel_hi:[1,0]
	v_pk_mul_f32 v[242:243], v[236:237], v[236:237]
	v_pk_mul_f32 v[240:241], v[238:239], v[238:239]
	v_pk_add_f32 v[234:235], v[234:235], v[234:235] op_sel_hi:[0,1]
	v_pk_mov_b32 v[244:245], v[242:243], v[240:241] op_sel:[1,0]
	v_mov_b32_e32 v243, v241
	v_pk_add_f32 v[240:241], v[244:245], v[242:243]
	v_pk_mul_f32 v[244:245], v[116:117], v[228:229] op_sel_hi:[1,0]
	v_pk_mul_f32 v[242:243], v[118:119], v[228:229] op_sel_hi:[1,0]
	v_mul_f32_e32 v234, v244, v244
	v_pk_fma_f32 v[246:247], v[244:245], v[244:245], v[234:235] op_sel_hi:[1,1,0]
	v_mul_f32_e32 v234, v242, v242
	v_pk_add_f32 v[240:241], v[240:241], v[240:241] op_sel_hi:[0,1]
	v_pk_fma_f32 v[248:249], v[242:243], v[242:243], v[234:235] op_sel_hi:[1,1,0]
	v_pk_mul_f32 v[176:177], v[112:113], v[228:229] op_sel_hi:[1,0]
	v_mul_f32_e32 v234, v250, v250
	v_mul_f32_e32 v246, v176, v176
	v_mul_f32_e32 v248, v177, v177
	v_mul_f32_e32 v240, v251, v251
	v_pk_add_f32 v[228:229], v[246:247], v[248:249]
	v_pk_add_f32 v[234:235], v[234:235], v[240:241]
	v_lshl_add_u64 v[240:241], v[206:207], 0, v[204:205]
	v_pk_add_f32 v[228:229], v[228:229], v[234:235]
	v_readlane_b32 s57, v254, 24
	v_add_f32_e32 v228, v228, v229
	ds_bpermute_b32 v229, v225, v228
	v_readlane_b32 s58, v254, 25
	v_readlane_b32 s59, v254, 26
	v_readlane_b32 s60, v254, 27
	v_readlane_b32 s61, v254, 28
	s_waitcnt lgkmcnt(0)
	v_add_f32_e32 v228, v228, v229
	ds_bpermute_b32 v229, v224, v228
	v_readlane_b32 s62, v254, 29
	v_readlane_b32 s63, v254, 30
	v_readlane_b32 s64, v254, 31
	v_readlane_b32 s65, v254, 32
	s_waitcnt lgkmcnt(0)
	v_add_f32_e32 v228, v228, v229
	v_fmamk_f32 v228, v228, 0x3c800000, v210
	v_readlane_b32 s66, v254, 33
	v_rsq_f32_e32 v228, v228
	v_readlane_b32 s67, v254, 34
	v_readlane_b32 s68, v254, 35
	v_readlane_b32 s69, v254, 36
	v_mul_f32_e32 v234, v223, v228
	v_pk_mul_f32 v[228:229], v[230:231], v[234:235] op_sel_hi:[1,0]
	v_pk_mul_f32 v[230:231], v[232:233], v[234:235] op_sel_hi:[1,0]
	s_waitcnt vmcnt(2)
	v_pk_mul_f32 v[228:229], v[140:141], v[228:229]
	v_pk_mul_f32 v[230:231], v[142:143], v[230:231]
	v_pk_mul_f32 v[232:233], v[236:237], v[234:235] op_sel_hi:[1,0]
	v_pk_mul_f32 v[236:237], v[238:239], v[234:235] op_sel_hi:[1,0]
	v_cvt_pk_bf16_f32 v228, v228, v229
	v_cvt_pk_bf16_f32 v229, v230, v231
	v_pk_mul_f32 v[232:233], v[136:137], v[232:233]
	v_pk_mul_f32 v[236:237], v[138:139], v[236:237]
	v_cvt_pk_bf16_f32 v230, v232, v233
	v_pk_mul_f32 v[176:177], v[176:177], v[234:235] op_sel_hi:[1,0]
	v_cvt_pk_bf16_f32 v231, v236, v237
	global_store_dwordx4 v[240:241], v[228:231], off
	v_pk_mul_f32 v[232:233], v[250:251], v[234:235] op_sel_hi:[1,0]
	s_waitcnt vmcnt(2)
	v_pk_mul_f32 v[176:177], v[128:129], v[176:177]
	v_pk_mul_f32 v[228:229], v[244:245], v[234:235] op_sel_hi:[1,0]
	v_pk_mul_f32 v[230:231], v[242:243], v[234:235] op_sel_hi:[1,0]
	s_waitcnt vmcnt(1)
	v_pk_mul_f32 v[228:229], v[132:133], v[228:229]
	v_pk_mul_f32 v[230:231], v[134:135], v[230:231]
	v_cvt_pk_bf16_f32 v228, v228, v229
	v_pk_mul_f32 v[232:233], v[130:131], v[232:233]
	v_cvt_pk_bf16_f32 v229, v230, v231
	v_cvt_pk_bf16_f32 v230, v176, v177
	s_nop 1
	v_readlane_b32 s38, v252, 17
	v_cvt_pk_bf16_f32 v231, v232, v233
	s_nop 1
	global_store_dwordx4 v[240:241], v[228:231], off offset:64
	v_readlane_b32 s39, v252, 18
	v_readlane_b32 s40, v252, 19
	v_min_u32_e32 v228, 32, v221
	v_lshlrev_b64 v[176:177], v228, v[200:201]
	v_min_u32_e32 v176, 1, v176
	v_or_b32_e32 v176, v177, v176
	v_cvt_f32_u32_e32 v176, v176
	v_sub_u32_e32 v177, 32, v228
	v_readlane_b32 s41, v252, 20
	v_readlane_b32 s42, v252, 21
	v_ldexp_f32 v176, v176, v177
	v_mul_f32_e32 v176, 0x35800000, v176
	v_fmamk_f32 v176, v176, 0x3a800000, v210
	v_readlane_b32 s43, v252, 22
	v_rsq_f32_e32 v176, v176
	v_readlane_b32 s44, v252, 23
	v_readlane_b32 s45, v252, 24
	v_readlane_b32 s46, v252, 25
	v_pk_mul_f32 v[228:229], v[108:109], v[176:177] op_sel_hi:[1,0]
	v_pk_mul_f32 v[230:231], v[110:111], v[176:177] op_sel_hi:[1,0]
	v_pk_mul_f32 v[234:235], v[228:229], v[228:229]
	v_pk_mul_f32 v[232:233], v[230:231], v[230:231]
	v_pk_mul_f32 v[248:249], v[98:99], v[176:177] op_sel_hi:[1,0]
	v_pk_mov_b32 v[236:237], v[234:235], v[232:233] op_sel:[1,0]
	v_mov_b32_e32 v235, v233
	v_pk_add_f32 v[232:233], v[236:237], v[234:235]
	v_pk_mul_f32 v[234:235], v[104:105], v[176:177] op_sel_hi:[1,0]
	v_pk_mul_f32 v[236:237], v[106:107], v[176:177] op_sel_hi:[1,0]
	v_pk_mul_f32 v[240:241], v[234:235], v[234:235]
	v_pk_mul_f32 v[238:239], v[236:237], v[236:237]
	v_pk_add_f32 v[232:233], v[232:233], v[232:233] op_sel_hi:[0,1]
	v_pk_mov_b32 v[242:243], v[240:241], v[238:239] op_sel:[1,0]
	v_mov_b32_e32 v241, v239
	v_pk_add_f32 v[238:239], v[242:243], v[240:241]
	v_pk_mul_f32 v[242:243], v[100:101], v[176:177] op_sel_hi:[1,0]
	v_pk_mul_f32 v[240:241], v[102:103], v[176:177] op_sel_hi:[1,0]
	v_mul_f32_e32 v232, v242, v242
	v_pk_fma_f32 v[244:245], v[242:243], v[242:243], v[232:233] op_sel_hi:[1,1,0]
	v_mul_f32_e32 v232, v240, v240
	v_pk_add_f32 v[238:239], v[238:239], v[238:239] op_sel_hi:[0,1]
	v_pk_fma_f32 v[246:247], v[240:241], v[240:241], v[232:233] op_sel_hi:[1,1,0]
	v_pk_mul_f32 v[176:177], v[96:97], v[176:177] op_sel_hi:[1,0]
	v_mul_f32_e32 v232, v248, v248
	v_mul_f32_e32 v244, v176, v176
	v_mul_f32_e32 v246, v177, v177
	v_mul_f32_e32 v238, v249, v249
	v_pk_add_f32 v[244:245], v[244:245], v[246:247]
	v_pk_add_f32 v[232:233], v[232:233], v[238:239]
	v_lshl_add_u64 v[238:239], v[206:207], 0, v[198:199]
	v_pk_add_f32 v[232:233], v[244:245], v[232:233]
	v_readlane_b32 s47, v252, 26
	v_add_f32_e32 v232, v232, v233
	ds_bpermute_b32 v233, v225, v232
	v_readlane_b32 s49, v252, 28
	v_readlane_b32 s50, v252, 29
	v_readlane_b32 s51, v252, 30
	v_readlane_b32 s48, v252, 40
	s_waitcnt lgkmcnt(0)
	v_add_f32_e32 v232, v232, v233
	ds_bpermute_b32 v233, v224, v232
	s_mov_b64 s[0:1], 0
	s_waitcnt lgkmcnt(0)
	v_add_f32_e32 v232, v232, v233
	v_fmamk_f32 v232, v232, 0x3c800000, v210
	s_nop 0
	v_rsq_f32_e32 v232, v232
	s_nop 0
	v_mul_f32_e32 v232, v223, v232
	v_pk_mul_f32 v[228:229], v[228:229], v[232:233] op_sel_hi:[1,0]
	v_pk_mul_f32 v[230:231], v[230:231], v[232:233] op_sel_hi:[1,0]
	v_pk_mul_f32 v[228:229], v[140:141], v[228:229]
	v_pk_mul_f32 v[230:231], v[142:143], v[230:231]
	v_pk_mul_f32 v[234:235], v[234:235], v[232:233] op_sel_hi:[1,0]
	v_pk_mul_f32 v[236:237], v[236:237], v[232:233] op_sel_hi:[1,0]
	v_cvt_pk_bf16_f32 v228, v228, v229
	v_cvt_pk_bf16_f32 v229, v230, v231
	v_pk_mul_f32 v[234:235], v[136:137], v[234:235]
	v_pk_mul_f32 v[236:237], v[138:139], v[236:237]
	v_cvt_pk_bf16_f32 v230, v234, v235
	v_pk_mul_f32 v[176:177], v[176:177], v[232:233] op_sel_hi:[1,0]
	v_cvt_pk_bf16_f32 v231, v236, v237
	global_store_dwordx4 v[238:239], v[228:231], off
	v_pk_mul_f32 v[176:177], v[128:129], v[176:177]
	s_nop 0
	v_pk_mul_f32 v[228:229], v[242:243], v[232:233] op_sel_hi:[1,0]
	v_pk_mul_f32 v[230:231], v[240:241], v[232:233] op_sel_hi:[1,0]
	v_pk_mul_f32 v[228:229], v[132:133], v[228:229]
	v_pk_mul_f32 v[230:231], v[134:135], v[230:231]
	v_pk_mul_f32 v[232:233], v[248:249], v[232:233] op_sel_hi:[1,0]
	v_cvt_pk_bf16_f32 v228, v228, v229
	v_cvt_pk_bf16_f32 v229, v230, v231
	v_cvt_pk_bf16_f32 v230, v176, v177
	s_nop 0
	v_pk_mul_f32 v[232:233], v[130:131], v[232:233]
	s_nop 0
	v_cvt_pk_bf16_f32 v231, v232, v233
	global_store_dwordx4 v[238:239], v[228:231], off offset:64
	s_nop 1
	v_min_u32_e32 v228, 32, v220
	v_lshlrev_b64 v[176:177], v228, v[192:193]
	v_min_u32_e32 v176, 1, v176
	v_or_b32_e32 v176, v177, v176
	v_cvt_f32_u32_e32 v176, v176
	v_sub_u32_e32 v177, 32, v228
	v_ldexp_f32 v176, v176, v177
	v_mul_f32_e32 v176, 0x35800000, v176
	v_fmamk_f32 v176, v176, 0x3a800000, v210
	s_nop 0
	v_rsq_f32_e32 v176, v176
	s_nop 0
	v_pk_mul_f32 v[228:229], v[92:93], v[176:177] op_sel_hi:[1,0]
	v_pk_mul_f32 v[230:231], v[94:95], v[176:177] op_sel_hi:[1,0]
	v_pk_mul_f32 v[234:235], v[228:229], v[228:229]
	v_pk_mul_f32 v[232:233], v[230:231], v[230:231]
	v_pk_mul_f32 v[248:249], v[82:83], v[176:177] op_sel_hi:[1,0]
	v_pk_mov_b32 v[236:237], v[234:235], v[232:233] op_sel:[1,0]
	v_mov_b32_e32 v235, v233
	v_pk_add_f32 v[232:233], v[236:237], v[234:235]
	v_pk_mul_f32 v[234:235], v[88:89], v[176:177] op_sel_hi:[1,0]
	v_pk_mul_f32 v[236:237], v[90:91], v[176:177] op_sel_hi:[1,0]
	v_pk_mul_f32 v[240:241], v[234:235], v[234:235]
	v_pk_mul_f32 v[238:239], v[236:237], v[236:237]
	v_pk_add_f32 v[232:233], v[232:233], v[232:233] op_sel_hi:[0,1]
	v_pk_mov_b32 v[242:243], v[240:241], v[238:239] op_sel:[1,0]
	v_mov_b32_e32 v241, v239
	v_pk_add_f32 v[238:239], v[242:243], v[240:241]
	v_pk_mul_f32 v[242:243], v[84:85], v[176:177] op_sel_hi:[1,0]
	v_pk_mul_f32 v[240:241], v[86:87], v[176:177] op_sel_hi:[1,0]
	v_mul_f32_e32 v232, v242, v242
	v_pk_fma_f32 v[244:245], v[242:243], v[242:243], v[232:233] op_sel_hi:[1,1,0]
	v_mul_f32_e32 v232, v240, v240
	v_pk_add_f32 v[238:239], v[238:239], v[238:239] op_sel_hi:[0,1]
	v_pk_fma_f32 v[246:247], v[240:241], v[240:241], v[232:233] op_sel_hi:[1,1,0]
	v_pk_mul_f32 v[176:177], v[80:81], v[176:177] op_sel_hi:[1,0]
	v_mul_f32_e32 v232, v248, v248
	v_mul_f32_e32 v244, v176, v176
	v_mul_f32_e32 v246, v177, v177
	v_mul_f32_e32 v238, v249, v249
	v_pk_add_f32 v[244:245], v[244:245], v[246:247]
	v_pk_add_f32 v[232:233], v[232:233], v[238:239]
	v_lshl_add_u64 v[238:239], v[206:207], 0, v[194:195]
	v_pk_add_f32 v[232:233], v[244:245], v[232:233]
	s_nop 0
	v_add_f32_e32 v232, v232, v233
	ds_bpermute_b32 v233, v225, v232
	s_waitcnt lgkmcnt(0)
	v_add_f32_e32 v232, v232, v233
	ds_bpermute_b32 v233, v224, v232
	s_waitcnt lgkmcnt(0)
	v_add_f32_e32 v232, v232, v233
	v_fmamk_f32 v232, v232, 0x3c800000, v210
	s_nop 0
	v_rsq_f32_e32 v232, v232
	s_nop 0
	v_mul_f32_e32 v232, v223, v232
	v_pk_mul_f32 v[228:229], v[228:229], v[232:233] op_sel_hi:[1,0]
	v_pk_mul_f32 v[230:231], v[230:231], v[232:233] op_sel_hi:[1,0]
	v_pk_mul_f32 v[228:229], v[140:141], v[228:229]
	v_pk_mul_f32 v[230:231], v[142:143], v[230:231]
	v_pk_mul_f32 v[234:235], v[234:235], v[232:233] op_sel_hi:[1,0]
	v_pk_mul_f32 v[236:237], v[236:237], v[232:233] op_sel_hi:[1,0]
	v_cvt_pk_bf16_f32 v228, v228, v229
	v_cvt_pk_bf16_f32 v229, v230, v231
	v_pk_mul_f32 v[234:235], v[136:137], v[234:235]
	v_pk_mul_f32 v[236:237], v[138:139], v[236:237]
	v_cvt_pk_bf16_f32 v230, v234, v235
	v_pk_mul_f32 v[176:177], v[176:177], v[232:233] op_sel_hi:[1,0]
	v_cvt_pk_bf16_f32 v231, v236, v237
	global_store_dwordx4 v[238:239], v[228:231], off
	v_pk_mul_f32 v[176:177], v[128:129], v[176:177]
	s_nop 0
	v_pk_mul_f32 v[228:229], v[242:243], v[232:233] op_sel_hi:[1,0]
	v_pk_mul_f32 v[230:231], v[240:241], v[232:233] op_sel_hi:[1,0]
	v_pk_mul_f32 v[228:229], v[132:133], v[228:229]
	v_pk_mul_f32 v[230:231], v[134:135], v[230:231]
	v_pk_mul_f32 v[232:233], v[248:249], v[232:233] op_sel_hi:[1,0]
	v_cvt_pk_bf16_f32 v228, v228, v229
	v_cvt_pk_bf16_f32 v229, v230, v231
	v_cvt_pk_bf16_f32 v230, v176, v177
	s_nop 0
	v_pk_mul_f32 v[232:233], v[130:131], v[232:233]
	s_nop 0
	v_cvt_pk_bf16_f32 v231, v232, v233
	global_store_dwordx4 v[238:239], v[228:231], off offset:64
	s_nop 1
	v_min_u32_e32 v228, 32, v219
	v_lshlrev_b64 v[176:177], v228, v[196:197]
	v_min_u32_e32 v176, 1, v176
	v_or_b32_e32 v176, v177, v176
	v_cvt_f32_u32_e32 v176, v176
	v_sub_u32_e32 v177, 32, v228
	v_ldexp_f32 v176, v176, v177
	v_mul_f32_e32 v176, 0x35800000, v176
	v_fmamk_f32 v176, v176, 0x3a800000, v210
	s_nop 0
	v_rsq_f32_e32 v176, v176
	s_nop 0
	v_pk_mul_f32 v[228:229], v[76:77], v[176:177] op_sel_hi:[1,0]
	v_pk_mul_f32 v[230:231], v[78:79], v[176:177] op_sel_hi:[1,0]
	v_pk_mul_f32 v[234:235], v[228:229], v[228:229]
	v_pk_mul_f32 v[232:233], v[230:231], v[230:231]
	v_pk_mul_f32 v[248:249], v[66:67], v[176:177] op_sel_hi:[1,0]
	v_pk_mov_b32 v[236:237], v[234:235], v[232:233] op_sel:[1,0]
	v_mov_b32_e32 v235, v233
	v_pk_add_f32 v[232:233], v[236:237], v[234:235]
	v_pk_mul_f32 v[234:235], v[72:73], v[176:177] op_sel_hi:[1,0]
	v_pk_mul_f32 v[236:237], v[74:75], v[176:177] op_sel_hi:[1,0]
	v_pk_mul_f32 v[240:241], v[234:235], v[234:235]
	v_pk_mul_f32 v[238:239], v[236:237], v[236:237]
	v_pk_add_f32 v[232:233], v[232:233], v[232:233] op_sel_hi:[0,1]
	v_pk_mov_b32 v[242:243], v[240:241], v[238:239] op_sel:[1,0]
	v_mov_b32_e32 v241, v239
	v_pk_add_f32 v[238:239], v[242:243], v[240:241]
	v_pk_mul_f32 v[242:243], v[68:69], v[176:177] op_sel_hi:[1,0]
	v_pk_mul_f32 v[240:241], v[70:71], v[176:177] op_sel_hi:[1,0]
	v_mul_f32_e32 v232, v242, v242
	v_pk_fma_f32 v[244:245], v[242:243], v[242:243], v[232:233] op_sel_hi:[1,1,0]
	v_mul_f32_e32 v232, v240, v240
	v_pk_add_f32 v[238:239], v[238:239], v[238:239] op_sel_hi:[0,1]
	v_pk_fma_f32 v[246:247], v[240:241], v[240:241], v[232:233] op_sel_hi:[1,1,0]
	v_pk_mul_f32 v[176:177], v[64:65], v[176:177] op_sel_hi:[1,0]
	v_mul_f32_e32 v232, v248, v248
	v_mul_f32_e32 v244, v176, v176
	v_mul_f32_e32 v246, v177, v177
	v_mul_f32_e32 v238, v249, v249
	v_pk_add_f32 v[244:245], v[244:245], v[246:247]
	v_pk_add_f32 v[232:233], v[232:233], v[238:239]
	v_lshl_add_u64 v[238:239], v[206:207], 0, v[190:191]
	v_pk_add_f32 v[232:233], v[244:245], v[232:233]
	s_nop 0
	v_add_f32_e32 v232, v232, v233
	ds_bpermute_b32 v233, v225, v232
	s_waitcnt lgkmcnt(0)
	v_add_f32_e32 v232, v232, v233
	ds_bpermute_b32 v233, v224, v232
	s_waitcnt lgkmcnt(0)
	v_add_f32_e32 v232, v232, v233
	v_fmamk_f32 v232, v232, 0x3c800000, v210
	s_nop 0
	v_rsq_f32_e32 v232, v232
	s_nop 0
	v_mul_f32_e32 v232, v223, v232
	v_pk_mul_f32 v[228:229], v[228:229], v[232:233] op_sel_hi:[1,0]
	v_pk_mul_f32 v[230:231], v[230:231], v[232:233] op_sel_hi:[1,0]
	v_pk_mul_f32 v[228:229], v[140:141], v[228:229]
	v_pk_mul_f32 v[230:231], v[142:143], v[230:231]
	v_pk_mul_f32 v[234:235], v[234:235], v[232:233] op_sel_hi:[1,0]
	v_pk_mul_f32 v[236:237], v[236:237], v[232:233] op_sel_hi:[1,0]
	v_pk_mul_f32 v[234:235], v[136:137], v[234:235]
	v_pk_mul_f32 v[236:237], v[138:139], v[236:237]
	v_cvt_pk_bf16_f32 v228, v228, v229
	v_cvt_pk_bf16_f32 v229, v230, v231
	v_cvt_pk_bf16_f32 v230, v234, v235
	v_pk_mul_f32 v[176:177], v[176:177], v[232:233] op_sel_hi:[1,0]
	v_cvt_pk_bf16_f32 v231, v236, v237
	global_store_dwordx4 v[238:239], v[228:231], off
	v_pk_mul_f32 v[176:177], v[128:129], v[176:177]
	s_nop 0
	v_pk_mul_f32 v[228:229], v[242:243], v[232:233] op_sel_hi:[1,0]
	v_pk_mul_f32 v[230:231], v[240:241], v[232:233] op_sel_hi:[1,0]
	v_pk_mul_f32 v[228:229], v[132:133], v[228:229]
	v_pk_mul_f32 v[230:231], v[134:135], v[230:231]
	v_pk_mul_f32 v[232:233], v[248:249], v[232:233] op_sel_hi:[1,0]
	v_cvt_pk_bf16_f32 v228, v228, v229
	v_cvt_pk_bf16_f32 v229, v230, v231
	v_cvt_pk_bf16_f32 v230, v176, v177
	v_ffbh_u32_e32 v176, v167
	v_pk_mul_f32 v[232:233], v[130:131], v[232:233]
	s_nop 0
	v_cvt_pk_bf16_f32 v231, v232, v233
	global_store_dwordx4 v[238:239], v[228:231], off offset:64
	s_nop 1
	v_min_u32_e32 v228, 32, v176
	v_lshlrev_b64 v[176:177], v228, v[166:167]
	v_min_u32_e32 v176, 1, v176
	v_or_b32_e32 v176, v177, v176
	v_cvt_f32_u32_e32 v176, v176
	v_sub_u32_e32 v177, 32, v228
	v_ldexp_f32 v176, v176, v177
	v_mul_f32_e32 v176, 0x35800000, v176
	v_fmamk_f32 v176, v176, 0x3a800000, v210
	s_nop 0
	v_rsq_f32_e32 v176, v176
	s_nop 0
	v_pk_mul_f32 v[228:229], v[60:61], v[176:177] op_sel_hi:[1,0]
	v_pk_mul_f32 v[230:231], v[62:63], v[176:177] op_sel_hi:[1,0]
	v_pk_mul_f32 v[234:235], v[228:229], v[228:229]
	v_pk_mul_f32 v[232:233], v[230:231], v[230:231]
	v_pk_mul_f32 v[248:249], v[50:51], v[176:177] op_sel_hi:[1,0]
	v_pk_mov_b32 v[236:237], v[234:235], v[232:233] op_sel:[1,0]
	v_mov_b32_e32 v235, v233
	v_pk_add_f32 v[232:233], v[236:237], v[234:235]
	v_pk_mul_f32 v[234:235], v[56:57], v[176:177] op_sel_hi:[1,0]
	v_pk_mul_f32 v[236:237], v[58:59], v[176:177] op_sel_hi:[1,0]
	v_pk_mul_f32 v[240:241], v[234:235], v[234:235]
	v_pk_mul_f32 v[238:239], v[236:237], v[236:237]
	v_pk_add_f32 v[232:233], v[232:233], v[232:233] op_sel_hi:[0,1]
	v_pk_mov_b32 v[242:243], v[240:241], v[238:239] op_sel:[1,0]
	v_mov_b32_e32 v241, v239
	v_pk_add_f32 v[238:239], v[242:243], v[240:241]
	v_pk_mul_f32 v[242:243], v[52:53], v[176:177] op_sel_hi:[1,0]
	v_pk_mul_f32 v[240:241], v[54:55], v[176:177] op_sel_hi:[1,0]
	v_mul_f32_e32 v232, v242, v242
	v_pk_fma_f32 v[244:245], v[242:243], v[242:243], v[232:233] op_sel_hi:[1,1,0]
	v_mul_f32_e32 v232, v240, v240
	v_pk_add_f32 v[238:239], v[238:239], v[238:239] op_sel_hi:[0,1]
	v_pk_fma_f32 v[246:247], v[240:241], v[240:241], v[232:233] op_sel_hi:[1,1,0]
	v_pk_mul_f32 v[176:177], v[48:49], v[176:177] op_sel_hi:[1,0]
	v_mul_f32_e32 v232, v248, v248
	v_mul_f32_e32 v244, v176, v176
	v_mul_f32_e32 v246, v177, v177
	v_mul_f32_e32 v238, v249, v249
	v_pk_add_f32 v[244:245], v[244:245], v[246:247]
	v_pk_add_f32 v[232:233], v[232:233], v[238:239]
	v_lshlrev_b64 v[238:239], 10, v[168:169]
	v_pk_add_f32 v[232:233], v[244:245], v[232:233]
	v_lshl_add_u64 v[238:239], v[206:207], 0, v[238:239]
	v_add_f32_e32 v232, v232, v233
	ds_bpermute_b32 v233, v225, v232
	s_waitcnt lgkmcnt(0)
	v_add_f32_e32 v232, v232, v233
	ds_bpermute_b32 v233, v224, v232
	s_waitcnt lgkmcnt(0)
	v_add_f32_e32 v232, v232, v233
	v_fmamk_f32 v232, v232, 0x3c800000, v210
	s_nop 0
	v_rsq_f32_e32 v232, v232
	s_nop 0
	v_mul_f32_e32 v232, v223, v232
	v_pk_mul_f32 v[228:229], v[228:229], v[232:233] op_sel_hi:[1,0]
	v_pk_mul_f32 v[230:231], v[230:231], v[232:233] op_sel_hi:[1,0]
	v_pk_mul_f32 v[228:229], v[140:141], v[228:229]
	v_pk_mul_f32 v[230:231], v[142:143], v[230:231]
	v_pk_mul_f32 v[234:235], v[234:235], v[232:233] op_sel_hi:[1,0]
	v_pk_mul_f32 v[236:237], v[236:237], v[232:233] op_sel_hi:[1,0]
	v_pk_mul_f32 v[234:235], v[136:137], v[234:235]
	v_pk_mul_f32 v[236:237], v[138:139], v[236:237]
	v_cvt_pk_bf16_f32 v228, v228, v229
	v_cvt_pk_bf16_f32 v229, v230, v231
	v_cvt_pk_bf16_f32 v230, v234, v235
	v_pk_mul_f32 v[176:177], v[176:177], v[232:233] op_sel_hi:[1,0]
	v_cvt_pk_bf16_f32 v231, v236, v237
	global_store_dwordx4 v[238:239], v[228:231], off
	v_pk_mul_f32 v[176:177], v[128:129], v[176:177]
	s_nop 0
	v_pk_mul_f32 v[228:229], v[242:243], v[232:233] op_sel_hi:[1,0]
	v_pk_mul_f32 v[230:231], v[240:241], v[232:233] op_sel_hi:[1,0]
	v_pk_mul_f32 v[228:229], v[132:133], v[228:229]
	v_pk_mul_f32 v[230:231], v[134:135], v[230:231]
	v_pk_mul_f32 v[232:233], v[248:249], v[232:233] op_sel_hi:[1,0]
	v_cvt_pk_bf16_f32 v228, v228, v229
	v_cvt_pk_bf16_f32 v229, v230, v231
	v_cvt_pk_bf16_f32 v230, v176, v177
	v_ffbh_u32_e32 v176, v189
	v_pk_mul_f32 v[232:233], v[130:131], v[232:233]
	s_nop 0
	v_cvt_pk_bf16_f32 v231, v232, v233
	global_store_dwordx4 v[238:239], v[228:231], off offset:64
	s_nop 1
	v_min_u32_e32 v228, 32, v176
	v_lshlrev_b64 v[176:177], v228, v[188:189]
	v_min_u32_e32 v176, 1, v176
	v_or_b32_e32 v176, v177, v176
	v_cvt_f32_u32_e32 v176, v176
	v_sub_u32_e32 v177, 32, v228
	v_ldexp_f32 v176, v176, v177
	v_mul_f32_e32 v176, 0x35800000, v176
	v_fmamk_f32 v176, v176, 0x3a800000, v210
	s_nop 0
	v_rsq_f32_e32 v176, v176
	s_nop 0
	v_pk_mul_f32 v[228:229], v[44:45], v[176:177] op_sel_hi:[1,0]
	v_pk_mul_f32 v[230:231], v[46:47], v[176:177] op_sel_hi:[1,0]
	v_pk_mul_f32 v[234:235], v[228:229], v[228:229]
	v_pk_mul_f32 v[232:233], v[230:231], v[230:231]
	v_pk_mul_f32 v[248:249], v[34:35], v[176:177] op_sel_hi:[1,0]
	v_pk_mov_b32 v[236:237], v[234:235], v[232:233] op_sel:[1,0]
	v_mov_b32_e32 v235, v233
	v_pk_add_f32 v[232:233], v[236:237], v[234:235]
	v_pk_mul_f32 v[234:235], v[40:41], v[176:177] op_sel_hi:[1,0]
	v_pk_mul_f32 v[236:237], v[42:43], v[176:177] op_sel_hi:[1,0]
	v_pk_mul_f32 v[240:241], v[234:235], v[234:235]
	v_pk_mul_f32 v[238:239], v[236:237], v[236:237]
	v_pk_add_f32 v[232:233], v[232:233], v[232:233] op_sel_hi:[0,1]
	v_pk_mov_b32 v[242:243], v[240:241], v[238:239] op_sel:[1,0]
	v_mov_b32_e32 v241, v239
	v_pk_add_f32 v[238:239], v[242:243], v[240:241]
	v_pk_mul_f32 v[242:243], v[36:37], v[176:177] op_sel_hi:[1,0]
	v_pk_mul_f32 v[240:241], v[38:39], v[176:177] op_sel_hi:[1,0]
	v_mul_f32_e32 v232, v242, v242
	v_pk_fma_f32 v[244:245], v[242:243], v[242:243], v[232:233] op_sel_hi:[1,1,0]
	v_mul_f32_e32 v232, v240, v240
	v_pk_add_f32 v[238:239], v[238:239], v[238:239] op_sel_hi:[0,1]
	v_pk_fma_f32 v[246:247], v[240:241], v[240:241], v[232:233] op_sel_hi:[1,1,0]
	v_pk_mul_f32 v[176:177], v[32:33], v[176:177] op_sel_hi:[1,0]
	v_mul_f32_e32 v232, v248, v248
	v_mul_f32_e32 v244, v176, v176
	v_mul_f32_e32 v246, v177, v177
	v_mul_f32_e32 v238, v249, v249
	v_pk_add_f32 v[244:245], v[244:245], v[246:247]
	v_pk_add_f32 v[232:233], v[232:233], v[238:239]
	v_lshlrev_b64 v[238:239], 10, v[164:165]
	v_pk_add_f32 v[232:233], v[244:245], v[232:233]
	v_lshl_add_u64 v[238:239], v[206:207], 0, v[238:239]
	v_add_f32_e32 v232, v232, v233
	ds_bpermute_b32 v233, v225, v232
	s_waitcnt lgkmcnt(0)
	v_add_f32_e32 v232, v232, v233
	ds_bpermute_b32 v233, v224, v232
	s_waitcnt lgkmcnt(0)
	v_add_f32_e32 v232, v232, v233
	v_fmamk_f32 v232, v232, 0x3c800000, v210
	s_nop 0
	v_rsq_f32_e32 v232, v232
	s_nop 0
	v_mul_f32_e32 v232, v223, v232
	v_pk_mul_f32 v[228:229], v[228:229], v[232:233] op_sel_hi:[1,0]
	v_pk_mul_f32 v[230:231], v[230:231], v[232:233] op_sel_hi:[1,0]
	v_pk_mul_f32 v[228:229], v[140:141], v[228:229]
	v_pk_mul_f32 v[230:231], v[142:143], v[230:231]
	v_pk_mul_f32 v[234:235], v[234:235], v[232:233] op_sel_hi:[1,0]
	v_pk_mul_f32 v[236:237], v[236:237], v[232:233] op_sel_hi:[1,0]
	v_pk_mul_f32 v[234:235], v[136:137], v[234:235]
	v_pk_mul_f32 v[236:237], v[138:139], v[236:237]
	v_cvt_pk_bf16_f32 v228, v228, v229
	v_cvt_pk_bf16_f32 v229, v230, v231
	v_cvt_pk_bf16_f32 v230, v234, v235
	v_pk_mul_f32 v[176:177], v[176:177], v[232:233] op_sel_hi:[1,0]
	v_cvt_pk_bf16_f32 v231, v236, v237
	global_store_dwordx4 v[238:239], v[228:231], off
	v_pk_mul_f32 v[176:177], v[128:129], v[176:177]
	s_nop 0
	v_pk_mul_f32 v[228:229], v[242:243], v[232:233] op_sel_hi:[1,0]
	v_pk_mul_f32 v[230:231], v[240:241], v[232:233] op_sel_hi:[1,0]
	v_pk_mul_f32 v[228:229], v[132:133], v[228:229]
	v_pk_mul_f32 v[230:231], v[134:135], v[230:231]
	v_pk_mul_f32 v[232:233], v[248:249], v[232:233] op_sel_hi:[1,0]
	v_cvt_pk_bf16_f32 v228, v228, v229
	v_cvt_pk_bf16_f32 v229, v230, v231
	v_cvt_pk_bf16_f32 v230, v176, v177
	v_ffbh_u32_e32 v176, v163
	v_pk_mul_f32 v[232:233], v[130:131], v[232:233]
	s_nop 0
	v_cvt_pk_bf16_f32 v231, v232, v233
	global_store_dwordx4 v[238:239], v[228:231], off offset:64
	s_nop 1
	v_min_u32_e32 v228, 32, v176
	v_lshlrev_b64 v[176:177], v228, v[162:163]
	v_min_u32_e32 v176, 1, v176
	v_or_b32_e32 v176, v177, v176
	v_cvt_f32_u32_e32 v176, v176
	v_sub_u32_e32 v177, 32, v228
	v_ldexp_f32 v176, v176, v177
	v_mul_f32_e32 v176, 0x35800000, v176
	v_fmamk_f32 v176, v176, 0x3a800000, v210
	s_nop 0
	v_rsq_f32_e32 v176, v176
	s_nop 0
	v_pk_mul_f32 v[228:229], v[28:29], v[176:177] op_sel_hi:[1,0]
	v_pk_mul_f32 v[230:231], v[30:31], v[176:177] op_sel_hi:[1,0]
	v_pk_mul_f32 v[234:235], v[228:229], v[228:229]
	v_pk_mul_f32 v[232:233], v[230:231], v[230:231]
	v_pk_mul_f32 v[248:249], v[18:19], v[176:177] op_sel_hi:[1,0]
	v_pk_mov_b32 v[236:237], v[234:235], v[232:233] op_sel:[1,0]
	v_mov_b32_e32 v235, v233
	v_pk_add_f32 v[232:233], v[236:237], v[234:235]
	v_pk_mul_f32 v[234:235], v[24:25], v[176:177] op_sel_hi:[1,0]
	v_pk_mul_f32 v[236:237], v[26:27], v[176:177] op_sel_hi:[1,0]
	v_pk_mul_f32 v[240:241], v[234:235], v[234:235]
	v_pk_mul_f32 v[238:239], v[236:237], v[236:237]
	v_pk_add_f32 v[232:233], v[232:233], v[232:233] op_sel_hi:[0,1]
	v_pk_mov_b32 v[242:243], v[240:241], v[238:239] op_sel:[1,0]
	v_mov_b32_e32 v241, v239
	v_pk_add_f32 v[238:239], v[242:243], v[240:241]
	v_pk_mul_f32 v[242:243], v[20:21], v[176:177] op_sel_hi:[1,0]
	v_pk_mul_f32 v[240:241], v[22:23], v[176:177] op_sel_hi:[1,0]
	v_mul_f32_e32 v232, v242, v242
	v_pk_fma_f32 v[244:245], v[242:243], v[242:243], v[232:233] op_sel_hi:[1,1,0]
	v_mul_f32_e32 v232, v240, v240
	v_pk_add_f32 v[238:239], v[238:239], v[238:239] op_sel_hi:[0,1]
	v_pk_fma_f32 v[246:247], v[240:241], v[240:241], v[232:233] op_sel_hi:[1,1,0]
	v_pk_mul_f32 v[176:177], v[16:17], v[176:177] op_sel_hi:[1,0]
	v_mul_f32_e32 v232, v248, v248
	v_mul_f32_e32 v244, v176, v176
	v_mul_f32_e32 v246, v177, v177
	v_mul_f32_e32 v238, v249, v249
	v_pk_add_f32 v[244:245], v[244:245], v[246:247]
	v_pk_add_f32 v[232:233], v[232:233], v[238:239]
	v_lshlrev_b64 v[238:239], 10, v[158:159]
	v_pk_add_f32 v[232:233], v[244:245], v[232:233]
	v_lshl_add_u64 v[238:239], v[206:207], 0, v[238:239]
	v_add_f32_e32 v232, v232, v233
	ds_bpermute_b32 v233, v225, v232
	s_waitcnt lgkmcnt(0)
	v_add_f32_e32 v232, v232, v233
	ds_bpermute_b32 v233, v224, v232
	s_waitcnt lgkmcnt(0)
	v_add_f32_e32 v232, v232, v233
	v_fmamk_f32 v232, v232, 0x3c800000, v210
	s_nop 0
	v_rsq_f32_e32 v232, v232
	s_nop 0
	v_mul_f32_e32 v232, v223, v232
	v_pk_mul_f32 v[228:229], v[228:229], v[232:233] op_sel_hi:[1,0]
	v_pk_mul_f32 v[230:231], v[230:231], v[232:233] op_sel_hi:[1,0]
	v_pk_mul_f32 v[228:229], v[140:141], v[228:229]
	v_pk_mul_f32 v[230:231], v[142:143], v[230:231]
	v_pk_mul_f32 v[234:235], v[234:235], v[232:233] op_sel_hi:[1,0]
	v_pk_mul_f32 v[236:237], v[236:237], v[232:233] op_sel_hi:[1,0]
	v_pk_mul_f32 v[234:235], v[136:137], v[234:235]
	v_pk_mul_f32 v[236:237], v[138:139], v[236:237]
	v_cvt_pk_bf16_f32 v228, v228, v229
	v_cvt_pk_bf16_f32 v229, v230, v231
	v_cvt_pk_bf16_f32 v230, v234, v235
	v_pk_mul_f32 v[176:177], v[176:177], v[232:233] op_sel_hi:[1,0]
	v_cvt_pk_bf16_f32 v231, v236, v237
	global_store_dwordx4 v[238:239], v[228:231], off
	v_pk_mul_f32 v[176:177], v[128:129], v[176:177]
	s_nop 0
	v_pk_mul_f32 v[228:229], v[242:243], v[232:233] op_sel_hi:[1,0]
	v_pk_mul_f32 v[230:231], v[240:241], v[232:233] op_sel_hi:[1,0]
	v_pk_mul_f32 v[228:229], v[132:133], v[228:229]
	v_pk_mul_f32 v[230:231], v[134:135], v[230:231]
	v_pk_mul_f32 v[232:233], v[248:249], v[232:233] op_sel_hi:[1,0]
	v_cvt_pk_bf16_f32 v228, v228, v229
	v_cvt_pk_bf16_f32 v229, v230, v231
	v_cvt_pk_bf16_f32 v230, v176, v177
	v_ffbh_u32_e32 v176, v161
	v_pk_mul_f32 v[232:233], v[130:131], v[232:233]
	s_nop 0
	v_cvt_pk_bf16_f32 v231, v232, v233
	global_store_dwordx4 v[238:239], v[228:231], off offset:64
	s_nop 1
	v_min_u32_e32 v228, 32, v176
	v_lshlrev_b64 v[176:177], v228, v[160:161]
	v_min_u32_e32 v176, 1, v176
	v_or_b32_e32 v176, v177, v176
	v_cvt_f32_u32_e32 v176, v176
	v_sub_u32_e32 v177, 32, v228
	v_ldexp_f32 v176, v176, v177
	v_mul_f32_e32 v176, 0x35800000, v176
	v_fmamk_f32 v176, v176, 0x3a800000, v210
	s_nop 0
	v_rsq_f32_e32 v176, v176
	s_nop 0
	v_pk_mul_f32 v[228:229], v[12:13], v[176:177] op_sel_hi:[1,0]
	v_pk_mul_f32 v[230:231], v[14:15], v[176:177] op_sel_hi:[1,0]
	v_pk_mul_f32 v[234:235], v[228:229], v[228:229]
	v_pk_mul_f32 v[232:233], v[230:231], v[230:231]
	v_pk_mul_f32 v[248:249], v[2:3], v[176:177] op_sel_hi:[1,0]
	v_pk_mov_b32 v[236:237], v[234:235], v[232:233] op_sel:[1,0]
	v_mov_b32_e32 v235, v233
	v_pk_add_f32 v[232:233], v[236:237], v[234:235]
	v_pk_mul_f32 v[234:235], v[8:9], v[176:177] op_sel_hi:[1,0]
	v_pk_mul_f32 v[236:237], v[10:11], v[176:177] op_sel_hi:[1,0]
	v_pk_mul_f32 v[240:241], v[234:235], v[234:235]
	v_pk_mul_f32 v[238:239], v[236:237], v[236:237]
	v_pk_add_f32 v[232:233], v[232:233], v[232:233] op_sel_hi:[0,1]
	v_pk_mov_b32 v[242:243], v[240:241], v[238:239] op_sel:[1,0]
	v_mov_b32_e32 v241, v239
	v_pk_add_f32 v[238:239], v[242:243], v[240:241]
	v_pk_mul_f32 v[242:243], v[4:5], v[176:177] op_sel_hi:[1,0]
	v_pk_mul_f32 v[240:241], v[6:7], v[176:177] op_sel_hi:[1,0]
	v_mul_f32_e32 v232, v242, v242
	v_pk_fma_f32 v[244:245], v[242:243], v[242:243], v[232:233] op_sel_hi:[1,1,0]
	v_mul_f32_e32 v232, v240, v240
	v_pk_add_f32 v[238:239], v[238:239], v[238:239] op_sel_hi:[0,1]
	v_pk_fma_f32 v[246:247], v[240:241], v[240:241], v[232:233] op_sel_hi:[1,1,0]
	v_pk_mul_f32 v[176:177], v[0:1], v[176:177] op_sel_hi:[1,0]
	v_mul_f32_e32 v232, v248, v248
	v_mul_f32_e32 v244, v176, v176
	v_mul_f32_e32 v246, v177, v177
	v_mul_f32_e32 v238, v249, v249
	v_pk_add_f32 v[244:245], v[244:245], v[246:247]
	v_pk_add_f32 v[232:233], v[232:233], v[238:239]
	s_nop 0
	v_pk_add_f32 v[232:233], v[244:245], v[232:233]
	s_nop 0
	v_add_f32_e32 v232, v232, v233
	ds_bpermute_b32 v225, v225, v232
	s_waitcnt lgkmcnt(0)
	v_add_f32_e32 v225, v232, v225
	ds_bpermute_b32 v224, v224, v225
	v_lshlrev_b64 v[232:233], 10, v[156:157]
	v_lshl_add_u64 v[206:207], v[206:207], 0, v[232:233]
	s_waitcnt lgkmcnt(0)
	v_add_f32_e32 v224, v225, v224
	v_fmamk_f32 v224, v224, 0x3c800000, v210
	s_nop 0
	v_rsq_f32_e32 v224, v224
	s_nop 0
	v_mul_f32_e32 v224, v223, v224
	v_pk_mul_f32 v[228:229], v[228:229], v[224:225] op_sel_hi:[1,0]
	v_pk_mul_f32 v[230:231], v[230:231], v[224:225] op_sel_hi:[1,0]
	v_pk_mul_f32 v[140:141], v[140:141], v[228:229]
	v_pk_mul_f32 v[142:143], v[142:143], v[230:231]
	v_pk_mul_f32 v[228:229], v[234:235], v[224:225] op_sel_hi:[1,0]
	v_pk_mul_f32 v[230:231], v[236:237], v[224:225] op_sel_hi:[1,0]
	s_nop 0
	v_pk_mul_f32 v[230:231], v[138:139], v[230:231]
	v_pk_mul_f32 v[138:139], v[136:137], v[228:229]
	v_cvt_pk_bf16_f32 v136, v140, v141
	v_cvt_pk_bf16_f32 v137, v142, v143
	s_nop 0
	v_cvt_pk_bf16_f32 v138, v138, v139
	v_cvt_pk_bf16_f32 v139, v230, v231
	global_store_dwordx4 v[206:207], v[136:139], off
	s_nop 1
	v_pk_mul_f32 v[136:137], v[242:243], v[224:225] op_sel_hi:[1,0]
	v_pk_mul_f32 v[138:139], v[240:241], v[224:225] op_sel_hi:[1,0]
	v_pk_mul_f32 v[132:133], v[132:133], v[136:137]
	v_pk_mul_f32 v[134:135], v[134:135], v[138:139]
	v_pk_mul_f32 v[136:137], v[176:177], v[224:225] op_sel_hi:[1,0]
	v_pk_mul_f32 v[138:139], v[248:249], v[224:225] op_sel_hi:[1,0]
	s_nop 0
	v_pk_mul_f32 v[138:139], v[130:131], v[138:139]
	v_pk_mul_f32 v[130:131], v[128:129], v[136:137]
	v_cvt_pk_bf16_f32 v128, v132, v133
	v_cvt_pk_bf16_f32 v129, v134, v135
	s_nop 0
	v_cvt_pk_bf16_f32 v130, v130, v131
	v_cvt_pk_bf16_f32 v131, v138, v139
	s_nop 1

.LBB0_350:
	s_lshl_b32 s25, s84, 1
	s_add_i32 s25, s85, s25
	s_and_b32 s85, s25, 3
	s_lshl_b32 s25, s85, 19
	s_add_u32 s92, s74, s25
	v_cmp_lt_i64_e32 vcc, s[52:53], v[180:181]
	s_addc_u32 s93, s75, 0
	s_and_b64 s[30:31], vcc, exec
	s_cselect_b32 s25, s93, s1
	s_cselect_b32 s30, s92, s0
	s_ashr_i32 s47, s46, 31
	s_lshl_b64 s[34:35], s[46:47], 19
	s_add_u32 s94, s54, s34
	s_addc_u32 s95, s55, s35
	s_and_b64 s[34:35], vcc, exec
	s_cselect_b32 s31, s95, s51
	s_cselect_b32 s33, s94, s50
	s_add_u32 s0, s0, 0x40080
	s_addc_u32 s1, s1, 0
	s_add_u32 s34, s50, 0x100
	s_addc_u32 s35, s51, 0
	s_mov_b32 s36, -2
	s_add_u32 s27, s0, 0xfffc0080
	s_addc_u32 s37, s1, -1
	s_add_i32 s47, 0, 0x10000
	v_add_u32_e32 v140, s47, v192
	ds_read_b128 v[128:131], v140
	ds_read_b128 v[132:135], v140 offset:1024
	ds_read_b128 v[136:139], v140 offset:2048
	ds_read_b128 v[140:143], v140 offset:3072
	s_cmp_eq_u32 s36, 12
	s_cselect_b32 s53, s25, s37
	s_cselect_b32 s52, s30, s27
	s_cselect_b32 s51, s31, s35
	s_cselect_b32 s50, s33, s34
	v_lshl_add_u64 v[176:177], s[0:1], 0, v[156:157]
	s_add_i32 m0, s77, 0xc000
	ds_read_b128 v[162:165], v194
	ds_read_b128 v[166:169], v194 offset:1024
	ds_read_b128 v[196:199], v194 offset:2048
	ds_read_b128 v[200:203], v194 offset:3072
	ds_read_b128 v[204:207], v194 offset:4096
	ds_read_b128 v[216:219], v194 offset:5120
	ds_read_b128 v[220:223], v194 offset:6144
	ds_read_b128 v[228:231], v194 offset:7168
	global_load_lds_dwordx4 v[176:177], off
	v_lshl_add_u64 v[176:177], s[0:1], 0, v[158:159]
	s_add_i32 m0, s77, 0xe000
	s_nop 0
	global_load_lds_dwordx4 v[176:177], off
	s_waitcnt lgkmcnt(8)
	s_setprio 1
	s_waitcnt lgkmcnt(0)
	s_barrier
	v_mfma_f32_16x16x32_bf16 v[124:127], v[128:131], v[162:165], 0
	v_mfma_f32_16x16x32_bf16 v[120:123], v[136:139], v[162:165], 0
	v_mfma_f32_16x16x32_bf16 v[116:119], v[128:131], v[196:199], 0
	v_mfma_f32_16x16x32_bf16 v[112:115], v[136:139], v[196:199], 0
	v_mfma_f32_16x16x32_bf16 v[108:111], v[128:131], v[204:207], 0
	v_mfma_f32_16x16x32_bf16 v[104:107], v[136:139], v[204:207], 0
	v_mfma_f32_16x16x32_bf16 v[100:103], v[128:131], v[220:223], 0
	v_mfma_f32_16x16x32_bf16 v[96:99], v[136:139], v[220:223], 0
	v_mfma_f32_16x16x32_bf16 v[124:127], v[132:135], v[166:169], v[124:127]
	v_mfma_f32_16x16x32_bf16 v[120:123], v[140:143], v[166:169], v[120:123]
	v_mfma_f32_16x16x32_bf16 v[116:119], v[132:135], v[200:203], v[116:119]
	v_mfma_f32_16x16x32_bf16 v[112:115], v[140:143], v[200:203], v[112:115]
	v_mfma_f32_16x16x32_bf16 v[108:111], v[132:135], v[216:219], v[108:111]
	v_mfma_f32_16x16x32_bf16 v[104:107], v[140:143], v[216:219], v[104:107]
	v_mfma_f32_16x16x32_bf16 v[100:103], v[132:135], v[228:231], v[100:103]
	v_mfma_f32_16x16x32_bf16 v[96:99], v[140:143], v[228:231], v[96:99]
	s_barrier
	s_setprio 0
	s_add_i32 s27, 0, 0x14000
	s_add_i32 s37, s47, s76
	v_add_u32_e32 v161, s27, v192
	v_lshl_add_u64 v[176:177], s[50:51], 0, v[148:149]
	s_mov_b32 m0, s37
	ds_read_b128 v[232:235], v161
	ds_read_b128 v[236:239], v161 offset:1024
	ds_read_b128 v[240:243], v161 offset:2048
	ds_read_b128 v[244:247], v161 offset:3072
	global_load_lds_dwordx4 v[176:177], off
	v_lshl_add_u64 v[188:189], s[50:51], 0, v[152:153]
	s_add_i32 m0, s37, 0x2000
	s_nop 0
	global_load_lds_dwordx4 v[188:189], off
	s_setprio 1
	s_waitcnt lgkmcnt(0)
	s_barrier
	v_mfma_f32_16x16x32_bf16 v[92:95], v[232:235], v[162:165], 0
	v_mfma_f32_16x16x32_bf16 v[88:91], v[240:243], v[162:165], 0
	v_mfma_f32_16x16x32_bf16 v[84:87], v[232:235], v[196:199], 0
	v_mfma_f32_16x16x32_bf16 v[80:83], v[240:243], v[196:199], 0
	v_mfma_f32_16x16x32_bf16 v[76:79], v[232:235], v[204:207], 0
	v_mfma_f32_16x16x32_bf16 v[72:75], v[240:243], v[204:207], 0
	v_mfma_f32_16x16x32_bf16 v[68:71], v[232:235], v[220:223], 0
	v_mfma_f32_16x16x32_bf16 v[64:67], v[240:243], v[220:223], 0
	v_mfma_f32_16x16x32_bf16 v[92:95], v[236:239], v[166:169], v[92:95]
	v_mfma_f32_16x16x32_bf16 v[88:91], v[244:247], v[166:169], v[88:91]
	v_mfma_f32_16x16x32_bf16 v[84:87], v[236:239], v[200:203], v[84:87]
	v_mfma_f32_16x16x32_bf16 v[80:83], v[244:247], v[200:203], v[80:83]
	v_mfma_f32_16x16x32_bf16 v[76:79], v[236:239], v[216:219], v[76:79]
	v_mfma_f32_16x16x32_bf16 v[72:75], v[244:247], v[216:219], v[72:75]
	v_mfma_f32_16x16x32_bf16 v[68:71], v[236:239], v[228:231], v[68:71]
	v_mfma_f32_16x16x32_bf16 v[64:67], v[244:247], v[228:231], v[64:67]
	s_barrier
	s_setprio 0
	s_mov_b32 m0, s77
	v_lshl_add_u64 v[224:225], s[52:53], 0, v[146:147]
	ds_read_b128 v[162:165], v194 offset:16384
	ds_read_b128 v[166:169], v194 offset:17408
	ds_read_b128 v[196:199], v194 offset:18432
	ds_read_b128 v[200:203], v194 offset:19456
	ds_read_b128 v[204:207], v194 offset:20480
	ds_read_b128 v[216:219], v194 offset:21504
	ds_read_b128 v[220:223], v194 offset:22528
	ds_read_b128 v[228:231], v194 offset:23552
	global_load_lds_dwordx4 v[224:225], off
	v_lshl_add_u64 v[248:249], s[52:53], 0, v[150:151]
	s_mov_b32 m0, s78
	s_nop 0
	global_load_lds_dwordx4 v[248:249], off
	s_setprio 1
	s_waitcnt lgkmcnt(0)
	s_barrier
	v_mfma_f32_16x16x32_bf16 v[60:63], v[128:131], v[162:165], 0
	v_mfma_f32_16x16x32_bf16 v[56:59], v[136:139], v[162:165], 0
	v_mfma_f32_16x16x32_bf16 v[52:55], v[128:131], v[196:199], 0
	v_mfma_f32_16x16x32_bf16 v[48:51], v[136:139], v[196:199], 0
	v_mfma_f32_16x16x32_bf16 v[44:47], v[128:131], v[204:207], 0
	v_mfma_f32_16x16x32_bf16 v[40:43], v[136:139], v[204:207], 0
	v_mfma_f32_16x16x32_bf16 v[36:39], v[128:131], v[220:223], 0
	v_mfma_f32_16x16x32_bf16 v[32:35], v[136:139], v[220:223], 0
	v_mfma_f32_16x16x32_bf16 v[60:63], v[132:135], v[166:169], v[60:63]
	v_mfma_f32_16x16x32_bf16 v[56:59], v[140:143], v[166:169], v[56:59]
	v_mfma_f32_16x16x32_bf16 v[52:55], v[132:135], v[200:203], v[52:55]
	v_mfma_f32_16x16x32_bf16 v[48:51], v[140:143], v[200:203], v[48:51]
	v_mfma_f32_16x16x32_bf16 v[44:47], v[132:135], v[216:219], v[44:47]
	v_mfma_f32_16x16x32_bf16 v[40:43], v[140:143], v[216:219], v[40:43]
	v_mfma_f32_16x16x32_bf16 v[36:39], v[132:135], v[228:231], v[36:39]
	v_mfma_f32_16x16x32_bf16 v[32:35], v[140:143], v[228:231], v[32:35]
	s_barrier
	s_setprio 0
	s_add_u32 s56, s50, 0x40000
	s_addc_u32 s57, s51, 0
	s_add_i32 s27, s27, s76
	v_lshl_add_u64 v[128:129], s[56:57], 0, v[148:149]
	s_mov_b32 m0, s27
	s_nop 0
	global_load_lds_dwordx4 v[128:129], off
	v_lshl_add_u64 v[128:129], s[56:57], 0, v[152:153]
	s_add_i32 m0, s27, 0x2000
	s_nop 0
	global_load_lds_dwordx4 v[128:129], off
	s_waitcnt vmcnt(6)
	s_setprio 1
	s_barrier
	v_mfma_f32_16x16x32_bf16 v[28:31], v[232:235], v[162:165], 0
	v_mfma_f32_16x16x32_bf16 v[24:27], v[240:243], v[162:165], 0
	v_mfma_f32_16x16x32_bf16 v[20:23], v[232:235], v[196:199], 0
	v_mfma_f32_16x16x32_bf16 v[16:19], v[240:243], v[196:199], 0
	v_mfma_f32_16x16x32_bf16 v[12:15], v[232:235], v[204:207], 0
	v_mfma_f32_16x16x32_bf16 v[8:11], v[240:243], v[204:207], 0
	v_mfma_f32_16x16x32_bf16 v[4:7], v[232:235], v[220:223], 0
	v_mfma_f32_16x16x32_bf16 v[0:3], v[240:243], v[220:223], 0
	v_mfma_f32_16x16x32_bf16 v[28:31], v[236:239], v[166:169], v[28:31]
	v_mfma_f32_16x16x32_bf16 v[24:27], v[244:247], v[166:169], v[24:27]
	v_mfma_f32_16x16x32_bf16 v[20:23], v[236:239], v[200:203], v[20:23]
	v_mfma_f32_16x16x32_bf16 v[16:19], v[244:247], v[200:203], v[16:19]
	v_mfma_f32_16x16x32_bf16 v[12:15], v[236:239], v[216:219], v[12:15]
	v_mfma_f32_16x16x32_bf16 v[8:11], v[244:247], v[216:219], v[8:11]
	v_mfma_f32_16x16x32_bf16 v[4:7], v[236:239], v[228:231], v[4:7]
	v_mfma_f32_16x16x32_bf16 v[0:3], v[244:247], v[228:231], v[0:3]
	s_barrier
	s_setprio 0
	s_add_i32 s27, 0, 0x18000
	v_add_u32_e32 v140, s27, v192
	ds_read_b128 v[128:131], v140
	ds_read_b128 v[132:135], v140 offset:1024
	ds_read_b128 v[136:139], v140 offset:2048
	ds_read_b128 v[140:143], v140 offset:3072
	s_add_u32 s52, s52, 0x40000
	s_addc_u32 s53, s53, 0
	s_mov_b32 m0, s81
	v_lshl_add_u64 v[232:233], s[52:53], 0, v[146:147]
	ds_read_b128 v[162:165], v194 offset:32768
	ds_read_b128 v[166:169], v194 offset:33792
	ds_read_b128 v[196:199], v194 offset:34816
	ds_read_b128 v[200:203], v194 offset:35840
	ds_read_b128 v[204:207], v194 offset:36864
	ds_read_b128 v[216:219], v194 offset:37888
	ds_read_b128 v[220:223], v194 offset:38912
	ds_read_b128 v[228:231], v194 offset:39936
	global_load_lds_dwordx4 v[232:233], off
	v_lshl_add_u64 v[232:233], s[52:53], 0, v[150:151]
	s_mov_b32 m0, s82
	s_nop 0
	global_load_lds_dwordx4 v[232:233], off
	s_waitcnt lgkmcnt(8)
	s_setprio 1
	s_waitcnt lgkmcnt(0)
	s_barrier
	v_mfma_f32_16x16x32_bf16 v[124:127], v[128:131], v[162:165], v[124:127]
	v_mfma_f32_16x16x32_bf16 v[120:123], v[136:139], v[162:165], v[120:123]
	v_mfma_f32_16x16x32_bf16 v[116:119], v[128:131], v[196:199], v[116:119]
	v_mfma_f32_16x16x32_bf16 v[112:115], v[136:139], v[196:199], v[112:115]
	v_mfma_f32_16x16x32_bf16 v[108:111], v[128:131], v[204:207], v[108:111]
	v_mfma_f32_16x16x32_bf16 v[104:107], v[136:139], v[204:207], v[104:107]
	v_mfma_f32_16x16x32_bf16 v[100:103], v[128:131], v[220:223], v[100:103]
	v_mfma_f32_16x16x32_bf16 v[96:99], v[136:139], v[220:223], v[96:99]
	v_mfma_f32_16x16x32_bf16 v[124:127], v[132:135], v[166:169], v[124:127]
	v_mfma_f32_16x16x32_bf16 v[120:123], v[140:143], v[166:169], v[120:123]
	v_mfma_f32_16x16x32_bf16 v[116:119], v[132:135], v[200:203], v[116:119]
	v_mfma_f32_16x16x32_bf16 v[112:115], v[140:143], v[200:203], v[112:115]
	v_mfma_f32_16x16x32_bf16 v[108:111], v[132:135], v[216:219], v[108:111]
	v_mfma_f32_16x16x32_bf16 v[104:107], v[140:143], v[216:219], v[104:107]
	v_mfma_f32_16x16x32_bf16 v[100:103], v[132:135], v[228:231], v[100:103]
	v_mfma_f32_16x16x32_bf16 v[96:99], v[140:143], v[228:231], v[96:99]
	s_barrier
	s_setprio 0
	s_add_i32 s37, 0, 0x1c000
	s_add_i32 s27, s27, s76
	v_add_u32_e32 v161, s37, v192
	v_lshl_add_u64 v[176:177], v[176:177], 0, s[18:19]
	s_mov_b32 m0, s27
	ds_read_b128 v[232:235], v161
	ds_read_b128 v[236:239], v161 offset:1024
	ds_read_b128 v[240:243], v161 offset:2048
	ds_read_b128 v[244:247], v161 offset:3072
	global_load_lds_dwordx4 v[176:177], off
	v_lshl_add_u64 v[176:177], v[188:189], 0, s[18:19]
	s_add_i32 m0, s27, 0x2000
	s_nop 0
	global_load_lds_dwordx4 v[176:177], off
	s_setprio 1
	s_waitcnt lgkmcnt(0)
	s_barrier
	v_mfma_f32_16x16x32_bf16 v[92:95], v[232:235], v[162:165], v[92:95]
	v_mfma_f32_16x16x32_bf16 v[88:91], v[240:243], v[162:165], v[88:91]
	v_mfma_f32_16x16x32_bf16 v[84:87], v[232:235], v[196:199], v[84:87]
	v_mfma_f32_16x16x32_bf16 v[80:83], v[240:243], v[196:199], v[80:83]
	v_mfma_f32_16x16x32_bf16 v[76:79], v[232:235], v[204:207], v[76:79]
	v_mfma_f32_16x16x32_bf16 v[72:75], v[240:243], v[204:207], v[72:75]
	v_mfma_f32_16x16x32_bf16 v[68:71], v[232:235], v[220:223], v[68:71]
	v_mfma_f32_16x16x32_bf16 v[64:67], v[240:243], v[220:223], v[64:67]
	v_mfma_f32_16x16x32_bf16 v[92:95], v[236:239], v[166:169], v[92:95]
	v_mfma_f32_16x16x32_bf16 v[88:91], v[244:247], v[166:169], v[88:91]
	v_mfma_f32_16x16x32_bf16 v[84:87], v[236:239], v[200:203], v[84:87]
	v_mfma_f32_16x16x32_bf16 v[80:83], v[244:247], v[200:203], v[80:83]
	v_mfma_f32_16x16x32_bf16 v[76:79], v[236:239], v[216:219], v[76:79]
	v_mfma_f32_16x16x32_bf16 v[72:75], v[244:247], v[216:219], v[72:75]
	v_mfma_f32_16x16x32_bf16 v[68:71], v[236:239], v[228:231], v[68:71]
	v_mfma_f32_16x16x32_bf16 v[64:67], v[244:247], v[228:231], v[64:67]
	s_barrier
	s_setprio 0
	s_mov_b32 m0, s80
	v_lshl_add_u64 v[176:177], v[224:225], 0, s[18:19]
	ds_read_b128 v[162:165], v194 offset:49152
	ds_read_b128 v[166:169], v194 offset:50176
	ds_read_b128 v[196:199], v194 offset:51200
	ds_read_b128 v[200:203], v194 offset:52224
	ds_read_b128 v[204:207], v194 offset:53248
	ds_read_b128 v[216:219], v194 offset:54272
	ds_read_b128 v[220:223], v194 offset:55296
	ds_read_b128 v[228:231], v194 offset:56320
	global_load_lds_dwordx4 v[176:177], off
	v_lshl_add_u64 v[176:177], v[248:249], 0, s[18:19]
	s_mov_b32 m0, s83
	s_nop 0
	global_load_lds_dwordx4 v[176:177], off
	s_setprio 1
	s_waitcnt lgkmcnt(0)
	s_barrier
	v_mfma_f32_16x16x32_bf16 v[60:63], v[128:131], v[162:165], v[60:63]
	v_mfma_f32_16x16x32_bf16 v[56:59], v[136:139], v[162:165], v[56:59]
	v_mfma_f32_16x16x32_bf16 v[52:55], v[128:131], v[196:199], v[52:55]
	v_mfma_f32_16x16x32_bf16 v[48:51], v[136:139], v[196:199], v[48:51]
	v_mfma_f32_16x16x32_bf16 v[44:47], v[128:131], v[204:207], v[44:47]
	v_mfma_f32_16x16x32_bf16 v[40:43], v[136:139], v[204:207], v[40:43]
	v_mfma_f32_16x16x32_bf16 v[36:39], v[128:131], v[220:223], v[36:39]
	v_mfma_f32_16x16x32_bf16 v[32:35], v[136:139], v[220:223], v[32:35]
	v_mfma_f32_16x16x32_bf16 v[60:63], v[132:135], v[166:169], v[60:63]
	v_mfma_f32_16x16x32_bf16 v[56:59], v[140:143], v[166:169], v[56:59]
	v_mfma_f32_16x16x32_bf16 v[52:55], v[132:135], v[200:203], v[52:55]
	v_mfma_f32_16x16x32_bf16 v[48:51], v[140:143], v[200:203], v[48:51]
	v_mfma_f32_16x16x32_bf16 v[44:47], v[132:135], v[216:219], v[44:47]
	v_mfma_f32_16x16x32_bf16 v[40:43], v[140:143], v[216:219], v[40:43]
	v_mfma_f32_16x16x32_bf16 v[36:39], v[132:135], v[228:231], v[36:39]
	v_mfma_f32_16x16x32_bf16 v[32:35], v[140:143], v[228:231], v[32:35]
	s_barrier
	s_setprio 0
	s_add_u32 s50, s50, 0x40080
	s_addc_u32 s51, s51, 0
	s_add_i32 s27, s37, s76
	v_lshl_add_u64 v[128:129], s[50:51], 0, v[148:149]
	s_mov_b32 m0, s27
	s_nop 0
	global_load_lds_dwordx4 v[128:129], off
	v_lshl_add_u64 v[128:129], s[50:51], 0, v[152:153]
	s_add_i32 m0, s27, 0x2000
	s_nop 0
	global_load_lds_dwordx4 v[128:129], off
	s_waitcnt vmcnt(6)
	s_setprio 1
	s_barrier
	v_mfma_f32_16x16x32_bf16 v[28:31], v[232:235], v[162:165], v[28:31]
	v_mfma_f32_16x16x32_bf16 v[24:27], v[240:243], v[162:165], v[24:27]
	v_mfma_f32_16x16x32_bf16 v[20:23], v[232:235], v[196:199], v[20:23]
	v_mfma_f32_16x16x32_bf16 v[16:19], v[240:243], v[196:199], v[16:19]
	v_mfma_f32_16x16x32_bf16 v[12:15], v[232:235], v[204:207], v[12:15]
	v_mfma_f32_16x16x32_bf16 v[8:11], v[240:243], v[204:207], v[8:11]
	v_mfma_f32_16x16x32_bf16 v[4:7], v[232:235], v[220:223], v[4:7]
	v_mfma_f32_16x16x32_bf16 v[0:3], v[240:243], v[220:223], v[0:3]
	v_mfma_f32_16x16x32_bf16 v[28:31], v[236:239], v[166:169], v[28:31]
	v_mfma_f32_16x16x32_bf16 v[24:27], v[244:247], v[166:169], v[24:27]
	v_mfma_f32_16x16x32_bf16 v[20:23], v[236:239], v[200:203], v[20:23]
	v_mfma_f32_16x16x32_bf16 v[16:19], v[244:247], v[200:203], v[16:19]
	v_mfma_f32_16x16x32_bf16 v[12:15], v[236:239], v[216:219], v[12:15]
	v_mfma_f32_16x16x32_bf16 v[8:11], v[244:247], v[216:219], v[8:11]
	v_mfma_f32_16x16x32_bf16 v[4:7], v[236:239], v[228:231], v[4:7]
	v_mfma_f32_16x16x32_bf16 v[0:3], v[244:247], v[228:231], v[0:3]
	s_barrier
	s_setprio 0
	s_add_i32 s36, s36, 2
	s_add_u32 s0, s0, 0x100
	s_addc_u32 s1, s1, 0
	s_add_u32 s34, s34, 0x100
	s_addc_u32 s35, s35, 0
	s_cmp_gt_u32 s36, 13
.LBB0_351:
	s_add_u32 s27, s0, 0xfffc0080
	s_addc_u32 s37, s1, -1
	s_add_i32 s47, 0, 0x10000
	v_add_u32_e32 v140, s47, v192
	ds_read_b128 v[128:131], v140
	ds_read_b128 v[132:135], v140 offset:1024
	ds_read_b128 v[136:139], v140 offset:2048
	ds_read_b128 v[140:143], v140 offset:3072
	s_cmp_eq_u32 s36, 12
	s_cselect_b32 s53, s25, s37
	s_cselect_b32 s52, s30, s27
	s_cselect_b32 s51, s31, s35
	s_cselect_b32 s50, s33, s34
	v_lshl_add_u64 v[176:177], s[0:1], 0, v[156:157]
	s_add_i32 m0, s77, 0xc000
	ds_read_b128 v[162:165], v194
	ds_read_b128 v[166:169], v194 offset:1024
	ds_read_b128 v[196:199], v194 offset:2048
	ds_read_b128 v[200:203], v194 offset:3072
	ds_read_b128 v[204:207], v194 offset:4096
	ds_read_b128 v[216:219], v194 offset:5120
	ds_read_b128 v[220:223], v194 offset:6144
	ds_read_b128 v[228:231], v194 offset:7168
	global_load_lds_dwordx4 v[176:177], off
	v_lshl_add_u64 v[176:177], s[0:1], 0, v[158:159]
	s_add_i32 m0, s77, 0xe000
	s_nop 0
	global_load_lds_dwordx4 v[176:177], off
	s_waitcnt lgkmcnt(8)
	s_setprio 1
	s_waitcnt lgkmcnt(0)
	s_barrier
	v_mfma_f32_16x16x32_bf16 v[124:127], v[128:131], v[162:165], v[124:127]
	v_mfma_f32_16x16x32_bf16 v[120:123], v[136:139], v[162:165], v[120:123]
	v_mfma_f32_16x16x32_bf16 v[116:119], v[128:131], v[196:199], v[116:119]
	v_mfma_f32_16x16x32_bf16 v[112:115], v[136:139], v[196:199], v[112:115]
	v_mfma_f32_16x16x32_bf16 v[108:111], v[128:131], v[204:207], v[108:111]
	v_mfma_f32_16x16x32_bf16 v[104:107], v[136:139], v[204:207], v[104:107]
	v_mfma_f32_16x16x32_bf16 v[100:103], v[128:131], v[220:223], v[100:103]
	v_mfma_f32_16x16x32_bf16 v[96:99], v[136:139], v[220:223], v[96:99]
	v_mfma_f32_16x16x32_bf16 v[124:127], v[132:135], v[166:169], v[124:127]
	v_mfma_f32_16x16x32_bf16 v[120:123], v[140:143], v[166:169], v[120:123]
	v_mfma_f32_16x16x32_bf16 v[116:119], v[132:135], v[200:203], v[116:119]
	v_mfma_f32_16x16x32_bf16 v[112:115], v[140:143], v[200:203], v[112:115]
	v_mfma_f32_16x16x32_bf16 v[108:111], v[132:135], v[216:219], v[108:111]
	v_mfma_f32_16x16x32_bf16 v[104:107], v[140:143], v[216:219], v[104:107]
	v_mfma_f32_16x16x32_bf16 v[100:103], v[132:135], v[228:231], v[100:103]
	v_mfma_f32_16x16x32_bf16 v[96:99], v[140:143], v[228:231], v[96:99]
	s_barrier
	s_setprio 0
	s_add_i32 s27, 0, 0x14000
	s_add_i32 s37, s47, s76
	v_add_u32_e32 v161, s27, v192
	v_lshl_add_u64 v[176:177], s[50:51], 0, v[148:149]
	s_mov_b32 m0, s37
	ds_read_b128 v[232:235], v161
	ds_read_b128 v[236:239], v161 offset:1024
	ds_read_b128 v[240:243], v161 offset:2048
	ds_read_b128 v[244:247], v161 offset:3072
	global_load_lds_dwordx4 v[176:177], off
	v_lshl_add_u64 v[188:189], s[50:51], 0, v[152:153]
	s_add_i32 m0, s37, 0x2000
	s_nop 0
	global_load_lds_dwordx4 v[188:189], off
	s_setprio 1
	s_waitcnt lgkmcnt(0)
	s_barrier
	v_mfma_f32_16x16x32_bf16 v[92:95], v[232:235], v[162:165], v[92:95]
	v_mfma_f32_16x16x32_bf16 v[88:91], v[240:243], v[162:165], v[88:91]
	v_mfma_f32_16x16x32_bf16 v[84:87], v[232:235], v[196:199], v[84:87]
	v_mfma_f32_16x16x32_bf16 v[80:83], v[240:243], v[196:199], v[80:83]
	v_mfma_f32_16x16x32_bf16 v[76:79], v[232:235], v[204:207], v[76:79]
	v_mfma_f32_16x16x32_bf16 v[72:75], v[240:243], v[204:207], v[72:75]
	v_mfma_f32_16x16x32_bf16 v[68:71], v[232:235], v[220:223], v[68:71]
	v_mfma_f32_16x16x32_bf16 v[64:67], v[240:243], v[220:223], v[64:67]
	v_mfma_f32_16x16x32_bf16 v[92:95], v[236:239], v[166:169], v[92:95]
	v_mfma_f32_16x16x32_bf16 v[88:91], v[244:247], v[166:169], v[88:91]
	v_mfma_f32_16x16x32_bf16 v[84:87], v[236:239], v[200:203], v[84:87]
	v_mfma_f32_16x16x32_bf16 v[80:83], v[244:247], v[200:203], v[80:83]
	v_mfma_f32_16x16x32_bf16 v[76:79], v[236:239], v[216:219], v[76:79]
	v_mfma_f32_16x16x32_bf16 v[72:75], v[244:247], v[216:219], v[72:75]
	v_mfma_f32_16x16x32_bf16 v[68:71], v[236:239], v[228:231], v[68:71]
	v_mfma_f32_16x16x32_bf16 v[64:67], v[244:247], v[228:231], v[64:67]
	s_barrier
	s_setprio 0
	s_mov_b32 m0, s77
	v_lshl_add_u64 v[224:225], s[52:53], 0, v[146:147]
	ds_read_b128 v[162:165], v194 offset:16384
	ds_read_b128 v[166:169], v194 offset:17408
	ds_read_b128 v[196:199], v194 offset:18432
	ds_read_b128 v[200:203], v194 offset:19456
	ds_read_b128 v[204:207], v194 offset:20480
	ds_read_b128 v[216:219], v194 offset:21504
	ds_read_b128 v[220:223], v194 offset:22528
	ds_read_b128 v[228:231], v194 offset:23552
	global_load_lds_dwordx4 v[224:225], off
	v_lshl_add_u64 v[248:249], s[52:53], 0, v[150:151]
	s_mov_b32 m0, s78
	s_nop 0
	global_load_lds_dwordx4 v[248:249], off
	s_setprio 1
	s_waitcnt lgkmcnt(0)
	s_barrier
	v_mfma_f32_16x16x32_bf16 v[60:63], v[128:131], v[162:165], v[60:63]
	v_mfma_f32_16x16x32_bf16 v[56:59], v[136:139], v[162:165], v[56:59]
	v_mfma_f32_16x16x32_bf16 v[52:55], v[128:131], v[196:199], v[52:55]
	v_mfma_f32_16x16x32_bf16 v[48:51], v[136:139], v[196:199], v[48:51]
	v_mfma_f32_16x16x32_bf16 v[44:47], v[128:131], v[204:207], v[44:47]
	v_mfma_f32_16x16x32_bf16 v[40:43], v[136:139], v[204:207], v[40:43]
	v_mfma_f32_16x16x32_bf16 v[36:39], v[128:131], v[220:223], v[36:39]
	v_mfma_f32_16x16x32_bf16 v[32:35], v[136:139], v[220:223], v[32:35]
	v_mfma_f32_16x16x32_bf16 v[60:63], v[132:135], v[166:169], v[60:63]
	v_mfma_f32_16x16x32_bf16 v[56:59], v[140:143], v[166:169], v[56:59]
	v_mfma_f32_16x16x32_bf16 v[52:55], v[132:135], v[200:203], v[52:55]
	v_mfma_f32_16x16x32_bf16 v[48:51], v[140:143], v[200:203], v[48:51]
	v_mfma_f32_16x16x32_bf16 v[44:47], v[132:135], v[216:219], v[44:47]
	v_mfma_f32_16x16x32_bf16 v[40:43], v[140:143], v[216:219], v[40:43]
	v_mfma_f32_16x16x32_bf16 v[36:39], v[132:135], v[228:231], v[36:39]
	v_mfma_f32_16x16x32_bf16 v[32:35], v[140:143], v[228:231], v[32:35]
	s_barrier
	s_setprio 0
	s_add_u32 s56, s50, 0x40000
	s_addc_u32 s57, s51, 0
	s_add_i32 s27, s27, s76
	v_lshl_add_u64 v[128:129], s[56:57], 0, v[148:149]
	s_mov_b32 m0, s27
	s_nop 0
	global_load_lds_dwordx4 v[128:129], off
	v_lshl_add_u64 v[128:129], s[56:57], 0, v[152:153]
	s_add_i32 m0, s27, 0x2000
	s_nop 0
	global_load_lds_dwordx4 v[128:129], off
	s_waitcnt vmcnt(6)
	s_setprio 1
	s_barrier
	v_mfma_f32_16x16x32_bf16 v[28:31], v[232:235], v[162:165], v[28:31]
	v_mfma_f32_16x16x32_bf16 v[24:27], v[240:243], v[162:165], v[24:27]
	v_mfma_f32_16x16x32_bf16 v[20:23], v[232:235], v[196:199], v[20:23]
	v_mfma_f32_16x16x32_bf16 v[16:19], v[240:243], v[196:199], v[16:19]
	v_mfma_f32_16x16x32_bf16 v[12:15], v[232:235], v[204:207], v[12:15]
	v_mfma_f32_16x16x32_bf16 v[8:11], v[240:243], v[204:207], v[8:11]
	v_mfma_f32_16x16x32_bf16 v[4:7], v[232:235], v[220:223], v[4:7]
	v_mfma_f32_16x16x32_bf16 v[0:3], v[240:243], v[220:223], v[0:3]
	v_mfma_f32_16x16x32_bf16 v[28:31], v[236:239], v[166:169], v[28:31]
	v_mfma_f32_16x16x32_bf16 v[24:27], v[244:247], v[166:169], v[24:27]
	v_mfma_f32_16x16x32_bf16 v[20:23], v[236:239], v[200:203], v[20:23]
	v_mfma_f32_16x16x32_bf16 v[16:19], v[244:247], v[200:203], v[16:19]
	v_mfma_f32_16x16x32_bf16 v[12:15], v[236:239], v[216:219], v[12:15]
	v_mfma_f32_16x16x32_bf16 v[8:11], v[244:247], v[216:219], v[8:11]
	v_mfma_f32_16x16x32_bf16 v[4:7], v[236:239], v[228:231], v[4:7]
	v_mfma_f32_16x16x32_bf16 v[0:3], v[244:247], v[228:231], v[0:3]
	s_barrier
	s_setprio 0
	s_add_i32 s27, 0, 0x18000
	v_add_u32_e32 v140, s27, v192
	ds_read_b128 v[128:131], v140
	ds_read_b128 v[132:135], v140 offset:1024
	ds_read_b128 v[136:139], v140 offset:2048
	ds_read_b128 v[140:143], v140 offset:3072
	s_add_u32 s52, s52, 0x40000
	s_addc_u32 s53, s53, 0
	s_mov_b32 m0, s81
	v_lshl_add_u64 v[232:233], s[52:53], 0, v[146:147]
	ds_read_b128 v[162:165], v194 offset:32768
	ds_read_b128 v[166:169], v194 offset:33792
	ds_read_b128 v[196:199], v194 offset:34816
	ds_read_b128 v[200:203], v194 offset:35840
	ds_read_b128 v[204:207], v194 offset:36864
	ds_read_b128 v[216:219], v194 offset:37888
	ds_read_b128 v[220:223], v194 offset:38912
	ds_read_b128 v[228:231], v194 offset:39936
	global_load_lds_dwordx4 v[232:233], off
	v_lshl_add_u64 v[232:233], s[52:53], 0, v[150:151]
	s_mov_b32 m0, s82
	s_nop 0
	global_load_lds_dwordx4 v[232:233], off
	s_waitcnt lgkmcnt(8)
	s_setprio 1
	s_waitcnt lgkmcnt(0)
	s_barrier
	v_mfma_f32_16x16x32_bf16 v[124:127], v[128:131], v[162:165], v[124:127]
	v_mfma_f32_16x16x32_bf16 v[120:123], v[136:139], v[162:165], v[120:123]
	v_mfma_f32_16x16x32_bf16 v[116:119], v[128:131], v[196:199], v[116:119]
	v_mfma_f32_16x16x32_bf16 v[112:115], v[136:139], v[196:199], v[112:115]
	v_mfma_f32_16x16x32_bf16 v[108:111], v[128:131], v[204:207], v[108:111]
	v_mfma_f32_16x16x32_bf16 v[104:107], v[136:139], v[204:207], v[104:107]
	v_mfma_f32_16x16x32_bf16 v[100:103], v[128:131], v[220:223], v[100:103]
	v_mfma_f32_16x16x32_bf16 v[96:99], v[136:139], v[220:223], v[96:99]
	v_mfma_f32_16x16x32_bf16 v[124:127], v[132:135], v[166:169], v[124:127]
	v_mfma_f32_16x16x32_bf16 v[120:123], v[140:143], v[166:169], v[120:123]
	v_mfma_f32_16x16x32_bf16 v[116:119], v[132:135], v[200:203], v[116:119]
	v_mfma_f32_16x16x32_bf16 v[112:115], v[140:143], v[200:203], v[112:115]
	v_mfma_f32_16x16x32_bf16 v[108:111], v[132:135], v[216:219], v[108:111]
	v_mfma_f32_16x16x32_bf16 v[104:107], v[140:143], v[216:219], v[104:107]
	v_mfma_f32_16x16x32_bf16 v[100:103], v[132:135], v[228:231], v[100:103]
	v_mfma_f32_16x16x32_bf16 v[96:99], v[140:143], v[228:231], v[96:99]
	s_barrier
	s_setprio 0
	s_add_i32 s37, 0, 0x1c000
	s_add_i32 s27, s27, s76
	v_add_u32_e32 v161, s37, v192
	v_lshl_add_u64 v[176:177], v[176:177], 0, s[18:19]
	s_mov_b32 m0, s27
	ds_read_b128 v[232:235], v161
	ds_read_b128 v[236:239], v161 offset:1024
	ds_read_b128 v[240:243], v161 offset:2048
	ds_read_b128 v[244:247], v161 offset:3072
	global_load_lds_dwordx4 v[176:177], off
	v_lshl_add_u64 v[176:177], v[188:189], 0, s[18:19]
	s_add_i32 m0, s27, 0x2000
	s_nop 0
	global_load_lds_dwordx4 v[176:177], off
	s_setprio 1
	s_waitcnt lgkmcnt(0)
	s_barrier
	v_mfma_f32_16x16x32_bf16 v[92:95], v[232:235], v[162:165], v[92:95]
	v_mfma_f32_16x16x32_bf16 v[88:91], v[240:243], v[162:165], v[88:91]
	v_mfma_f32_16x16x32_bf16 v[84:87], v[232:235], v[196:199], v[84:87]
	v_mfma_f32_16x16x32_bf16 v[80:83], v[240:243], v[196:199], v[80:83]
	v_mfma_f32_16x16x32_bf16 v[76:79], v[232:235], v[204:207], v[76:79]
	v_mfma_f32_16x16x32_bf16 v[72:75], v[240:243], v[204:207], v[72:75]
	v_mfma_f32_16x16x32_bf16 v[68:71], v[232:235], v[220:223], v[68:71]
	v_mfma_f32_16x16x32_bf16 v[64:67], v[240:243], v[220:223], v[64:67]
	v_mfma_f32_16x16x32_bf16 v[92:95], v[236:239], v[166:169], v[92:95]
	v_mfma_f32_16x16x32_bf16 v[88:91], v[244:247], v[166:169], v[88:91]
	v_mfma_f32_16x16x32_bf16 v[84:87], v[236:239], v[200:203], v[84:87]
	v_mfma_f32_16x16x32_bf16 v[80:83], v[244:247], v[200:203], v[80:83]
	v_mfma_f32_16x16x32_bf16 v[76:79], v[236:239], v[216:219], v[76:79]
	v_mfma_f32_16x16x32_bf16 v[72:75], v[244:247], v[216:219], v[72:75]
	v_mfma_f32_16x16x32_bf16 v[68:71], v[236:239], v[228:231], v[68:71]
	v_mfma_f32_16x16x32_bf16 v[64:67], v[244:247], v[228:231], v[64:67]
	s_barrier
	s_setprio 0
	s_mov_b32 m0, s80
	v_lshl_add_u64 v[176:177], v[224:225], 0, s[18:19]
	ds_read_b128 v[162:165], v194 offset:49152
	ds_read_b128 v[166:169], v194 offset:50176
	ds_read_b128 v[196:199], v194 offset:51200
	ds_read_b128 v[200:203], v194 offset:52224
	ds_read_b128 v[204:207], v194 offset:53248
	ds_read_b128 v[216:219], v194 offset:54272
	ds_read_b128 v[220:223], v194 offset:55296
	ds_read_b128 v[228:231], v194 offset:56320
	global_load_lds_dwordx4 v[176:177], off
	v_lshl_add_u64 v[176:177], v[248:249], 0, s[18:19]
	s_mov_b32 m0, s83
	s_nop 0
	global_load_lds_dwordx4 v[176:177], off
	s_setprio 1
	s_waitcnt lgkmcnt(0)
	s_barrier
	v_mfma_f32_16x16x32_bf16 v[60:63], v[128:131], v[162:165], v[60:63]
	v_mfma_f32_16x16x32_bf16 v[56:59], v[136:139], v[162:165], v[56:59]
	v_mfma_f32_16x16x32_bf16 v[52:55], v[128:131], v[196:199], v[52:55]
	v_mfma_f32_16x16x32_bf16 v[48:51], v[136:139], v[196:199], v[48:51]
	v_mfma_f32_16x16x32_bf16 v[44:47], v[128:131], v[204:207], v[44:47]
	v_mfma_f32_16x16x32_bf16 v[40:43], v[136:139], v[204:207], v[40:43]
	v_mfma_f32_16x16x32_bf16 v[36:39], v[128:131], v[220:223], v[36:39]
	v_mfma_f32_16x16x32_bf16 v[32:35], v[136:139], v[220:223], v[32:35]
	v_mfma_f32_16x16x32_bf16 v[60:63], v[132:135], v[166:169], v[60:63]
	v_mfma_f32_16x16x32_bf16 v[56:59], v[140:143], v[166:169], v[56:59]
	v_mfma_f32_16x16x32_bf16 v[52:55], v[132:135], v[200:203], v[52:55]
	v_mfma_f32_16x16x32_bf16 v[48:51], v[140:143], v[200:203], v[48:51]
	v_mfma_f32_16x16x32_bf16 v[44:47], v[132:135], v[216:219], v[44:47]
	v_mfma_f32_16x16x32_bf16 v[40:43], v[140:143], v[216:219], v[40:43]
	v_mfma_f32_16x16x32_bf16 v[36:39], v[132:135], v[228:231], v[36:39]
	v_mfma_f32_16x16x32_bf16 v[32:35], v[140:143], v[228:231], v[32:35]
	s_barrier
	s_setprio 0
	s_add_u32 s50, s50, 0x40080
	s_addc_u32 s51, s51, 0
	s_add_i32 s27, s37, s76
	v_lshl_add_u64 v[128:129], s[50:51], 0, v[148:149]
	s_mov_b32 m0, s27
	s_nop 0
	global_load_lds_dwordx4 v[128:129], off
	v_lshl_add_u64 v[128:129], s[50:51], 0, v[152:153]
	s_add_i32 m0, s27, 0x2000
	s_nop 0
	global_load_lds_dwordx4 v[128:129], off
	s_waitcnt vmcnt(6)
	s_setprio 1
	s_barrier
	v_mfma_f32_16x16x32_bf16 v[28:31], v[232:235], v[162:165], v[28:31]
	v_mfma_f32_16x16x32_bf16 v[24:27], v[240:243], v[162:165], v[24:27]
	v_mfma_f32_16x16x32_bf16 v[20:23], v[232:235], v[196:199], v[20:23]
	v_mfma_f32_16x16x32_bf16 v[16:19], v[240:243], v[196:199], v[16:19]
	v_mfma_f32_16x16x32_bf16 v[12:15], v[232:235], v[204:207], v[12:15]
	v_mfma_f32_16x16x32_bf16 v[8:11], v[240:243], v[204:207], v[8:11]
	v_mfma_f32_16x16x32_bf16 v[4:7], v[232:235], v[220:223], v[4:7]
	v_mfma_f32_16x16x32_bf16 v[0:3], v[240:243], v[220:223], v[0:3]
	v_mfma_f32_16x16x32_bf16 v[28:31], v[236:239], v[166:169], v[28:31]
	v_mfma_f32_16x16x32_bf16 v[24:27], v[244:247], v[166:169], v[24:27]
	v_mfma_f32_16x16x32_bf16 v[20:23], v[236:239], v[200:203], v[20:23]
	v_mfma_f32_16x16x32_bf16 v[16:19], v[244:247], v[200:203], v[16:19]
	v_mfma_f32_16x16x32_bf16 v[12:15], v[236:239], v[216:219], v[12:15]
	v_mfma_f32_16x16x32_bf16 v[8:11], v[244:247], v[216:219], v[8:11]
	v_mfma_f32_16x16x32_bf16 v[4:7], v[236:239], v[228:231], v[4:7]
	v_mfma_f32_16x16x32_bf16 v[0:3], v[244:247], v[228:231], v[0:3]
	s_barrier
	s_setprio 0
	s_add_i32 s36, s36, 2
	s_add_u32 s0, s0, 0x100
	s_addc_u32 s1, s1, 0
	s_add_u32 s34, s34, 0x100
	s_addc_u32 s35, s35, 0
	s_cmp_gt_u32 s36, 13
	s_cbranch_scc0 .LBB0_351
	s_lshl_b32 s0, s11, 8
	s_or_b32 s50, s0, s79
	s_ashr_i32 s51, s50, 31
	v_lshl_add_u64 v[140:141], s[50:51], 3, v[154:155]
	global_load_dwordx4 v[128:131], v[140:141], off offset:48
	global_load_dwordx4 v[132:135], v[140:141], off offset:32
	global_load_dwordx4 v[136:139], v[140:141], off offset:16
	global_load_dwordx4 v[162:165], v[140:141], off
	s_mov_b32 s34, 0x35800000
	s_mov_b32 s0, 0x358637bd
	v_mov_b64_e32 v[168:169], s[0:1]
	s_mov_b32 s30, 0x45800000
	s_cmp_lt_u32 s10, 2
	s_waitcnt vmcnt(0)
	v_ffbh_u32_e32 v142, v165
	v_min_u32_e32 v161, 32, v142
	v_lshlrev_b64 v[142:143], v161, v[164:165]
	v_min_u32_e32 v142, 1, v142
	v_or_b32_e32 v142, v143, v142
	v_cvt_f32_u32_e32 v142, v142
	v_sub_u32_e32 v143, 32, v161
	v_ldexp_f32 v143, v142, v143
	v_ffbh_u32_e32 v142, v163
	v_min_u32_e32 v142, 32, v142
	v_lshlrev_b64 v[162:163], v142, v[162:163]
	v_min_u32_e32 v161, 1, v162
	v_or_b32_e32 v161, v163, v161
	v_cvt_f32_u32_e32 v161, v161
	v_sub_u32_e32 v142, 32, v142
	v_ldexp_f32 v142, v161, v142
	v_pk_mul_f32 v[142:143], v[142:143], s[34:35] op_sel_hi:[1,0]
	s_nop 0
	v_pk_fma_f32 v[142:143], v[142:143], s[2:3], v[168:169] op_sel_hi:[1,0,0]
	s_nop 0
	v_mul_f32_e32 v161, 0x4b800000, v142
	v_cmp_gt_f32_e64 s[0:1], s89, v142
	v_cmp_gt_f32_e32 vcc, s89, v143
	s_nop 0
	v_cndmask_b32_e64 v142, v142, v161, s[0:1]
	v_mul_f32_e32 v161, 0x4b800000, v143
	v_cndmask_b32_e32 v143, v143, v161, vcc
	v_rsq_f32_e32 v142, v142
	v_rsq_f32_e32 v143, v143
	s_nop 0
	v_pk_mul_f32 v[162:163], v[142:143], s[30:31] op_sel_hi:[1,0]
	s_nop 0
	v_cndmask_b32_e64 v166, v142, v162, s[0:1]
	v_ffbh_u32_e32 v142, v139
	v_min_u32_e32 v142, 32, v142
	v_lshlrev_b64 v[138:139], v142, v[138:139]
	v_min_u32_e32 v138, 1, v138
	v_or_b32_e32 v138, v139, v138
	v_cvt_f32_u32_e32 v138, v138
	v_sub_u32_e32 v139, 32, v142
	v_cndmask_b32_e32 v167, v143, v163, vcc
	v_pk_mul_f32 v[60:61], v[60:61], v[166:167]
	v_ldexp_f32 v139, v138, v139
	v_ffbh_u32_e32 v138, v137
	v_min_u32_e32 v138, 32, v138
	v_lshlrev_b64 v[136:137], v138, v[136:137]
	v_min_u32_e32 v136, 1, v136
	v_or_b32_e32 v136, v137, v136
	v_cvt_f32_u32_e32 v136, v136
	v_sub_u32_e32 v137, 32, v138
	v_pk_mul_f32 v[52:53], v[52:53], v[166:167]
	v_pk_mul_f32 v[44:45], v[44:45], v[166:167]
	v_ldexp_f32 v138, v136, v137
	v_pk_mul_f32 v[136:137], v[138:139], s[34:35] op_sel_hi:[1,0]
	v_pk_mul_f32 v[36:37], v[36:37], v[166:167]
	v_pk_fma_f32 v[136:137], v[136:137], s[2:3], v[168:169] op_sel_hi:[1,0,0]
	s_nop 0
	v_mul_f32_e32 v138, 0x4b800000, v136
	v_cmp_gt_f32_e64 s[0:1], s89, v136
	v_cmp_gt_f32_e32 vcc, s89, v137
	s_nop 0
	v_cndmask_b32_e64 v136, v136, v138, s[0:1]
	v_mul_f32_e32 v138, 0x4b800000, v137
	v_cndmask_b32_e32 v137, v137, v138, vcc
	v_rsq_f32_e32 v136, v136
	v_rsq_f32_e32 v137, v137
	s_nop 0
	v_pk_mul_f32 v[138:139], v[136:137], s[30:31] op_sel_hi:[1,0]
	s_nop 0
	v_cndmask_b32_e64 v162, v136, v138, s[0:1]
	v_ffbh_u32_e32 v136, v135
	v_min_u32_e32 v136, 32, v136
	v_lshlrev_b64 v[134:135], v136, v[134:135]
	v_min_u32_e32 v134, 1, v134
	v_or_b32_e32 v134, v135, v134
	v_cvt_f32_u32_e32 v134, v134
	v_sub_u32_e32 v135, 32, v136
	v_cndmask_b32_e32 v163, v137, v139, vcc
	v_ldexp_f32 v135, v134, v135
	v_ffbh_u32_e32 v134, v133
	v_min_u32_e32 v134, 32, v134
	v_lshlrev_b64 v[132:133], v134, v[132:133]
	v_min_u32_e32 v132, 1, v132
	v_or_b32_e32 v132, v133, v132
	v_cvt_f32_u32_e32 v132, v132
	v_sub_u32_e32 v133, 32, v134
	v_ldexp_f32 v134, v132, v133
	v_pk_mul_f32 v[132:133], v[134:135], s[34:35] op_sel_hi:[1,0]
	s_nop 0
	v_pk_fma_f32 v[132:133], v[132:133], s[2:3], v[168:169] op_sel_hi:[1,0,0]
	s_nop 0
	v_mul_f32_e32 v134, 0x4b800000, v132
	v_cmp_gt_f32_e64 s[0:1], s89, v132
	v_cmp_gt_f32_e32 vcc, s89, v133
	s_nop 0
	v_cndmask_b32_e64 v132, v132, v134, s[0:1]
	v_mul_f32_e32 v134, 0x4b800000, v133
	v_cndmask_b32_e32 v133, v133, v134, vcc
	v_rsq_f32_e32 v132, v132
	v_rsq_f32_e32 v133, v133
	s_nop 0
	v_pk_mul_f32 v[134:135], v[132:133], s[30:31] op_sel_hi:[1,0]
	s_nop 0
	v_cndmask_b32_e64 v188, v132, v134, s[0:1]
	v_ffbh_u32_e32 v132, v131
	v_min_u32_e32 v132, 32, v132
	v_lshlrev_b64 v[130:131], v132, v[130:131]
	v_min_u32_e32 v130, 1, v130
	v_or_b32_e32 v130, v131, v130
	v_cvt_f32_u32_e32 v130, v130
	v_sub_u32_e32 v131, 32, v132
	v_cndmask_b32_e32 v189, v133, v135, vcc
	v_pk_mul_f32 v[56:57], v[56:57], v[188:189]
	v_ldexp_f32 v131, v130, v131
	v_ffbh_u32_e32 v130, v129
	v_min_u32_e32 v130, 32, v130
	v_lshlrev_b64 v[128:129], v130, v[128:129]
	v_min_u32_e32 v128, 1, v128
	v_or_b32_e32 v128, v129, v128
	v_cvt_f32_u32_e32 v128, v128
	v_sub_u32_e32 v129, 32, v130
	v_pk_mul_f32 v[48:49], v[48:49], v[188:189]
	v_pk_mul_f32 v[40:41], v[40:41], v[188:189]
	v_ldexp_f32 v130, v128, v129
	v_pk_mul_f32 v[128:129], v[130:131], s[34:35] op_sel_hi:[1,0]
	v_pk_mul_f32 v[32:33], v[32:33], v[188:189]
	v_pk_fma_f32 v[128:129], v[128:129], s[2:3], v[168:169] op_sel_hi:[1,0,0]
	s_nop 0
	v_mul_f32_e32 v130, 0x4b800000, v128
	v_cmp_gt_f32_e64 s[0:1], s89, v128
	v_cmp_gt_f32_e32 vcc, s89, v129
	s_nop 0
	v_cndmask_b32_e64 v128, v128, v130, s[0:1]
	v_mul_f32_e32 v130, 0x4b800000, v129
	v_cndmask_b32_e32 v129, v129, v130, vcc
	v_rsq_f32_e32 v128, v128
	v_rsq_f32_e32 v129, v129
	s_nop 0
	v_pk_mul_f32 v[130:131], v[128:129], s[30:31] op_sel_hi:[1,0]
	s_nop 0
	v_cndmask_b32_e32 v165, v129, v131, vcc
	v_cndmask_b32_e64 v164, v128, v130, s[0:1]
	global_load_dwordx4 v[128:131], v[140:141], off offset:1072
	global_load_dwordx4 v[132:135], v[140:141], off offset:1056
	global_load_dwordx4 v[136:139], v[140:141], off offset:1040
	s_nop 0
	global_load_dwordx4 v[140:143], v[140:141], off offset:1024
	s_waitcnt vmcnt(0)
	v_ffbh_u32_e32 v161, v143
	v_min_u32_e32 v161, 32, v161
	v_lshlrev_b64 v[142:143], v161, v[142:143]
	v_min_u32_e32 v142, 1, v142
	v_or_b32_e32 v142, v143, v142
	v_cvt_f32_u32_e32 v142, v142
	v_sub_u32_e32 v143, 32, v161
	v_ldexp_f32 v143, v142, v143
	v_ffbh_u32_e32 v142, v141
	v_min_u32_e32 v142, 32, v142
	v_lshlrev_b64 v[140:141], v142, v[140:141]
	v_min_u32_e32 v140, 1, v140
	v_or_b32_e32 v140, v141, v140
	v_cvt_f32_u32_e32 v140, v140
	v_sub_u32_e32 v141, 32, v142
	v_ldexp_f32 v142, v140, v141
	v_pk_mul_f32 v[140:141], v[142:143], s[34:35] op_sel_hi:[1,0]
	s_nop 0
	v_pk_fma_f32 v[140:141], v[140:141], s[2:3], v[168:169] op_sel_hi:[1,0,0]
	s_nop 0
	v_mul_f32_e32 v142, 0x4b800000, v140
	v_cmp_gt_f32_e64 s[0:1], s89, v140
	v_cmp_gt_f32_e32 vcc, s89, v141
	s_nop 0
	v_cndmask_b32_e64 v140, v140, v142, s[0:1]
	v_mul_f32_e32 v142, 0x4b800000, v141
	v_cndmask_b32_e32 v141, v141, v142, vcc
	v_rsq_f32_e32 v140, v140
	v_rsq_f32_e32 v141, v141
	s_nop 0
	v_pk_mul_f32 v[142:143], v[140:141], s[30:31] op_sel_hi:[1,0]
	s_nop 0
	v_cndmask_b32_e64 v142, v140, v142, s[0:1]
	v_ffbh_u32_e32 v140, v139
	v_min_u32_e32 v140, 32, v140
	v_lshlrev_b64 v[138:139], v140, v[138:139]
	v_min_u32_e32 v138, 1, v138
	v_or_b32_e32 v138, v139, v138
	v_cvt_f32_u32_e32 v138, v138
	v_sub_u32_e32 v139, 32, v140
	v_cndmask_b32_e32 v143, v141, v143, vcc
	v_pk_mul_f32 v[140:141], v[124:125], v[166:167]
	v_ldexp_f32 v139, v138, v139
	v_ffbh_u32_e32 v138, v137
	v_min_u32_e32 v138, 32, v138
	v_lshlrev_b64 v[136:137], v138, v[136:137]
	v_min_u32_e32 v136, 1, v136
	v_or_b32_e32 v136, v137, v136
	v_cvt_f32_u32_e32 v136, v136
	v_sub_u32_e32 v137, 32, v138
	v_pk_mul_f32 v[28:29], v[28:29], v[142:143]
	v_pk_mul_f32 v[20:21], v[20:21], v[142:143]
	v_ldexp_f32 v138, v136, v137
	v_pk_mul_f32 v[136:137], v[138:139], s[34:35] op_sel_hi:[1,0]
	v_pk_mul_f32 v[12:13], v[12:13], v[142:143]
	v_pk_fma_f32 v[136:137], v[136:137], s[2:3], v[168:169] op_sel_hi:[1,0,0]
	v_pk_mul_f32 v[4:5], v[4:5], v[142:143]
	v_mul_f32_e32 v138, 0x4b800000, v136
	v_cmp_gt_f32_e64 s[0:1], s89, v136
	v_cmp_gt_f32_e32 vcc, s89, v137
	s_nop 0
	v_cndmask_b32_e64 v136, v136, v138, s[0:1]
	v_mul_f32_e32 v138, 0x4b800000, v137
	v_cndmask_b32_e32 v137, v137, v138, vcc
	v_rsq_f32_e32 v136, v136
	v_rsq_f32_e32 v137, v137
	s_nop 0
	v_pk_mul_f32 v[138:139], v[136:137], s[30:31] op_sel_hi:[1,0]
	s_nop 0
	v_cndmask_b32_e64 v136, v136, v138, s[0:1]
	v_ffbh_u32_e32 v138, v135
	v_min_u32_e32 v138, 32, v138
	v_lshlrev_b64 v[134:135], v138, v[134:135]
	v_min_u32_e32 v134, 1, v134
	v_or_b32_e32 v134, v135, v134
	v_cvt_f32_u32_e32 v134, v134
	v_sub_u32_e32 v135, 32, v138
	v_cndmask_b32_e32 v137, v137, v139, vcc
	v_pk_mul_f32 v[138:139], v[120:121], v[188:189]
	v_ldexp_f32 v135, v134, v135
	v_ffbh_u32_e32 v134, v133
	v_min_u32_e32 v134, 32, v134
	v_lshlrev_b64 v[132:133], v134, v[132:133]
	v_min_u32_e32 v132, 1, v132
	v_or_b32_e32 v132, v133, v132
	v_cvt_f32_u32_e32 v132, v132
	v_sub_u32_e32 v133, 32, v134
	v_pk_mul_f32 v[120:121], v[84:85], v[142:143]
	v_ldexp_f32 v134, v132, v133
	v_pk_mul_f32 v[132:133], v[134:135], s[34:35] op_sel_hi:[1,0]
	s_nop 0
	v_pk_fma_f32 v[132:133], v[132:133], s[2:3], v[168:169] op_sel_hi:[1,0,0]
	s_nop 0
	v_mul_f32_e32 v134, 0x4b800000, v132
	v_cmp_gt_f32_e64 s[0:1], s89, v132
	v_cmp_gt_f32_e32 vcc, s89, v133
	s_nop 0
	v_cndmask_b32_e64 v132, v132, v134, s[0:1]
	v_mul_f32_e32 v134, 0x4b800000, v133
	v_cndmask_b32_e32 v133, v133, v134, vcc
	v_rsq_f32_e32 v132, v132
	v_rsq_f32_e32 v133, v133
	s_nop 0
	v_pk_mul_f32 v[134:135], v[132:133], s[30:31] op_sel_hi:[1,0]
	s_nop 0
	v_cndmask_b32_e64 v176, v132, v134, s[0:1]
	v_ffbh_u32_e32 v132, v131
	v_min_u32_e32 v132, 32, v132
	v_lshlrev_b64 v[130:131], v132, v[130:131]
	v_min_u32_e32 v130, 1, v130
	v_or_b32_e32 v130, v131, v130
	v_cvt_f32_u32_e32 v130, v130
	v_sub_u32_e32 v131, 32, v132
	v_cndmask_b32_e32 v177, v133, v135, vcc
	v_pk_mul_f32 v[124:125], v[88:89], v[176:177]
	v_ldexp_f32 v131, v130, v131
	v_ffbh_u32_e32 v130, v129
	v_min_u32_e32 v130, 32, v130
	v_lshlrev_b64 v[128:129], v130, v[128:129]
	v_min_u32_e32 v128, 1, v128
	v_or_b32_e32 v128, v129, v128
	v_cvt_f32_u32_e32 v128, v128
	v_sub_u32_e32 v129, 32, v130
	v_pk_mul_f32 v[134:135], v[116:117], v[166:167]
	v_pk_mul_f32 v[132:133], v[112:113], v[188:189]
	v_ldexp_f32 v130, v128, v129
	v_pk_mul_f32 v[128:129], v[130:131], s[34:35] op_sel_hi:[1,0]
	v_pk_mul_f32 v[116:117], v[80:81], v[176:177]
	v_pk_fma_f32 v[128:129], v[128:129], s[2:3], v[168:169] op_sel_hi:[1,0,0]
	v_pk_mul_f32 v[88:89], v[104:105], v[188:189]
	v_mul_f32_e32 v130, 0x4b800000, v128
	v_cmp_gt_f32_e64 s[0:1], s89, v128
	v_cmp_gt_f32_e32 vcc, s89, v129
	v_pk_mul_f32 v[112:113], v[76:77], v[142:143]
	v_cndmask_b32_e64 v128, v128, v130, s[0:1]
	v_mul_f32_e32 v130, 0x4b800000, v129
	v_cndmask_b32_e32 v129, v129, v130, vcc
	v_rsq_f32_e32 v128, v128
	v_rsq_f32_e32 v129, v129
	v_pk_mul_f32 v[76:77], v[100:101], v[166:167]
	v_pk_mul_f32 v[104:105], v[68:69], v[142:143]
	v_pk_mul_f32 v[24:25], v[24:25], v[176:177]
	v_pk_mul_f32 v[130:131], v[128:129], s[30:31] op_sel_hi:[1,0]
	v_pk_mul_f32 v[16:17], v[16:17], v[176:177]
	v_cndmask_b32_e32 v129, v129, v131, vcc
	v_cndmask_b32_e64 v128, v128, v130, s[0:1]
	s_mov_b64 s[0:1], -1
	v_pk_mul_f32 v[130:131], v[92:93], v[142:143]
	v_pk_mul_f32 v[92:93], v[108:109], v[166:167]
	v_pk_mul_f32 v[108:109], v[72:73], v[176:177]
	v_pk_mul_f32 v[72:73], v[96:97], v[188:189]
	v_pk_mul_f32 v[96:97], v[64:65], v[176:177]
	v_pk_mul_f32 v[8:9], v[8:9], v[176:177]
	v_pk_mul_f32 v[0:1], v[0:1], v[176:177]
	s_cbranch_scc1 .LBB0_354
	v_lshl_add_u32 v68, s10, 8, v193
	v_ashrrev_i32_e32 v69, 31, v68
	v_pk_mul_f32 v[64:65], v[126:127], v[162:163]
	v_cvt_pk_bf16_f32 v80, v140, v141
	s_lshl_b64 s[0:1], s[50:51], 1
	v_cvt_pk_bf16_f32 v81, v64, v65
	v_lshlrev_b64 v[64:65], 13, v[68:69]
	v_lshl_add_u64 v[64:65], s[44:45], 0, v[64:65]
	v_lshl_add_u64 v[64:65], v[64:65], 0, s[0:1]
	v_lshl_add_u64 v[64:65], v[64:65], 0, v[144:145]
	v_mov_b32_e32 v161, v145
	v_lshl_add_u64 v[64:65], v[64:65], 0, v[160:161]
	global_store_dwordx2 v[64:65], v[80:81], off
	v_pk_mul_f32 v[80:81], v[122:123], v[164:165]
	v_cvt_pk_bf16_f32 v84, v138, v139
	s_nop 0
	v_cvt_pk_bf16_f32 v85, v80, v81
	v_pk_mul_f32 v[80:81], v[94:95], v[136:137]
	global_store_dwordx2 v[64:65], v[84:85], off offset:16
	v_cvt_pk_bf16_f32 v84, v130, v131
	v_cvt_pk_bf16_f32 v85, v80, v81
	v_pk_mul_f32 v[80:81], v[90:91], v[128:129]
	global_store_dwordx2 v[64:65], v[84:85], off offset:256
	v_cvt_pk_bf16_f32 v84, v124, v125
	v_cvt_pk_bf16_f32 v85, v80, v81
	v_or_b32_e32 v80, 16, v68
	v_ashrrev_i32_e32 v81, 31, v80
	v_lshlrev_b64 v[80:81], 13, v[80:81]
	v_lshl_add_u64 v[80:81], s[44:45], 0, v[80:81]
	v_lshl_add_u64 v[80:81], v[80:81], 0, s[0:1]
	v_lshl_add_u64 v[80:81], v[80:81], 0, v[144:145]
	global_store_dwordx2 v[64:65], v[84:85], off offset:272
	v_pk_mul_f32 v[84:85], v[118:119], v[162:163]
	v_cvt_pk_bf16_f32 v100, v134, v135
	v_lshl_add_u64 v[80:81], v[80:81], 0, v[160:161]
	v_cvt_pk_bf16_f32 v101, v84, v85
	global_store_dwordx2 v[80:81], v[100:101], off
	v_pk_mul_f32 v[84:85], v[114:115], v[164:165]
	v_cvt_pk_bf16_f32 v100, v132, v133
	s_nop 0
	v_cvt_pk_bf16_f32 v101, v84, v85
	global_store_dwordx2 v[80:81], v[100:101], off offset:16
	v_pk_mul_f32 v[84:85], v[86:87], v[136:137]
	v_cvt_pk_bf16_f32 v100, v120, v121
	s_nop 0
	v_cvt_pk_bf16_f32 v101, v84, v85
	global_store_dwordx2 v[80:81], v[100:101], off offset:256
	v_pk_mul_f32 v[84:85], v[82:83], v[128:129]
	v_cvt_pk_bf16_f32 v100, v116, v117
	s_nop 0
	v_cvt_pk_bf16_f32 v101, v84, v85
	global_store_dwordx2 v[80:81], v[100:101], off offset:272
	v_or_b32_e32 v80, 32, v68
	v_ashrrev_i32_e32 v81, 31, v80
	v_lshlrev_b64 v[80:81], 13, v[80:81]
	v_lshl_add_u64 v[80:81], s[44:45], 0, v[80:81]
	v_or_b32_e32 v68, 48, v68
	v_lshl_add_u64 v[80:81], v[80:81], 0, s[0:1]
	v_ashrrev_i32_e32 v69, 31, v68
	v_pk_mul_f32 v[84:85], v[110:111], v[162:163]
	v_lshl_add_u64 v[80:81], v[80:81], 0, v[144:145]
	v_lshlrev_b64 v[68:69], 13, v[68:69]
	v_cvt_pk_bf16_f32 v100, v92, v93
	v_cvt_pk_bf16_f32 v101, v84, v85
	v_lshl_add_u64 v[80:81], v[80:81], 0, v[160:161]
	v_pk_mul_f32 v[84:85], v[106:107], v[164:165]
	v_lshl_add_u64 v[68:69], s[44:45], 0, v[68:69]
	global_store_dwordx2 v[80:81], v[100:101], off
	v_cvt_pk_bf16_f32 v100, v88, v89
	v_cvt_pk_bf16_f32 v101, v84, v85
	v_pk_mul_f32 v[84:85], v[78:79], v[136:137]
	v_lshl_add_u64 v[68:69], v[68:69], 0, s[0:1]
	global_store_dwordx2 v[80:81], v[100:101], off offset:16
	v_cvt_pk_bf16_f32 v100, v112, v113
	v_cvt_pk_bf16_f32 v101, v84, v85
	v_pk_mul_f32 v[84:85], v[74:75], v[128:129]
	v_lshl_add_u64 v[68:69], v[68:69], 0, v[144:145]
	global_store_dwordx2 v[80:81], v[100:101], off offset:256
	v_cvt_pk_bf16_f32 v100, v108, v109
	v_cvt_pk_bf16_f32 v101, v84, v85
	global_store_dwordx2 v[80:81], v[100:101], off offset:272
	v_cvt_pk_bf16_f32 v84, v76, v77
	v_lshl_add_u64 v[68:69], v[68:69], 0, v[160:161]
	v_pk_mul_f32 v[80:81], v[102:103], v[162:163]
	s_mov_b64 s[0:1], 0x100000
	v_cvt_pk_bf16_f32 v85, v80, v81
	global_store_dwordx2 v[68:69], v[84:85], off
	v_cvt_pk_bf16_f32 v84, v72, v73
	v_pk_mul_f32 v[80:81], v[98:99], v[164:165]
	s_nop 0
	v_cvt_pk_bf16_f32 v85, v80, v81
	global_store_dwordx2 v[68:69], v[84:85], off offset:16
	v_cvt_pk_bf16_f32 v84, v104, v105
	v_pk_mul_f32 v[80:81], v[70:71], v[136:137]
	s_nop 0
	v_cvt_pk_bf16_f32 v85, v80, v81
	global_store_dwordx2 v[68:69], v[84:85], off offset:256
	v_cvt_pk_bf16_f32 v84, v96, v97
	v_pk_mul_f32 v[80:81], v[66:67], v[128:129]
	s_nop 0
	v_cvt_pk_bf16_f32 v85, v80, v81
	global_store_dwordx2 v[68:69], v[84:85], off offset:272
	v_add_co_u32_e32 v84, vcc, s29, v64
	v_pk_mul_f32 v[68:69], v[62:63], v[162:163]
	s_nop 0
	v_addc_co_u32_e32 v85, vcc, 0, v65, vcc
	v_cvt_pk_bf16_f32 v80, v60, v61
	v_cvt_pk_bf16_f32 v81, v68, v69
	v_lshl_add_u64 v[68:69], v[64:65], 0, s[0:1]
	global_store_dwordx2 v[84:85], v[80:81], off
	v_cvt_pk_bf16_f32 v84, v56, v57
	v_pk_mul_f32 v[80:81], v[58:59], v[164:165]
	s_mov_b64 s[0:1], 0x120000
	v_cvt_pk_bf16_f32 v85, v80, v81
	global_store_dwordx2 v[68:69], v[84:85], off offset:16
	v_cvt_pk_bf16_f32 v84, v28, v29
	v_pk_mul_f32 v[80:81], v[30:31], v[136:137]
	s_nop 0
	v_cvt_pk_bf16_f32 v85, v80, v81
	global_store_dwordx2 v[68:69], v[84:85], off offset:256
	v_cvt_pk_bf16_f32 v84, v24, v25
	v_pk_mul_f32 v[80:81], v[26:27], v[128:129]
	s_nop 0
	v_cvt_pk_bf16_f32 v85, v80, v81
	global_store_dwordx2 v[68:69], v[84:85], off offset:272
	v_add_co_u32_e32 v84, vcc, s49, v64
	v_pk_mul_f32 v[68:69], v[54:55], v[162:163]
	v_cvt_pk_bf16_f32 v80, v52, v53
	s_nop 0
	v_addc_co_u32_e32 v85, vcc, 0, v65, vcc
	v_cvt_pk_bf16_f32 v81, v68, v69
	v_lshl_add_u64 v[68:69], v[64:65], 0, s[0:1]
	global_store_dwordx2 v[84:85], v[80:81], off
	v_pk_mul_f32 v[80:81], v[50:51], v[164:165]
	v_cvt_pk_bf16_f32 v84, v48, v49
	s_mov_b64 s[0:1], 0x140000
	v_cvt_pk_bf16_f32 v85, v80, v81
	global_store_dwordx2 v[68:69], v[84:85], off offset:16
	v_pk_mul_f32 v[80:81], v[22:23], v[136:137]
	v_cvt_pk_bf16_f32 v84, v20, v21
	s_nop 0
	v_cvt_pk_bf16_f32 v85, v80, v81
	global_store_dwordx2 v[68:69], v[84:85], off offset:256
	v_pk_mul_f32 v[80:81], v[18:19], v[128:129]
	v_cvt_pk_bf16_f32 v84, v16, v17
	s_nop 0
	v_cvt_pk_bf16_f32 v85, v80, v81
	global_store_dwordx2 v[68:69], v[84:85], off offset:272
	v_pk_mul_f32 v[68:69], v[46:47], v[162:163]
	v_cvt_pk_bf16_f32 v80, v44, v45
	s_nop 0
	v_cvt_pk_bf16_f32 v81, v68, v69
	v_lshl_add_u64 v[68:69], v[64:65], 0, s[0:1]
	s_mov_b32 s0, 0x140000
	v_add_co_u32_e32 v84, vcc, s0, v64
	s_mov_b64 s[0:1], 0x160000
	s_nop 0
	v_addc_co_u32_e32 v85, vcc, 0, v65, vcc
	global_store_dwordx2 v[84:85], v[80:81], off
	v_pk_mul_f32 v[80:81], v[42:43], v[164:165]
	v_cvt_pk_bf16_f32 v84, v40, v41
	s_nop 0
	v_cvt_pk_bf16_f32 v85, v80, v81
	global_store_dwordx2 v[68:69], v[84:85], off offset:16
	v_pk_mul_f32 v[80:81], v[14:15], v[136:137]
	v_cvt_pk_bf16_f32 v84, v12, v13
	s_nop 0
	v_cvt_pk_bf16_f32 v85, v80, v81
	global_store_dwordx2 v[68:69], v[84:85], off offset:256
	v_pk_mul_f32 v[80:81], v[10:11], v[128:129]
	v_cvt_pk_bf16_f32 v84, v8, v9
	s_nop 0
	v_cvt_pk_bf16_f32 v85, v80, v81
	global_store_dwordx2 v[68:69], v[84:85], off offset:272
	v_pk_mul_f32 v[68:69], v[38:39], v[162:163]
	v_cvt_pk_bf16_f32 v80, v36, v37
	s_nop 0
	v_cvt_pk_bf16_f32 v81, v68, v69
	v_lshl_add_u64 v[68:69], v[64:65], 0, s[0:1]
	s_mov_b32 s0, 0x160000
	v_add_co_u32_e32 v64, vcc, s0, v64
	s_mov_b64 s[0:1], 0
	s_nop 0
	v_addc_co_u32_e32 v65, vcc, 0, v65, vcc
	global_store_dwordx2 v[64:65], v[80:81], off
	v_pk_mul_f32 v[64:65], v[34:35], v[164:165]
	v_cvt_pk_bf16_f32 v80, v32, v33
	s_nop 0
	v_cvt_pk_bf16_f32 v81, v64, v65
	global_store_dwordx2 v[68:69], v[80:81], off offset:16
	v_pk_mul_f32 v[64:65], v[6:7], v[136:137]
	v_cvt_pk_bf16_f32 v80, v4, v5
	s_nop 0
	v_cvt_pk_bf16_f32 v81, v64, v65
	global_store_dwordx2 v[68:69], v[80:81], off offset:256
	v_pk_mul_f32 v[64:65], v[2:3], v[128:129]
	v_cvt_pk_bf16_f32 v80, v0, v1
	s_nop 0
	v_cvt_pk_bf16_f32 v81, v64, v65
	s_nop 1
	global_store_dwordx2 v[68:69], v[80:81], off offset:272
